# packed fp32 ops split into scalar pairs (attention tile-loop adds; P5/P1/P3 epilogue muls); jump-threaded flag tests in attention tile loops
# speedup vs baseline: 1.0041x; 1.0031x over previous
; __device__ __forceinline__ unsigned cvt_pk_bf16(float lo, float hi) { unsigned r; asm volatile("v_cvt_pk_bf16_f32 %0, %1, %2" : "=v"(r) : "v"(lo), "v"(hi)); return r; }
;     __device__ __forceinline__ void operator()(const i32x4 (&acc)[2][2][4][2], const Unit& u, int wr, int wc, int fr, int fq) const {
;         const int row0 = u.pm * BM + wr * 64 + fr; const int col0 = u.pn * BM + wc * 32 + 8 * fq;
;         f32x4 w0[2], w1[2]; float sav[8];
; #pragma unroll
;         for (int bj = 0; bj < 2; ++bj) { w0[bj] = *(const f32x4*)(sw + col0 + bj * HALF); w1[bj] = *(const f32x4*)(sw + col0 + bj * HALF + 4); }
; #pragma unroll
;         for (int i = 0; i < 8; ++i) sav[i] = sa[row0 + (i >> 2) * HALF + (i & 3) * 16];
; #pragma unroll
;         for (int ai = 0; ai < 2; ++ai)
; #pragma unroll
;             for (int m = 0; m < 4; ++m) {
;                 const int r = row0 + ai * HALF + m * 16;
;                 float sc = sav[4 * ai + m]; if (qscale != 0.f && (u.pn < 4 || (u.pn >= 12 && u.pn < 16))) sc *= qscale;
;                 bf16_t* rowp = O + (size_t)r * ldc + col0;
; #pragma unroll
;                 for (int bj = 0; bj < 2; ++bj) { const i32x4 a0 = acc[ai][bj][m][0], a1 = acc[ai][bj][m][1];
;                     const f32x4 v0 = (f32x4){(float)a0[0], (float)a0[1], (float)a0[2], (float)a0[3]} * w0[bj] * sc, v1 = (f32x4){(float)a1[0], (float)a1[1], (float)a1[2], (float)a1[3]} * w1[bj] * sc;
;                     u32x4 w; w.x = cvt_pk_bf16(v0[0], v0[1]); w.y = cvt_pk_bf16(v0[2], v0[3]); w.z = cvt_pk_bf16(v1[0], v1[1]); w.w = cvt_pk_bf16(v1[2], v1[3]);
;                     if (hm_rows) { const int c = col0 + bj * HALF; *(u32x4*)(O + ((size_t)(c >> 6) * hm_rows + r) * 64 + (c & 63)) = w; }
;                     else *(u32x4*)(rowp + bj * HALF) = w; } }
.LBB0_158:
	v_lshl_add_u32 v172, s37, 8, v167
	v_lshl_add_u32 v162, s18, 8, v165
	v_ashrrev_i32_e32 v173, 31, v172
	v_ashrrev_i32_e32 v163, 31, v162
	v_lshl_add_u64 v[108:109], v[172:173], 2, s[10:11]
	v_lshl_add_u64 v[174:175], v[162:163], 2, s[8:9]
	global_load_dword v171, v[174:175], off
	global_load_dwordx4 v[128:131], v[108:109], off
	global_load_dwordx4 v[120:123], v[108:109], off offset:16
	global_load_dwordx4 v[112:115], v[108:109], off offset:512
	s_nop 0
	global_load_dwordx4 v[108:111], v[108:109], off offset:528
	s_nop 0
	global_load_dword v185, v[174:175], off offset:64
	v_cvt_f32_i32_e32 v177, v125
	v_cvt_f32_i32_e32 v176, v124
	global_load_dword v187, v[174:175], off offset:128
	global_load_dword v192, v[174:175], off offset:192
	global_load_dword v193, v[174:175], off offset:512
	global_load_dword v194, v[174:175], off offset:576
	global_load_dword v125, v[174:175], off offset:640
	global_load_dword v124, v[174:175], off offset:704
	s_cmp_lt_i32 s37, 4
	v_cvt_f32_i32_e32 v141, v141
	v_cvt_f32_i32_e32 v140, v140
	v_cvt_f32_i32_e32 v143, v143
	v_cvt_f32_i32_e32 v142, v142
	v_cvt_f32_i32_e32 v137, v137
	v_cvt_f32_i32_e32 v136, v136
	v_cvt_f32_i32_e32 v139, v139
	v_cvt_f32_i32_e32 v138, v138
	v_cvt_f32_i32_e32 v133, v133
	v_cvt_f32_i32_e32 v132, v132
	v_cvt_f32_i32_e32 v135, v135
	v_cvt_f32_i32_e32 v134, v134
	v_cvt_f32_i32_e32 v127, v127
	v_cvt_f32_i32_e32 v126, v126
	v_cvt_f32_i32_e32 v181, v119
	s_cselect_b64 s[20:21], -1, 0
	s_and_b32 s3, s37, 0x7ffffffc
	v_ashrrev_i32_e32 v119, 6, v172
	v_cvt_f32_i32_e32 v180, v118
	v_add_u32_e32 v118, 0x80, v172
	s_cmp_eq_u32 s3, 12
	v_mad_i64_i32 v[182:183], s[22:23], v119, s31, v[162:163]
	v_ashrrev_i32_e32 v118, 6, v118
	s_cselect_b64 s[22:23], -1, 0
	v_cvt_f32_i32_e32 v179, v117
	v_cvt_f32_i32_e32 v178, v116
	v_lshlrev_b64 v[174:175], 7, v[182:183]
	v_mad_i64_i32 v[182:183], s[24:25], v118, s31, v[162:163]
	s_or_b64 vcc, s[20:21], s[22:23]
	v_cvt_f32_i32_e32 v105, v105
	v_cvt_f32_i32_e32 v107, v107
	v_cvt_f32_i32_e32 v106, v106
	v_cvt_f32_i32_e32 v104, v104
	v_lshl_add_u64 v[174:175], v[152:153], 0, v[174:175]
	v_lshlrev_b64 v[182:183], 7, v[182:183]
	v_cvt_f32_i32_e32 v101, v101
	v_cvt_f32_i32_e32 v100, v100
	v_or_b32_e32 v172, 16, v162
	v_lshl_add_u64 v[182:183], v[152:153], 0, v[182:183]
	v_cvt_f32_i32_e32 v97, v97
	v_cvt_f32_i32_e32 v99, v99
	v_cvt_f32_i32_e32 v98, v98
	v_cvt_f32_i32_e32 v96, v96
	v_ashrrev_i32_e32 v173, 31, v172
	v_cvt_f32_i32_e32 v103, v103
	v_cvt_f32_i32_e32 v102, v102
	v_cvt_f32_i32_e32 v93, v93
	v_cvt_f32_i32_e32 v92, v92
	v_cvt_f32_i32_e32 v89, v89
	v_cvt_f32_i32_e32 v91, v91
	v_cvt_f32_i32_e32 v90, v90
	v_cvt_f32_i32_e32 v88, v88
	v_cvt_f32_i32_e32 v95, v95
	v_cvt_f32_i32_e32 v94, v94
	v_cvt_f32_i32_e32 v85, v85
	v_cvt_f32_i32_e32 v84, v84
	v_cvt_f32_i32_e32 v81, v81
	v_cvt_f32_i32_e32 v83, v83
	v_cvt_f32_i32_e32 v82, v82
	v_cvt_f32_i32_e32 v80, v80
	v_cvt_f32_i32_e32 v87, v87
	v_cvt_f32_i32_e32 v86, v86
	v_cvt_f32_i32_e32 v77, v77
	v_cvt_f32_i32_e32 v76, v76
	v_cvt_f32_i32_e32 v73, v73
	v_cvt_f32_i32_e32 v75, v75
	v_cvt_f32_i32_e32 v74, v74
	v_cvt_f32_i32_e32 v72, v72
	s_waitcnt vmcnt(0)
	v_mul_f32_e32 v163, 0x3e38aa3b, v171
	v_mul_f32_e32 v142, v130, v142
	v_mul_f32_e32 v143, v131, v143
	v_mul_f32_e32 v140, v128, v140
	v_mul_f32_e32 v141, v129, v141
	v_mul_f32_e32 v138, v122, v138
	v_mul_f32_e32 v139, v123, v139
	v_mul_f32_e32 v136, v120, v136
	v_mul_f32_e32 v137, v121, v137
	v_mul_f32_e32 v134, v114, v134
	v_mul_f32_e32 v135, v115, v135
	v_mul_f32_e32 v132, v112, v132
	v_mul_f32_e32 v133, v113, v133
	v_mul_f32_e32 v126, v110, v126
	v_mul_f32_e32 v127, v111, v127
	v_cndmask_b32_e32 v184, v171, v163, vcc
	v_mul_f32_e32 v176, v108, v176
	v_mul_f32_e32 v177, v109, v177
	v_mul_f32_e32 v186, 0x3e38aa3b, v185
	v_mul_f32_e32 v142, v142, v184
	v_mul_f32_e32 v143, v143, v184
	v_mul_f32_e32 v140, v140, v184
	v_mul_f32_e32 v141, v141, v184
	v_mul_f32_e32 v138, v138, v184
	v_mul_f32_e32 v139, v139, v184
	v_mul_f32_e32 v136, v136, v184
	v_mul_f32_e32 v137, v137, v184
	v_mul_f32_e32 v188, v134, v184
	v_mul_f32_e32 v189, v135, v184
	v_mul_f32_e32 v190, v132, v184
	v_mul_f32_e32 v191, v133, v184
	v_mul_f32_e32 v126, v126, v184
	v_mul_f32_e32 v127, v127, v184
	v_cvt_pk_bf16_f32 v132, v140, v141
	v_cvt_pk_bf16_f32 v133, v142, v143
	v_cvt_pk_bf16_f32 v134, v136, v137
	v_cvt_pk_bf16_f32 v135, v138, v139
	v_cndmask_b32_e32 v186, v185, v186, vcc
	v_mul_f32_e32 v176, v176, v184
	v_mul_f32_e32 v177, v177, v184
	global_store_dwordx4 v[174:175], v[132:135], off
	v_mul_f32_e32 v106, v122, v106
	v_mul_f32_e32 v107, v123, v107
	v_mul_f32_e32 v104, v120, v104
	v_mul_f32_e32 v105, v121, v105
	v_cvt_pk_bf16_f32 v132, v190, v191
	v_cvt_pk_bf16_f32 v133, v188, v189
	v_cvt_pk_bf16_f32 v134, v176, v177
	v_cvt_pk_bf16_f32 v135, v126, v127
	v_mul_f32_e32 v126, v130, v180
	v_mul_f32_e32 v127, v131, v181
	global_store_dwordx4 v[182:183], v[132:135], off
	v_mul_f32_e32 v126, v126, v186
	v_mul_f32_e32 v127, v127, v186
	v_mul_f32_e32 v100, v112, v100
	v_mul_f32_e32 v101, v113, v101
	v_mul_f32_e32 v132, v128, v178
	v_mul_f32_e32 v133, v129, v179
	v_mul_f32_e32 v134, v106, v186
	v_mul_f32_e32 v135, v107, v186
	v_mul_f32_e32 v132, v132, v186
	v_mul_f32_e32 v133, v133, v186
	v_mul_f32_e32 v106, v104, v186
	v_mul_f32_e32 v107, v105, v186
	v_cvt_pk_bf16_f32 v104, v132, v133
	v_cvt_pk_bf16_f32 v105, v126, v127
	v_mad_i64_i32 v[126:127], s[20:21], v119, s31, v[172:173]
	v_lshlrev_b64 v[126:127], 7, v[126:127]
	v_lshl_add_u64 v[126:127], v[152:153], 0, v[126:127]
	v_mul_f32_e32 v100, v100, v186
	v_mul_f32_e32 v101, v101, v186
	v_mul_f32_e32 v98, v110, v98
	v_mul_f32_e32 v99, v111, v99
	v_mul_f32_e32 v96, v108, v96
; __device__ __forceinline__ unsigned cvt_pk_bf16(float lo, float hi) { unsigned r; asm volatile("v_cvt_pk_bf16_f32 %0, %1, %2" : "=v"(r) : "v"(lo), "v"(hi)); return r; }
;     __device__ __forceinline__ void operator()(const i32x4 (&acc)[2][2][4][2], const Unit& u, int wr, int wc, int fr, int fq) const {
;     ...
;                 const int r = row0 + ai * HALF + m * 16;
;                 float sc = sav[4 * ai + m]; if (qscale != 0.f && (u.pn < 4 || (u.pn >= 12 && u.pn < 16))) sc *= qscale;
;                 bf16_t* rowp = O + (size_t)r * ldc + col0;
; #pragma unroll
;                 for (int bj = 0; bj < 2; ++bj) { const i32x4 a0 = acc[ai][bj][m][0], a1 = acc[ai][bj][m][1];
;                     const f32x4 v0 = (f32x4){(float)a0[0], (float)a0[1], (float)a0[2], (float)a0[3]} * w0[bj] * sc, v1 = (f32x4){(float)a1[0], (float)a1[1], (float)a1[2], (float)a1[3]} * w1[bj] * sc;
;                     u32x4 w; w.x = cvt_pk_bf16(v0[0], v0[1]); w.y = cvt_pk_bf16(v0[2], v0[3]); w.z = cvt_pk_bf16(v1[0], v1[1]); w.w = cvt_pk_bf16(v1[2], v1[3]);
;                     if (hm_rows) { const int c = col0 + bj * HALF; *(u32x4*)(O + ((size_t)(c >> 6) * hm_rows + r) * 64 + (c & 63)) = w; }
;                     else *(u32x4*)(rowp + bj * HALF) = w; } }
	v_mul_f32_e32 v97, v109, v97
	v_cvt_pk_bf16_f32 v106, v106, v107
	v_cvt_pk_bf16_f32 v107, v134, v135
	global_store_dwordx4 v[126:127], v[104:107], off
	v_mul_f32_e32 v102, v114, v102
	v_mul_f32_e32 v103, v115, v103
	v_mul_f32_e32 v92, v128, v92
	v_mul_f32_e32 v93, v129, v93
	v_mul_f32_e32 v104, v98, v186
	v_mul_f32_e32 v105, v99, v186
	v_mul_f32_e32 v98, v96, v186
	v_mul_f32_e32 v99, v97, v186
	v_cvt_pk_bf16_f32 v96, v100, v101
	v_mad_i64_i32 v[100:101], s[20:21], v118, s31, v[172:173]
	v_lshlrev_b64 v[100:101], 7, v[100:101]
	v_mul_f32_e32 v102, v102, v186
	v_mul_f32_e32 v103, v103, v186
	v_lshl_add_u64 v[100:101], v[152:153], 0, v[100:101]
	v_cvt_pk_bf16_f32 v97, v102, v103
	v_cvt_pk_bf16_f32 v98, v98, v99
	v_cvt_pk_bf16_f32 v99, v104, v105
	global_store_dwordx4 v[100:101], v[96:99], off
	v_mul_f32_e32 v90, v122, v90
	v_mul_f32_e32 v91, v123, v91
	v_mul_f32_e32 v88, v120, v88
	v_mul_f32_e32 v89, v121, v89
	v_mul_f32_e32 v97, 0x3e38aa3b, v187
	v_or_b32_e32 v96, 32, v162
	v_cndmask_b32_e32 v98, v187, v97, vcc
	v_ashrrev_i32_e32 v97, 31, v96
	v_mul_f32_e32 v92, v92, v98
	v_mul_f32_e32 v93, v93, v98
	v_mul_f32_e32 v100, v90, v98
	v_mul_f32_e32 v101, v91, v98
	v_mul_f32_e32 v90, v88, v98
	v_mul_f32_e32 v91, v89, v98
	v_cvt_pk_bf16_f32 v88, v92, v93
	v_mad_i64_i32 v[92:93], s[20:21], v119, s31, v[96:97]
	v_mul_f32_e32 v94, v130, v94
	v_mul_f32_e32 v95, v131, v95
	v_lshlrev_b64 v[92:93], 7, v[92:93]
	v_mul_f32_e32 v84, v112, v84
	v_mul_f32_e32 v85, v113, v85
	v_mul_f32_e32 v94, v94, v98
	v_mul_f32_e32 v95, v95, v98
	v_lshl_add_u64 v[92:93], v[152:153], 0, v[92:93]
	v_cvt_pk_bf16_f32 v89, v94, v95
	v_mul_f32_e32 v84, v84, v98
	v_mul_f32_e32 v85, v85, v98
	v_mul_f32_e32 v82, v110, v82
	v_mul_f32_e32 v83, v111, v83
	v_mul_f32_e32 v80, v108, v80
	v_mul_f32_e32 v81, v109, v81
	v_cvt_pk_bf16_f32 v90, v90, v91
	v_cvt_pk_bf16_f32 v91, v100, v101
	global_store_dwordx4 v[92:93], v[88:91], off
	v_mul_f32_e32 v86, v114, v86
	v_mul_f32_e32 v87, v115, v87
	v_cvt_f32_i32_e32 v79, v79
	v_mul_f32_e32 v88, v82, v98
	v_mul_f32_e32 v89, v83, v98
	v_mul_f32_e32 v82, v80, v98
	v_mul_f32_e32 v83, v81, v98
	v_cvt_pk_bf16_f32 v80, v84, v85
	v_mad_i64_i32 v[84:85], s[20:21], v118, s31, v[96:97]
	v_lshlrev_b64 v[84:85], 7, v[84:85]
	v_mul_f32_e32 v86, v86, v98
	v_mul_f32_e32 v87, v87, v98
	v_lshl_add_u64 v[84:85], v[152:153], 0, v[84:85]
	v_cvt_pk_bf16_f32 v81, v86, v87
	v_cvt_pk_bf16_f32 v82, v82, v83
	v_cvt_pk_bf16_f32 v83, v88, v89
	global_store_dwordx4 v[84:85], v[80:83], off
	v_cvt_f32_i32_e32 v78, v78
	v_cvt_f32_i32_e32 v69, v69
	v_mul_f32_e32 v81, 0x3e38aa3b, v192
	v_cvt_f32_i32_e32 v68, v68
	v_or_b32_e32 v80, 48, v162
	v_cndmask_b32_e32 v82, v192, v81, vcc
	v_mul_f32_e32 v76, v128, v76
	v_mul_f32_e32 v77, v129, v77
	v_cvt_f32_i32_e32 v65, v65
	v_cvt_f32_i32_e32 v67, v67
	v_cvt_f32_i32_e32 v66, v66
	v_cvt_f32_i32_e32 v64, v64
	v_ashrrev_i32_e32 v81, 31, v80
	v_mul_f32_e32 v76, v76, v82
	v_mul_f32_e32 v77, v77, v82
	v_mul_f32_e32 v74, v122, v74
	v_mul_f32_e32 v75, v123, v75
	v_mul_f32_e32 v72, v120, v72
	v_mul_f32_e32 v73, v121, v73
	v_mul_f32_e32 v84, v74, v82
	v_mul_f32_e32 v85, v75, v82
	v_mul_f32_e32 v74, v72, v82
	v_mul_f32_e32 v75, v73, v82
	v_cvt_pk_bf16_f32 v72, v76, v77
	v_mad_i64_i32 v[76:77], s[20:21], v119, s31, v[80:81]
	v_mul_f32_e32 v78, v130, v78
	v_mul_f32_e32 v79, v131, v79
	v_lshlrev_b64 v[76:77], 7, v[76:77]
	v_cvt_f32_i32_e32 v71, v71
	v_cvt_f32_i32_e32 v70, v70
	v_mul_f32_e32 v68, v112, v68
	v_mul_f32_e32 v69, v113, v69
	v_mul_f32_e32 v78, v78, v82
	v_mul_f32_e32 v79, v79, v82
	v_lshl_add_u64 v[76:77], v[152:153], 0, v[76:77]
	v_cvt_pk_bf16_f32 v73, v78, v79
	v_mul_f32_e32 v68, v68, v82
	v_mul_f32_e32 v69, v69, v82
	v_mul_f32_e32 v66, v110, v66
	v_mul_f32_e32 v67, v111, v67
	v_mul_f32_e32 v64, v108, v64
	v_mul_f32_e32 v65, v109, v65
	v_cvt_pk_bf16_f32 v74, v74, v75
	v_cvt_pk_bf16_f32 v75, v84, v85
	global_store_dwordx4 v[76:77], v[72:75], off
	v_cvt_f32_i32_e32 v61, v61
	v_cvt_f32_i32_e32 v60, v60
	v_mul_f32_e32 v72, v66, v82
	v_mul_f32_e32 v73, v67, v82
	v_mul_f32_e32 v66, v64, v82
	v_mul_f32_e32 v67, v65, v82
	v_cvt_pk_bf16_f32 v64, v68, v69
	v_mad_i64_i32 v[68:69], s[20:21], v118, s31, v[80:81]
	v_lshlrev_b64 v[68:69], 7, v[68:69]
	v_cvt_f32_i32_e32 v57, v57
	v_cvt_f32_i32_e32 v59, v59
	v_cvt_f32_i32_e32 v58, v58
	v_cvt_f32_i32_e32 v56, v56
	v_mul_f32_e32 v70, v114, v70
	v_mul_f32_e32 v71, v115, v71
	v_lshl_add_u64 v[68:69], v[152:153], 0, v[68:69]
	v_mul_f32_e32 v70, v70, v82
	v_mul_f32_e32 v71, v71, v82
	v_cvt_f32_i32_e32 v63, v63
	v_cvt_pk_bf16_f32 v65, v70, v71
	v_cvt_pk_bf16_f32 v66, v66, v67
	v_cvt_pk_bf16_f32 v67, v72, v73
	global_store_dwordx4 v[68:69], v[64:67], off
	v_cvt_f32_i32_e32 v62, v62
	v_cvt_f32_i32_e32 v53, v53
	v_mul_f32_e32 v64, 0x3e38aa3b, v193
	v_cvt_f32_i32_e32 v52, v52
	v_add_u32_e32 v116, 0x80, v162
	v_cndmask_b32_e32 v64, v193, v64, vcc
	v_mul_f32_e32 v60, v128, v60
	v_mul_f32_e32 v61, v129, v61
	v_cvt_f32_i32_e32 v49, v49
	v_cvt_f32_i32_e32 v51, v51
	v_cvt_f32_i32_e32 v50, v50
	v_cvt_f32_i32_e32 v48, v48
	v_ashrrev_i32_e32 v117, 31, v116
	v_mul_f32_e32 v60, v60, v64
	v_mul_f32_e32 v61, v61, v64
	v_mul_f32_e32 v58, v122, v58
	v_mul_f32_e32 v59, v123, v59
	v_mul_f32_e32 v56, v120, v56
	v_mul_f32_e32 v57, v121, v57
	v_mul_f32_e32 v66, v58, v64
	v_mul_f32_e32 v67, v59, v64
	v_mul_f32_e32 v58, v56, v64
	v_mul_f32_e32 v59, v57, v64
	v_cvt_pk_bf16_f32 v56, v60, v61
	v_mad_i64_i32 v[60:61], s[20:21], v119, s31, v[116:117]
	v_cvt_f32_i32_e32 v55, v55
	v_cvt_f32_i32_e32 v54, v54
	v_mul_f32_e32 v62, v130, v62
	v_mul_f32_e32 v63, v131, v63
	v_lshlrev_b64 v[60:61], 7, v[60:61]
	v_mul_f32_e32 v52, v112, v52
; __device__ __forceinline__ unsigned cvt_pk_bf16(float lo, float hi) { unsigned r; asm volatile("v_cvt_pk_bf16_f32 %0, %1, %2" : "=v"(r) : "v"(lo), "v"(hi)); return r; }
;     __device__ __forceinline__ void operator()(const i32x4 (&acc)[2][2][4][2], const Unit& u, int wr, int wc, int fr, int fq) const {
;     ...
;                 const int r = row0 + ai * HALF + m * 16;
;                 float sc = sav[4 * ai + m]; if (qscale != 0.f && (u.pn < 4 || (u.pn >= 12 && u.pn < 16))) sc *= qscale;
;                 bf16_t* rowp = O + (size_t)r * ldc + col0;
; #pragma unroll
;                 for (int bj = 0; bj < 2; ++bj) { const i32x4 a0 = acc[ai][bj][m][0], a1 = acc[ai][bj][m][1];
;                     const f32x4 v0 = (f32x4){(float)a0[0], (float)a0[1], (float)a0[2], (float)a0[3]} * w0[bj] * sc, v1 = (f32x4){(float)a1[0], (float)a1[1], (float)a1[2], (float)a1[3]} * w1[bj] * sc;
;                     u32x4 w; w.x = cvt_pk_bf16(v0[0], v0[1]); w.y = cvt_pk_bf16(v0[2], v0[3]); w.z = cvt_pk_bf16(v1[0], v1[1]); w.w = cvt_pk_bf16(v1[2], v1[3]);
;                     if (hm_rows) { const int c = col0 + bj * HALF; *(u32x4*)(O + ((size_t)(c >> 6) * hm_rows + r) * 64 + (c & 63)) = w; }
;                     else *(u32x4*)(rowp + bj * HALF) = w; } }
	v_mul_f32_e32 v53, v113, v53
	v_mul_f32_e32 v62, v62, v64
	v_mul_f32_e32 v63, v63, v64
	v_lshl_add_u64 v[60:61], v[152:153], 0, v[60:61]
	v_cvt_pk_bf16_f32 v57, v62, v63
	v_mul_f32_e32 v52, v52, v64
	v_mul_f32_e32 v53, v53, v64
	v_mul_f32_e32 v50, v110, v50
	v_mul_f32_e32 v51, v111, v51
	v_mul_f32_e32 v48, v108, v48
	v_mul_f32_e32 v49, v109, v49
	v_cvt_pk_bf16_f32 v58, v58, v59
	v_cvt_pk_bf16_f32 v59, v66, v67
	global_store_dwordx4 v[60:61], v[56:59], off
	v_cvt_f32_i32_e32 v45, v45
	v_cvt_f32_i32_e32 v44, v44
	v_mul_f32_e32 v56, v50, v64
	v_mul_f32_e32 v57, v51, v64
	v_mul_f32_e32 v50, v48, v64
	v_mul_f32_e32 v51, v49, v64
	v_cvt_pk_bf16_f32 v48, v52, v53
	v_mad_i64_i32 v[52:53], s[20:21], v118, s31, v[116:117]
	v_mul_f32_e32 v54, v114, v54
	v_mul_f32_e32 v55, v115, v55
	v_lshlrev_b64 v[52:53], 7, v[52:53]
	v_cvt_f32_i32_e32 v41, v41
	v_cvt_f32_i32_e32 v43, v43
	v_cvt_f32_i32_e32 v42, v42
	v_cvt_f32_i32_e32 v40, v40
	v_mul_f32_e32 v54, v54, v64
	v_mul_f32_e32 v55, v55, v64
	v_lshl_add_u64 v[52:53], v[152:153], 0, v[52:53]
	v_cvt_pk_bf16_f32 v49, v54, v55
	v_cvt_pk_bf16_f32 v50, v50, v51
	v_cvt_pk_bf16_f32 v51, v56, v57
	global_store_dwordx4 v[52:53], v[48:51], off
	v_cvt_f32_i32_e32 v47, v47
	v_cvt_f32_i32_e32 v46, v46
	v_mul_f32_e32 v49, 0x3e38aa3b, v194
	v_cvt_f32_i32_e32 v37, v37
	v_cvt_f32_i32_e32 v36, v36
	v_add_u32_e32 v48, 0x90, v162
	v_cndmask_b32_e32 v50, v194, v49, vcc
	v_mul_f32_e32 v44, v128, v44
	v_mul_f32_e32 v45, v129, v45
	v_cvt_f32_i32_e32 v33, v33
	v_cvt_f32_i32_e32 v35, v35
	v_cvt_f32_i32_e32 v34, v34
	v_cvt_f32_i32_e32 v32, v32
	v_ashrrev_i32_e32 v49, 31, v48
	v_mul_f32_e32 v44, v44, v50
	v_mul_f32_e32 v45, v45, v50
	v_mul_f32_e32 v42, v122, v42
	v_mul_f32_e32 v43, v123, v43
	v_mul_f32_e32 v40, v120, v40
	v_mul_f32_e32 v41, v121, v41
	v_mul_f32_e32 v52, v42, v50
	v_mul_f32_e32 v53, v43, v50
	v_mul_f32_e32 v42, v40, v50
	v_mul_f32_e32 v43, v41, v50
	v_cvt_pk_bf16_f32 v40, v44, v45
	v_mad_i64_i32 v[44:45], s[20:21], v119, s31, v[48:49]
	v_cvt_f32_i32_e32 v39, v39
	v_cvt_f32_i32_e32 v38, v38
	v_mul_f32_e32 v46, v130, v46
	v_mul_f32_e32 v47, v131, v47
	v_lshlrev_b64 v[44:45], 7, v[44:45]
	v_mul_f32_e32 v36, v112, v36
	v_mul_f32_e32 v37, v113, v37
	v_mul_f32_e32 v46, v46, v50
	v_mul_f32_e32 v47, v47, v50
	v_lshl_add_u64 v[44:45], v[152:153], 0, v[44:45]
	v_cvt_pk_bf16_f32 v41, v46, v47
	v_mul_f32_e32 v36, v36, v50
	v_mul_f32_e32 v37, v37, v50
	v_mul_f32_e32 v34, v110, v34
	v_mul_f32_e32 v35, v111, v35
	v_mul_f32_e32 v32, v108, v32
	v_mul_f32_e32 v33, v109, v33
	v_cvt_pk_bf16_f32 v42, v42, v43
	v_cvt_pk_bf16_f32 v43, v52, v53
	global_store_dwordx4 v[44:45], v[40:43], off
	v_cvt_f32_i32_e32 v29, v29
	v_cvt_f32_i32_e32 v28, v28
	v_mul_f32_e32 v40, v34, v50
	v_mul_f32_e32 v41, v35, v50
	v_mul_f32_e32 v34, v32, v50
	v_mul_f32_e32 v35, v33, v50
	v_cvt_pk_bf16_f32 v32, v36, v37
	v_mad_i64_i32 v[36:37], s[20:21], v118, s31, v[48:49]
	v_mul_f32_e32 v38, v114, v38
	v_mul_f32_e32 v39, v115, v39
	v_lshlrev_b64 v[36:37], 7, v[36:37]
	v_cvt_f32_i32_e32 v25, v25
	v_cvt_f32_i32_e32 v27, v27
	v_cvt_f32_i32_e32 v26, v26
	v_cvt_f32_i32_e32 v24, v24
	v_mul_f32_e32 v38, v38, v50
	v_mul_f32_e32 v39, v39, v50
	v_lshl_add_u64 v[36:37], v[152:153], 0, v[36:37]
	v_cvt_pk_bf16_f32 v33, v38, v39
	v_cvt_pk_bf16_f32 v34, v34, v35
	v_cvt_pk_bf16_f32 v35, v40, v41
	global_store_dwordx4 v[36:37], v[32:35], off
	v_cvt_f32_i32_e32 v31, v31
	v_cvt_f32_i32_e32 v30, v30
	v_mul_f32_e32 v33, 0x3e38aa3b, v125
	v_cvt_f32_i32_e32 v21, v21
	v_cvt_f32_i32_e32 v20, v20
	v_add_u32_e32 v32, 0xa0, v162
	v_cndmask_b32_e32 v34, v125, v33, vcc
	v_mul_f32_e32 v28, v128, v28
	v_mul_f32_e32 v29, v129, v29
	v_cvt_f32_i32_e32 v17, v17
	v_cvt_f32_i32_e32 v19, v19
	v_cvt_f32_i32_e32 v18, v18
	v_cvt_f32_i32_e32 v16, v16
	v_ashrrev_i32_e32 v33, 31, v32
	v_mul_f32_e32 v28, v28, v34
; __device__ __forceinline__ unsigned cvt_pk_bf16(float lo, float hi) { unsigned r; asm volatile("v_cvt_pk_bf16_f32 %0, %1, %2" : "=v"(r) : "v"(lo), "v"(hi)); return r; }
; #define PG8_BAR __builtin_amdgcn_s_barrier()
;     __device__ __forceinline__ void operator()(const i32x4 (&acc)[2][2][4][2], const Unit& u, int wr, int wc, int fr, int fq) const {
;     ...
;                 const int r = row0 + ai * HALF + m * 16;
;                 float sc = sav[4 * ai + m]; if (qscale != 0.f && (u.pn < 4 || (u.pn >= 12 && u.pn < 16))) sc *= qscale;
;                 bf16_t* rowp = O + (size_t)r * ldc + col0;
; #pragma unroll
;                 for (int bj = 0; bj < 2; ++bj) { const i32x4 a0 = acc[ai][bj][m][0], a1 = acc[ai][bj][m][1];
;                     const f32x4 v0 = (f32x4){(float)a0[0], (float)a0[1], (float)a0[2], (float)a0[3]} * w0[bj] * sc, v1 = (f32x4){(float)a1[0], (float)a1[1], (float)a1[2], (float)a1[3]} * w1[bj] * sc;
;                     u32x4 w; w.x = cvt_pk_bf16(v0[0], v0[1]); w.y = cvt_pk_bf16(v0[2], v0[3]); w.z = cvt_pk_bf16(v1[0], v1[1]); w.w = cvt_pk_bf16(v1[2], v1[3]);
;                     if (hm_rows) { const int c = col0 + bj * HALF; *(u32x4*)(O + ((size_t)(c >> 6) * hm_rows + r) * 64 + (c & 63)) = w; }
;                     else *(u32x4*)(rowp + bj * HALF) = w; } }
; template <class Epi, class Sched, bool ALIGN_EPI = false, bool SP2 = false>
; __device__ __forceinline__ void gemm_phase(PG8_LAS unsigned char* lds, const Gemm g, const Sched& S, const Epi& E, int wid  ) {
;     ...
;         if (!has_next) break;
; #pragma unroll
;         for (int a = 0; a < 2; ++a)
; #pragma unroll
;             for (int b = 0; b < 2; ++b)
; #pragma unroll
;                 for (int m = 0; m < 4; ++m)
; #pragma unroll
;                     for (int n = 0; n < 2; ++n) acc[a][b][m][n] = (acc_t){0, 0, 0, 0};
;         cur = nxt; cA = nA; cB = nB; ++ui;
;         if constexpr (ALIGN_EPI) { if (wr == 1) PG8_BAR; }
	v_mul_f32_e32 v29, v29, v34
	v_mul_f32_e32 v26, v122, v26
	v_mul_f32_e32 v27, v123, v27
	v_mul_f32_e32 v24, v120, v24
	v_mul_f32_e32 v25, v121, v25
	v_mul_f32_e32 v36, v26, v34
	v_mul_f32_e32 v37, v27, v34
	v_mul_f32_e32 v26, v24, v34
	v_mul_f32_e32 v27, v25, v34
	v_cvt_pk_bf16_f32 v24, v28, v29
	v_mad_i64_i32 v[28:29], s[20:21], v119, s31, v[32:33]
	v_cvt_f32_i32_e32 v23, v23
	v_cvt_f32_i32_e32 v22, v22
	v_mul_f32_e32 v30, v130, v30
	v_mul_f32_e32 v31, v131, v31
	v_lshlrev_b64 v[28:29], 7, v[28:29]
	v_mul_f32_e32 v20, v112, v20
	v_mul_f32_e32 v21, v113, v21
	v_mul_f32_e32 v30, v30, v34
	v_mul_f32_e32 v31, v31, v34
	v_lshl_add_u64 v[28:29], v[152:153], 0, v[28:29]
	v_cvt_pk_bf16_f32 v25, v30, v31
	v_mul_f32_e32 v20, v20, v34
	v_mul_f32_e32 v21, v21, v34
	v_mul_f32_e32 v18, v110, v18
	v_mul_f32_e32 v19, v111, v19
	v_mul_f32_e32 v16, v108, v16
	v_mul_f32_e32 v17, v109, v17
	v_cvt_pk_bf16_f32 v26, v26, v27
	v_cvt_pk_bf16_f32 v27, v36, v37
	global_store_dwordx4 v[28:29], v[24:27], off
	v_cvt_f32_i32_e32 v13, v13
	v_cvt_f32_i32_e32 v12, v12
	v_mul_f32_e32 v24, v18, v34
	v_mul_f32_e32 v25, v19, v34
	v_mul_f32_e32 v18, v16, v34
	v_mul_f32_e32 v19, v17, v34
	v_cvt_pk_bf16_f32 v16, v20, v21
	v_mad_i64_i32 v[20:21], s[20:21], v118, s31, v[32:33]
	v_mul_f32_e32 v22, v114, v22
	v_mul_f32_e32 v23, v115, v23
	v_lshlrev_b64 v[20:21], 7, v[20:21]
	v_cvt_f32_i32_e32 v9, v9
	v_cvt_f32_i32_e32 v11, v11
	v_cvt_f32_i32_e32 v10, v10
	v_cvt_f32_i32_e32 v8, v8
	v_mul_f32_e32 v22, v22, v34
	v_mul_f32_e32 v23, v23, v34
	v_lshl_add_u64 v[20:21], v[152:153], 0, v[20:21]
	v_cvt_pk_bf16_f32 v17, v22, v23
	v_cvt_pk_bf16_f32 v18, v18, v19
	v_cvt_pk_bf16_f32 v19, v24, v25
	global_store_dwordx4 v[20:21], v[16:19], off
	v_cvt_f32_i32_e32 v15, v15
	v_cvt_f32_i32_e32 v14, v14
	v_mul_f32_e32 v17, 0x3e38aa3b, v124
	v_cvt_f32_i32_e32 v5, v5
	v_cvt_f32_i32_e32 v4, v4
	v_add_u32_e32 v16, 0xb0, v162
	v_cndmask_b32_e32 v18, v124, v17, vcc
	v_mul_f32_e32 v12, v128, v12
	v_mul_f32_e32 v13, v129, v13
	v_cvt_f32_i32_e32 v1, v1
	v_cvt_f32_i32_e32 v3, v3
	v_cvt_f32_i32_e32 v2, v2
	v_cvt_f32_i32_e32 v0, v0
	v_ashrrev_i32_e32 v17, 31, v16
	v_mul_f32_e32 v12, v12, v18
	v_mul_f32_e32 v13, v13, v18
	v_mul_f32_e32 v10, v122, v10
	v_mul_f32_e32 v11, v123, v11
	v_mul_f32_e32 v8, v120, v8
	v_mul_f32_e32 v9, v121, v9
	v_mul_f32_e32 v20, v10, v18
	v_mul_f32_e32 v21, v11, v18
	v_mul_f32_e32 v10, v8, v18
	v_mul_f32_e32 v11, v9, v18
	v_cvt_pk_bf16_f32 v8, v12, v13
	v_mad_i64_i32 v[12:13], s[20:21], v119, s31, v[16:17]
	v_mul_f32_e32 v14, v130, v14
	v_mul_f32_e32 v15, v131, v15
	v_lshlrev_b64 v[12:13], 7, v[12:13]
	v_cvt_f32_i32_e32 v7, v7
	v_cvt_f32_i32_e32 v6, v6
	v_mul_f32_e32 v4, v112, v4
	v_mul_f32_e32 v5, v113, v5
	v_mul_f32_e32 v14, v14, v18
	v_mul_f32_e32 v15, v15, v18
	v_lshl_add_u64 v[12:13], v[152:153], 0, v[12:13]
	v_cvt_pk_bf16_f32 v9, v14, v15
	v_mul_f32_e32 v4, v4, v18
	v_mul_f32_e32 v5, v5, v18
	v_mul_f32_e32 v2, v110, v2
	v_mul_f32_e32 v3, v111, v3
	v_mul_f32_e32 v0, v108, v0
	v_mul_f32_e32 v1, v109, v1
	v_cvt_pk_bf16_f32 v10, v10, v11
	v_cvt_pk_bf16_f32 v11, v20, v21
	global_store_dwordx4 v[12:13], v[8:11], off
	v_mul_f32_e32 v6, v114, v6
	v_mul_f32_e32 v7, v115, v7
	s_andn2_b64 vcc, exec, s[4:5]
	v_mul_f32_e32 v8, v2, v18
	v_mul_f32_e32 v9, v3, v18
	v_mul_f32_e32 v2, v0, v18
	v_mul_f32_e32 v3, v1, v18
	v_cvt_pk_bf16_f32 v0, v4, v5
	v_mad_i64_i32 v[4:5], s[20:21], v118, s31, v[16:17]
	v_lshlrev_b64 v[4:5], 7, v[4:5]
	v_lshl_add_u64 v[4:5], v[152:153], 0, v[4:5]
	s_mov_b64 s[4:5], -1
	v_mul_f32_e32 v6, v6, v18
	v_mul_f32_e32 v7, v7, v18
	s_nop 0
	v_cvt_pk_bf16_f32 v1, v6, v7
	v_cvt_pk_bf16_f32 v2, v2, v3
	v_cvt_pk_bf16_f32 v3, v8, v9
	global_store_dwordx4 v[4:5], v[0:3], off
	s_cbranch_vccnz .LBB0_151
	s_and_b64 vcc, exec, s[54:55]
	s_cbranch_vccnz .LBB0_150
	s_barrier
	s_branch .LBB0_150

; #define LAS __attribute__((address_space(3)))
;     ...
;     for (int j = jbeg; j < jend; ++j) {
;         const int kt0 = kp0 + 32 * j;
;         const int jn = (j + 1 < NTILE) ? j + 1 : j;
;         if (!(kt0 + 31 < 0 || kt0 >= Lsub)) {
;     ...
;         } else {
; #pragma unroll
;             for (int ks = 0; ks < 4; ++ks) kf[ks] = *(const LAS bf16x8*)(kb + 4096 * jn + koff[ks]);
;         }
.LBB0_313:
	s_add_i32 s72, s4, s91
	s_add_i32 s94, s93, 1
	s_add_i32 s95, s72, 0xffffff80
	s_cmpk_lg_i32 s91, 0x100
	s_cselect_b32 s73, s94, 8
	s_cmpk_gt_i32 s95, 0xffe0
	s_cselect_b64 s[74:75], -1, 0
	s_cmp_lt_i32 s95, s88
	s_cselect_b64 s[76:77], -1, 0
	s_and_b64 s[74:75], s[74:75], s[76:77]
	s_mov_b64 s[76:77], -1
	s_and_b64 vcc, exec, s[74:75]
	v_lshl_add_u32 v14, s73, 12, v241
	s_cbranch_vccnz .Lp2t_6933
	v_add_u32_e32 v1, v14, v237
	v_add_u32_e32 v6, v14, v238
	ds_read_b128 v[2:5], v1
	ds_read_b128 v[6:9], v6
	v_add_u32_e32 v1, v14, v239
	v_add_u32_e32 v15, v14, v240
	ds_read_b128 v[10:13], v1
	ds_read_b128 v[144:147], v15
	s_mov_b64 s[76:77], 0
	s_branch .LBB0_337

; #define LAS __attribute__((address_space(3)))
;     ...
;             s16x4 vlo[2][2], vhi[2][2];
; #pragma unroll
;             for (int st = 0; st < 2; ++st) {
;                 vlo[0][st] = __builtin_bit_cast(s16x4, __builtin_amdgcn_ds_read_tr16_b64_v4i16((LAS s16x4*)(vb0 + 4096 * j + 2048 * st)));
;                 vhi[0][st] = __builtin_bit_cast(s16x4, __builtin_amdgcn_ds_read_tr16_b64_v4i16((LAS s16x4*)(vb0 + 4096 * j + 2048 * st + 1024)));
;                 vlo[1][st] = __builtin_bit_cast(s16x4, __builtin_amdgcn_ds_read_tr16_b64_v4i16((LAS s16x4*)(vb1 + 4096 * j + 2048 * st)));
;                 vhi[1][st] = __builtin_bit_cast(s16x4, __builtin_amdgcn_ds_read_tr16_b64_v4i16((LAS s16x4*)(vb1 + 4096 * j + 2048 * st + 1024))); }
;             f32x16 s; float cj;
;             const float cl = slope2 * (float)(32 * j - HALFW - ql);
;             if (j < JM) { s = __builtin_amdgcn_mfma_f32_32x32x16_bf16(kf[0], qf[0], CL, 0, 0, 0); cj = cl; }
;             else if (j == JM) { s = __builtin_amdgcn_mfma_f32_32x32x16_bf16(kf[0], qf[0], CM, 0, 0, 0); cj = 0.f; }
;             else { s = __builtin_amdgcn_mfma_f32_32x32x16_bf16(kf[0], qf[0], CR, 0, 0, 0); cj = -cl; }
.Lp2t_6933:
	s_waitcnt lgkmcnt(3)
	v_add_u32_e32 v1, v244, v242
	v_add_u32_e32 v4, v243, v242
	v_add_u32_e32 v1, 0x10000, v1
	v_add_u32_e32 v4, 0x10000, v4
	ds_read_b64_tr_b16 v[208:209], v1
	ds_read_b64_tr_b16 v[210:211], v1 offset:1024
	s_waitcnt lgkmcnt(3)
	ds_read_b64_tr_b16 v[10:11], v4
	ds_read_b64_tr_b16 v[12:13], v4 offset:1024
	ds_read_b64_tr_b16 v[6:7], v1 offset:2048
	ds_read_b64_tr_b16 v[8:9], v1 offset:3072
	v_add_u32_e32 v2, s91, v245
	v_cvt_f32_i32_e32 v15, v2
	ds_read_b64_tr_b16 v[2:3], v4 offset:2048
	ds_read_b64_tr_b16 v[4:5], v4 offset:3072
	s_cmp_gt_u32 s93, 3
	s_mov_b64 s[76:77], -1
	v_mul_f32_e32 v15, v232, v15
	s_cbranch_scc0 .Lp2t_6995
	s_cmpk_lg_i32 s91, 0x80
	s_cbranch_scc0 .Lp2t_6969
	v_xor_b32_e32 v1, 0x80000000, v15
	s_mov_b64 s[76:77], 0
	s_waitcnt vmcnt(3)
	v_mfma_f32_32x32x16_bf16 v[144:159], v[204:207], v[176:179], v[112:127]
	s_branch .LBB0_321

;     ...
;             if (j < JM) { s = __builtin_amdgcn_mfma_f32_32x32x16_bf16(kf[0], qf[0], CL, 0, 0, 0); cj = cl; }
;             else if (j == JM) { s = __builtin_amdgcn_mfma_f32_32x32x16_bf16(kf[0], qf[0], CM, 0, 0, 0); cj = 0.f; }
;             else { s = __builtin_amdgcn_mfma_f32_32x32x16_bf16(kf[0], qf[0], CR, 0, 0, 0); cj = -cl; }
.Lp2t_6969:
	s_nop 9
	v_xor_b32_e32 v159, 0x80000000, v129
	v_xor_b32_e32 v158, 0x80000000, v128
	v_xor_b32_e32 v157, 0x80000000, v131
	v_xor_b32_e32 v156, 0x80000000, v130
	v_xor_b32_e32 v155, 0x80000000, v133
	v_xor_b32_e32 v154, 0x80000000, v132
	v_xor_b32_e32 v153, 0x80000000, v135
	v_xor_b32_e32 v152, 0x80000000, v134
	v_xor_b32_e32 v151, 0x80000000, v137
	v_xor_b32_e32 v150, 0x80000000, v136
	v_xor_b32_e32 v149, 0x80000000, v139
	v_xor_b32_e32 v148, 0x80000000, v138
	v_xor_b32_e32 v147, 0x80000000, v141
	v_xor_b32_e32 v146, 0x80000000, v140
	v_xor_b32_e32 v145, 0x80000000, v143
	v_xor_b32_e32 v144, 0x80000000, v142
	v_mov_b32_e32 v1, 0
	s_waitcnt vmcnt(3)
	v_mfma_f32_32x32x16_bf16 v[144:159], v[204:207], v[176:179], v[144:159]
.LBB0_321:
	s_mov_b64 s[76:77], 0
	s_branch .LBB0_324

;     ...
;             if (j < JM) { s = __builtin_amdgcn_mfma_f32_32x32x16_bf16(kf[0], qf[0], CL, 0, 0, 0); cj = cl; }
.Lp2t_6995:
	s_waitcnt vmcnt(3)
	v_mfma_f32_32x32x16_bf16 v[144:159], v[204:207], v[176:179], v[96:111]
	v_mov_b32_e32 v1, v15

;     ...
;             if (j == 0) {
; #pragma unroll
;                 for (int reg = 0; reg < 16; ++reg) s[reg] = ((reg & 3) + 8 * (reg >> 2) >= ql4) ? s[reg] : -INFINITY;
.Lp2t_7045:
	s_cmp_eq_u32 s93, 0
	s_cbranch_scc0 .LBB0_331
	s_nop 4
	v_cndmask_b32_e64 v144, v144, v235, s[96:97]
	v_cndmask_b32_e64 v145, v145, v235, s[44:45]
	v_cndmask_b32_e64 v146, v146, v235, s[46:47]
	v_cndmask_b32_e64 v147, v147, v235, s[82:83]
	v_cndmask_b32_e64 v148, v148, v235, s[84:85]
	v_cndmask_b32_e64 v149, v149, v235, s[78:79]
	v_cndmask_b32_e64 v150, v150, v235, s[86:87]
	v_cndmask_b32_e64 v151, v151, v235, s[0:1]
	v_cndmask_b32_e64 v152, v152, v235, s[56:57]
	v_cndmask_b32_e64 v153, v153, v235, s[58:59]
	v_cndmask_b32_e64 v154, v154, v235, s[60:61]
	v_cndmask_b32_e64 v155, v155, v235, s[62:63]
	v_cndmask_b32_e64 v156, v156, v235, s[64:65]
	v_cndmask_b32_e64 v157, v157, v235, s[66:67]
	v_cndmask_b32_e64 v158, v158, v235, s[68:69]
	v_cndmask_b32_e64 v159, v159, v235, s[70:71]

; __device__ __forceinline__ unsigned pk2(float lo, float hi) { const f32x2 v = {lo, hi}; return __builtin_bit_cast(unsigned, __builtin_convertvector(v, bf16x2_t)); }
;     ...
;             const float dd = cj - m;
;             f32x2 ps2 = {0.f, 0.f}; const f32x2 dd2 = {dd, dd};
; #pragma unroll
;             for (int rp = 0; rp < 8; ++rp) { f32x2 t; { const f32x2 in_ = {s[2 * rp], s[2 * rp + 1]}; asm("v_pk_add_f32 %0, %1, %2" : "=v"(t) : "v"(in_), "v"(dd2)); } t[0] = __builtin_amdgcn_exp2f(t[0]); t[1] = __builtin_amdgcn_exp2f(t[1]); s[2 * rp] = t[0]; s[2 * rp + 1] = t[1]; asm("v_pk_add_f32 %0, %1, %2" : "=v"(ps2) : "v"(ps2), "v"(t)); }
;             lsum += ps2[0] + ps2[1];
;             bf16x8 pf[2];
; #pragma unroll
;             for (int st = 0; st < 2; ++st) { v4u t; t.x = pk2(s[8 * st + 0], s[8 * st + 1]); t.y = pk2(s[8 * st + 2], s[8 * st + 3]); t.z = pk2(s[8 * st + 4], s[8 * st + 5]); t.w = pk2(s[8 * st + 6], s[8 * st + 7]); pf[st] = __builtin_bit_cast(bf16x8, t); }
; #pragma unroll
;             for (int st = 0; st < 2; ++st) {
;                 const bf16x8 v0 = (bf16x8){vlo[0][st][0], vlo[0][st][1], vlo[0][st][2], vlo[0][st][3], vhi[0][st][0], vhi[0][st][1], vhi[0][st][2], vhi[0][st][3]};
;                 const bf16x8 v1 = (bf16x8){vlo[1][st][0], vlo[1][st][1], vlo[1][st][2], vlo[1][st][3], vhi[1][st][0], vhi[1][st][1], vhi[1][st][2], vhi[1][st][3]};
;                 o0 = __builtin_amdgcn_mfma_f32_32x32x16_bf16(v0, pf[st], o0, 0, 0, 0);
;                 o1 = __builtin_amdgcn_mfma_f32_32x32x16_bf16(v1, pf[st], o1, 0, 0, 0); }
.LBB0_336:
	v_sub_f32_e32 v14, v1, v252
	v_add_f32_e32 v144, v144, v14
	v_add_f32_e32 v145, v145, v14
	v_add_f32_e32 v146, v146, v14
	v_add_f32_e32 v147, v147, v14
	v_add_f32_e32 v148, v148, v14
	v_add_f32_e32 v149, v149, v14
	v_add_f32_e32 v150, v150, v14
	v_add_f32_e32 v151, v151, v14
	v_exp_f32_e32 v144, v144
	v_exp_f32_e32 v145, v145
	v_exp_f32_e32 v146, v146
	v_exp_f32_e32 v147, v147
	v_exp_f32_e32 v148, v148
	v_exp_f32_e32 v149, v149
	v_exp_f32_e32 v150, v150
	v_exp_f32_e32 v151, v151
	v_add_f32_e32 v160, v144, v146
	v_add_f32_e32 v161, v145, v147
	v_cvt_pk_bf16_f32 v144, v144, v145
	v_cvt_pk_bf16_f32 v145, v146, v147
	v_cvt_pk_bf16_f32 v146, v148, v149
	v_cvt_pk_bf16_f32 v147, v150, v151
	v_add_f32_e32 v152, v152, v14
	v_add_f32_e32 v153, v153, v14
	v_add_f32_e32 v154, v154, v14
	v_add_f32_e32 v155, v155, v14
	v_add_f32_e32 v156, v156, v14
	v_add_f32_e32 v157, v157, v14
	s_nop 0
	v_exp_f32_e32 v152, v152
	s_waitcnt lgkmcnt(0)
	v_mfma_f32_32x32x16_bf16 v[80:95], v[208:211], v[144:147], v[80:95]
	v_exp_f32_e32 v153, v153
	v_exp_f32_e32 v154, v154
	v_exp_f32_e32 v155, v155
	v_exp_f32_e32 v156, v156
	v_exp_f32_e32 v157, v157
	v_mfma_f32_32x32x16_bf16 v[64:79], v[10:13], v[144:147], v[64:79]
	v_add_f32_e32 v10, v158, v14
	v_add_f32_e32 v11, v159, v14
	v_cvt_pk_bf16_f32 v12, v156, v157
	v_exp_f32_e32 v14, v10
	v_exp_f32_e32 v15, v11
	v_cvt_pk_bf16_f32 v10, v152, v153
	v_cvt_pk_bf16_f32 v11, v154, v155
	v_cvt_pk_bf16_f32 v13, v14, v15
	s_nop 1
	v_mfma_f32_32x32x16_bf16 v[80:95], v[6:9], v[10:13], v[80:95]
	v_add_f32_e32 v6, v160, v148
	v_add_f32_e32 v7, v161, v149
	s_nop 0
	v_add_f32_e32 v6, v6, v150
	v_add_f32_e32 v7, v7, v151
	s_nop 0
	v_add_f32_e32 v6, v6, v152
	v_add_f32_e32 v7, v7, v153
	s_nop 0
	v_add_f32_e32 v6, v6, v154
	v_add_f32_e32 v7, v7, v155
	v_mfma_f32_32x32x16_bf16 v[64:79], v[2:5], v[10:13], v[64:79]
	v_add_f32_e32 v6, v6, v156
	v_add_f32_e32 v7, v7, v157
	s_nop 0
	v_add_f32_e32 v6, v6, v14
	v_add_f32_e32 v7, v7, v15
	s_nop 0
	v_add_f32_e32 v1, v6, v7
	v_add_f32_e32 v253, v253, v1
	s_branch .LBB0_338

; #define LAS __attribute__((address_space(3)))
;     ...
;     for (int j = jbeg; j < jend; ++j) {
;         const int kt0 = kp0 + 32 * j;
;         const int jn = (j + 1 < NTILE) ? j + 1 : j;
;         if (!(kt0 + 31 < 0 || kt0 >= Lsub)) {
;     ...
;         } else {
; #pragma unroll
;             for (int ks = 0; ks < 4; ++ks) kf[ks] = *(const LAS bf16x8*)(kb + 4096 * jn + koff[ks]);
;         }
.LBB0_343:
	s_add_i32 s72, s4, s91
	s_add_i32 s92, s93, 1
	s_sub_i32 s73, s72, 64
	s_cmpk_lg_i32 s91, 0x80
	s_cselect_b32 s80, s92, 4
	s_cmpk_gt_i32 s73, 0xffe0
	s_cselect_b64 s[74:75], -1, 0
	s_cmp_lt_i32 s73, s88
	s_cselect_b64 s[76:77], -1, 0
	s_and_b64 s[74:75], s[74:75], s[76:77]
	s_mov_b64 s[76:77], -1
	s_and_b64 vcc, exec, s[74:75]
	v_lshl_add_u32 v14, s80, 12, v241
	s_cbranch_vccnz .Lp2t_7509
	v_add_u32_e32 v1, v14, v237
	v_add_u32_e32 v6, v14, v238
	ds_read_b128 v[2:5], v1
	ds_read_b128 v[6:9], v6
	v_add_u32_e32 v1, v14, v239
	v_add_u32_e32 v15, v14, v240
	ds_read_b128 v[10:13], v1
	ds_read_b128 v[96:99], v15
	s_mov_b64 s[76:77], 0
	s_branch .LBB0_367

; #define LAS __attribute__((address_space(3)))
;     ...
;             s16x4 vlo[2][2], vhi[2][2];
; #pragma unroll
;             for (int st = 0; st < 2; ++st) {
;                 vlo[0][st] = __builtin_bit_cast(s16x4, __builtin_amdgcn_ds_read_tr16_b64_v4i16((LAS s16x4*)(vb0 + 4096 * j + 2048 * st)));
;                 vhi[0][st] = __builtin_bit_cast(s16x4, __builtin_amdgcn_ds_read_tr16_b64_v4i16((LAS s16x4*)(vb0 + 4096 * j + 2048 * st + 1024)));
;                 vlo[1][st] = __builtin_bit_cast(s16x4, __builtin_amdgcn_ds_read_tr16_b64_v4i16((LAS s16x4*)(vb1 + 4096 * j + 2048 * st)));
;                 vhi[1][st] = __builtin_bit_cast(s16x4, __builtin_amdgcn_ds_read_tr16_b64_v4i16((LAS s16x4*)(vb1 + 4096 * j + 2048 * st + 1024))); }
;             f32x16 s; float cj;
;             const float cl = slope2 * (float)(32 * j - HALFW - ql);
;             if (j < JM) { s = __builtin_amdgcn_mfma_f32_32x32x16_bf16(kf[0], qf[0], CL, 0, 0, 0); cj = cl; }
;             else if (j == JM) { s = __builtin_amdgcn_mfma_f32_32x32x16_bf16(kf[0], qf[0], CM, 0, 0, 0); cj = 0.f; }
;             else { s = __builtin_amdgcn_mfma_f32_32x32x16_bf16(kf[0], qf[0], CR, 0, 0, 0); cj = -cl; }
.Lp2t_7509:
	s_waitcnt lgkmcnt(3)
	v_add_u32_e32 v1, v150, v242
	v_add_u32_e32 v4, v151, v242
	v_add_u32_e32 v1, 0x10000, v1
	v_add_u32_e32 v4, 0x10000, v4
	ds_read_b64_tr_b16 v[144:145], v1
	ds_read_b64_tr_b16 v[146:147], v1 offset:1024
	s_waitcnt lgkmcnt(3)
	ds_read_b64_tr_b16 v[10:11], v4
	ds_read_b64_tr_b16 v[12:13], v4 offset:1024
	ds_read_b64_tr_b16 v[6:7], v1 offset:2048
	ds_read_b64_tr_b16 v[8:9], v1 offset:3072
	v_add_u32_e32 v2, s91, v247
	v_cvt_f32_i32_e32 v15, v2
	ds_read_b64_tr_b16 v[2:3], v4 offset:2048
	ds_read_b64_tr_b16 v[4:5], v4 offset:3072
	s_cmp_gt_u32 s93, 1
	s_mov_b64 s[76:77], -1
	v_mul_f32_e32 v15, v230, v15
	s_cbranch_scc0 .Lp2t_7571
	s_cmp_lg_u32 s91, 64
	s_cbranch_scc0 .Lp2t_7545
	v_xor_b32_e32 v1, 0x80000000, v15
	s_mov_b64 s[76:77], 0
	s_waitcnt vmcnt(11)
	v_mfma_f32_32x32x16_bf16 v[96:111], v[140:143], v[176:179], v[32:47]
	s_branch .LBB0_351

;     ...
;             if (j < JM) { s = __builtin_amdgcn_mfma_f32_32x32x16_bf16(kf[0], qf[0], CL, 0, 0, 0); cj = cl; }
;             else if (j == JM) { s = __builtin_amdgcn_mfma_f32_32x32x16_bf16(kf[0], qf[0], CM, 0, 0, 0); cj = 0.f; }
;             else { s = __builtin_amdgcn_mfma_f32_32x32x16_bf16(kf[0], qf[0], CR, 0, 0, 0); cj = -cl; }
.Lp2t_7545:
	s_nop 9
	v_xor_b32_e32 v111, 0x80000000, v51
	v_xor_b32_e32 v110, 0x80000000, v50
	v_xor_b32_e32 v109, 0x80000000, v53
	v_xor_b32_e32 v108, 0x80000000, v52
	v_xor_b32_e32 v107, 0x80000000, v55
	v_xor_b32_e32 v106, 0x80000000, v54
	v_xor_b32_e32 v105, 0x80000000, v57
	v_xor_b32_e32 v104, 0x80000000, v56
	v_xor_b32_e32 v103, 0x80000000, v59
	v_xor_b32_e32 v102, 0x80000000, v58
	v_xor_b32_e32 v101, 0x80000000, v61
	v_xor_b32_e32 v100, 0x80000000, v60
	v_xor_b32_e32 v99, 0x80000000, v49
	v_xor_b32_e32 v98, 0x80000000, v48
	v_xor_b32_e32 v97, 0x80000000, v63
	v_xor_b32_e32 v96, 0x80000000, v62
	v_mov_b32_e32 v1, 0
	s_waitcnt vmcnt(11)
	v_mfma_f32_32x32x16_bf16 v[96:111], v[140:143], v[176:179], v[96:111]

;     ...
;             if (j < JM) { s = __builtin_amdgcn_mfma_f32_32x32x16_bf16(kf[0], qf[0], CL, 0, 0, 0); cj = cl; }
.Lp2t_7571:
	s_waitcnt vmcnt(11)
	v_mfma_f32_32x32x16_bf16 v[96:111], v[140:143], v[176:179], v[16:31]
	v_mov_b32_e32 v1, v15

;     ...
;             if (j == 0) {
; #pragma unroll
;                 for (int reg = 0; reg < 16; ++reg) s[reg] = ((reg & 3) + 8 * (reg >> 2) >= ql4) ? s[reg] : -INFINITY;
.Lp2t_7621:
	s_cmp_eq_u32 s93, 0
	s_cbranch_scc0 .LBB0_361
	s_nop 4
	v_cndmask_b32_e64 v96, v96, v235, s[96:97]
	v_cndmask_b32_e64 v97, v97, v235, s[44:45]
	v_cndmask_b32_e64 v98, v98, v235, s[46:47]
	v_cndmask_b32_e64 v99, v99, v235, s[82:83]
	v_cndmask_b32_e64 v100, v100, v235, s[84:85]
	v_cndmask_b32_e64 v101, v101, v235, s[78:79]
	v_cndmask_b32_e64 v102, v102, v235, s[86:87]
	v_cndmask_b32_e64 v103, v103, v235, s[0:1]
	v_cndmask_b32_e64 v104, v104, v235, s[56:57]
	v_cndmask_b32_e64 v105, v105, v235, s[58:59]
	v_cndmask_b32_e64 v106, v106, v235, s[60:61]
	v_cndmask_b32_e64 v107, v107, v235, s[62:63]
	v_cndmask_b32_e64 v108, v108, v235, s[64:65]
	v_cndmask_b32_e64 v109, v109, v235, s[66:67]
	v_cndmask_b32_e64 v110, v110, v235, s[68:69]
	v_cndmask_b32_e64 v111, v111, v235, s[70:71]

; __device__ __forceinline__ unsigned pk2(float lo, float hi) { const f32x2 v = {lo, hi}; return __builtin_bit_cast(unsigned, __builtin_convertvector(v, bf16x2_t)); }
;     ...
;             const float dd = cj - m;
;             f32x2 ps2 = {0.f, 0.f}; const f32x2 dd2 = {dd, dd};
; #pragma unroll
;             for (int rp = 0; rp < 8; ++rp) { f32x2 t; { const f32x2 in_ = {s[2 * rp], s[2 * rp + 1]}; asm("v_pk_add_f32 %0, %1, %2" : "=v"(t) : "v"(in_), "v"(dd2)); } t[0] = __builtin_amdgcn_exp2f(t[0]); t[1] = __builtin_amdgcn_exp2f(t[1]); s[2 * rp] = t[0]; s[2 * rp + 1] = t[1]; asm("v_pk_add_f32 %0, %1, %2" : "=v"(ps2) : "v"(ps2), "v"(t)); }
;             lsum += ps2[0] + ps2[1];
;             bf16x8 pf[2];
; #pragma unroll
;             for (int st = 0; st < 2; ++st) { v4u t; t.x = pk2(s[8 * st + 0], s[8 * st + 1]); t.y = pk2(s[8 * st + 2], s[8 * st + 3]); t.z = pk2(s[8 * st + 4], s[8 * st + 5]); t.w = pk2(s[8 * st + 6], s[8 * st + 7]); pf[st] = __builtin_bit_cast(bf16x8, t); }
; #pragma unroll
;             for (int st = 0; st < 2; ++st) {
;                 const bf16x8 v0 = (bf16x8){vlo[0][st][0], vlo[0][st][1], vlo[0][st][2], vlo[0][st][3], vhi[0][st][0], vhi[0][st][1], vhi[0][st][2], vhi[0][st][3]};
;                 const bf16x8 v1 = (bf16x8){vlo[1][st][0], vlo[1][st][1], vlo[1][st][2], vlo[1][st][3], vhi[1][st][0], vhi[1][st][1], vhi[1][st][2], vhi[1][st][3]};
;                 o0 = __builtin_amdgcn_mfma_f32_32x32x16_bf16(v0, pf[st], o0, 0, 0, 0);
;                 o1 = __builtin_amdgcn_mfma_f32_32x32x16_bf16(v1, pf[st], o1, 0, 0, 0); }
.LBB0_366:
	v_sub_f32_e32 v14, v1, v148
	v_add_f32_e32 v96, v96, v14
	v_add_f32_e32 v97, v97, v14
	v_add_f32_e32 v98, v98, v14
	v_add_f32_e32 v99, v99, v14
	v_add_f32_e32 v100, v100, v14
	v_add_f32_e32 v101, v101, v14
	v_add_f32_e32 v102, v102, v14
	v_add_f32_e32 v103, v103, v14
	v_exp_f32_e32 v96, v96
	v_exp_f32_e32 v97, v97
	v_exp_f32_e32 v98, v98
	v_exp_f32_e32 v99, v99
	v_exp_f32_e32 v100, v100
	v_exp_f32_e32 v101, v101
	v_exp_f32_e32 v102, v102
	v_exp_f32_e32 v103, v103
	v_add_f32_e32 v112, v96, v98
	v_add_f32_e32 v113, v97, v99
	v_cvt_pk_bf16_f32 v96, v96, v97
	v_cvt_pk_bf16_f32 v97, v98, v99
	v_cvt_pk_bf16_f32 v98, v100, v101
	v_cvt_pk_bf16_f32 v99, v102, v103
	v_add_f32_e32 v104, v104, v14
	v_add_f32_e32 v105, v105, v14
	v_add_f32_e32 v106, v106, v14
	v_add_f32_e32 v107, v107, v14
	v_add_f32_e32 v108, v108, v14
	v_add_f32_e32 v109, v109, v14
	s_nop 0
	v_exp_f32_e32 v104, v104
	s_waitcnt lgkmcnt(0)
	v_mfma_f32_32x32x16_bf16 v[80:95], v[144:147], v[96:99], v[80:95]
	v_exp_f32_e32 v105, v105
	v_exp_f32_e32 v106, v106
	v_exp_f32_e32 v107, v107
	v_exp_f32_e32 v108, v108
	v_exp_f32_e32 v109, v109
	v_mfma_f32_32x32x16_bf16 v[64:79], v[10:13], v[96:99], v[64:79]
	v_add_f32_e32 v10, v110, v14
	v_add_f32_e32 v11, v111, v14
	v_cvt_pk_bf16_f32 v12, v108, v109
	v_exp_f32_e32 v14, v10
	v_exp_f32_e32 v15, v11
	v_cvt_pk_bf16_f32 v10, v104, v105
	v_cvt_pk_bf16_f32 v11, v106, v107
	v_cvt_pk_bf16_f32 v13, v14, v15
	s_nop 1
	v_mfma_f32_32x32x16_bf16 v[80:95], v[6:9], v[10:13], v[80:95]
	v_add_f32_e32 v6, v112, v100
	v_add_f32_e32 v7, v113, v101
	s_nop 0
	v_add_f32_e32 v6, v6, v102
	v_add_f32_e32 v7, v7, v103
	s_nop 0
	v_add_f32_e32 v6, v6, v104
	v_add_f32_e32 v7, v7, v105
	s_nop 0
	v_add_f32_e32 v6, v6, v106
	v_add_f32_e32 v7, v7, v107
	v_mfma_f32_32x32x16_bf16 v[64:79], v[2:5], v[10:13], v[64:79]
	v_add_f32_e32 v6, v6, v108
	v_add_f32_e32 v7, v7, v109
	s_nop 0
	v_add_f32_e32 v6, v6, v14
	v_add_f32_e32 v7, v7, v15
	s_nop 0
	v_add_f32_e32 v1, v6, v7
	v_add_f32_e32 v149, v149, v1
	s_branch .LBB0_368

; __device__ __forceinline__ void p3_finalize(Frame& F) {
;     ...
;         float ls[3]; v4u oa[3][2];
; #pragma unroll
;         for (int p = 0; p < 3; ++p) { ls[p] = ((const float*)(outb + OUT_LSE + (size_t)p * OUT_LSE_STRIDE))[(size_t)t * 16 + head];
;             const v4u* src = (const v4u*)((const bf16*)(outb + OUT_OA + (size_t)p * OUT_OA_STRIDE) + (size_t)t * 1024 + 16 * lane); oa[p][0] = src[0]; oa[p][1] = src[1]; }
;         const v4u* sb = (const v4u*)(OB + (size_t)t * 1024 + 16 * lane); const v4u ob0 = sb[0], ob1 = sb[1];
;         const float mx = fmaxf(fmaxf(ls[0], ls[1]), ls[2]);
;         float w0 = __builtin_amdgcn_exp2f(ls[0] - mx), w1 = __builtin_amdgcn_exp2f(ls[1] - mx), w2 = __builtin_amdgcn_exp2f(ls[2] - mx);
;         const float inv = 1.0f / (w0 + w1 + w2); w0 *= inv; w1 *= inv; w2 *= inv;
;         float a[16], b[16]; float sa = 0.f, sbq = 0.f;
; #pragma unroll
;         for (int q = 0; q < 2; ++q)
; #pragma unroll
;             for (int e = 0; e < 4; ++e) {
;                 const unsigned x0 = oa[0][q][e], x1 = oa[1][q][e], x2 = oa[2][q][e], y = (q == 0 ? ob0 : ob1)[e];
;                 const float lo = w0 * bflo(x0) + w1 * bflo(x1) + w2 * bflo(x2), hi = w0 * bfhi(x0) + w1 * bfhi(x1) + w2 * bfhi(x2);
;                 a[q * 8 + e * 2] = lo; a[q * 8 + e * 2 + 1] = hi; sa += lo * lo + hi * hi;
;                 const float bl = bflo(y), bh = bfhi(y); b[q * 8 + e * 2] = bl; b[q * 8 + e * 2 + 1] = bh; sbq += bl * bl + bh * bh; }
.LBB0_441:
	v_add_co_u32_e32 v38, vcc, 0xffd00000, v34
	v_lshl_add_u64 v[36:37], s[8:9], 0, v[32:33]
	s_nop 0
	v_addc_co_u32_e32 v39, vcc, -1, v35, vcc
	v_add_co_u32_e32 v60, vcc, s22, v34
	global_load_dword v81, v[34:35], off
	s_nop 0
	v_addc_co_u32_e32 v61, vcc, -1, v35, vcc
	v_add_co_u32_e32 v64, vcc, s23, v36
	global_load_dwordx4 v[52:55], v[36:37], off
	global_load_dwordx4 v[56:59], v[36:37], off offset:16
	global_load_dword v83, v[38:39], off
	global_load_dword v84, v[60:61], off
	v_addc_co_u32_e32 v65, vcc, 0, v37, vcc
	v_add_co_u32_e32 v70, vcc, s24, v36
	v_lshl_add_u64 v[40:41], s[14:15], 0, v[32:33]
	v_lshl_add_u64 v[62:63], v[36:37], 0, s[16:17]
	v_addc_co_u32_e32 v71, vcc, 0, v37, vcc
	v_lshl_add_u64 v[68:69], v[36:37], 0, s[18:19]
	v_lshl_add_u64 v[72:73], v[40:41], 0, s[20:21]
	global_load_dwordx4 v[60:63], v[62:63], off offset:16
	s_nop 0
	global_load_dwordx4 v[64:67], v[64:65], off
	v_add_co_u32_e32 v40, vcc, s25, v40
	global_load_dwordx4 v[36:39], v[68:69], off offset:16
	s_nop 0
	global_load_dwordx4 v[68:71], v[70:71], off
	v_addc_co_u32_e32 v41, vcc, 0, v41, vcc
	global_load_dwordx4 v[72:75], v[72:73], off offset:16
	s_nop 0
	global_load_dwordx4 v[76:79], v[40:41], off
	v_lshl_add_u64 v[42:43], s[2:3], 0, v[32:33]
	v_add_co_u32_e64 v42, s[0:1], s27, v42
	s_add_i32 s28, s28, s84
	s_nop 0
	v_addc_co_u32_e64 v43, s[0:1], 0, v43, s[0:1]
	s_add_u32 s2, s2, s6
	s_addc_u32 s3, s3, s7
	s_add_u32 s8, s8, s10
	s_addc_u32 s9, s9, s11
	s_add_u32 s14, s14, s10
	s_addc_u32 s15, s15, s11
	v_lshl_add_u64 v[34:35], v[34:35], 0, s[12:13]
	s_cmpk_lt_i32 s28, 0x6000
	s_waitcnt vmcnt(9)
	v_and_b32_e32 v91, 0xffff0000, v55
	s_waitcnt vmcnt(8)
	v_and_b32_e32 v85, 0xffff0000, v57
	s_waitcnt vmcnt(6)
	v_max3_f32 v40, v83, v84, v81
	v_sub_f32_e32 v102, v83, v40
	v_sub_f32_e32 v103, v84, v40
	v_lshlrev_b32_e32 v86, 16, v57
	v_and_b32_e32 v57, 0xffff0000, v56
	v_lshlrev_b32_e32 v88, 16, v56
	v_sub_f32_e32 v104, v81, v40
	v_exp_f32_e32 v128, v104
	v_and_b32_e32 v41, 0xffff0000, v59
	v_lshlrev_b32_e32 v80, 16, v59
	s_waitcnt vmcnt(5)
	v_lshlrev_b32_e32 v84, 16, v61
	v_and_b32_e32 v87, 0xffff0000, v61
	v_lshlrev_b32_e32 v56, 16, v60
	v_and_b32_e32 v89, 0xffff0000, v60
	v_exp_f32_e32 v61, v102
	v_exp_f32_e32 v60, v103
	v_and_b32_e32 v59, 0xffff0000, v58
	v_lshlrev_b32_e32 v82, 16, v58
	v_lshlrev_b32_e32 v92, 16, v55
	v_and_b32_e32 v55, 0xffff0000, v54
	v_lshlrev_b32_e32 v94, 16, v54
	v_and_b32_e32 v97, 0xffff0000, v53
	v_lshlrev_b32_e32 v98, 16, v53
	v_and_b32_e32 v53, 0xffff0000, v52
	v_lshlrev_b32_e32 v100, 16, v52
	v_lshlrev_b32_e32 v40, 16, v63
	v_and_b32_e32 v81, 0xffff0000, v63
	v_lshlrev_b32_e32 v58, 16, v62
	v_and_b32_e32 v83, 0xffff0000, v62
	s_waitcnt vmcnt(4)
	v_lshlrev_b32_e32 v90, 16, v67
	v_and_b32_e32 v93, 0xffff0000, v67
	v_lshlrev_b32_e32 v54, 16, v66
	v_and_b32_e32 v95, 0xffff0000, v66
	v_lshlrev_b32_e32 v96, 16, v65
	v_and_b32_e32 v99, 0xffff0000, v65
	v_lshlrev_b32_e32 v52, 16, v64
	v_and_b32_e32 v101, 0xffff0000, v64
	s_waitcnt vmcnt(3)
	v_lshlrev_b32_e32 v62, 16, v39
	v_and_b32_e32 v63, 0xffff0000, v39
	v_lshlrev_b32_e32 v64, 16, v38
	v_and_b32_e32 v65, 0xffff0000, v38
	v_lshlrev_b32_e32 v38, 16, v37
	v_and_b32_e32 v39, 0xffff0000, v37
	v_lshlrev_b32_e32 v66, 16, v36
	v_and_b32_e32 v67, 0xffff0000, v36
	s_waitcnt vmcnt(2)
	v_lshlrev_b32_e32 v36, 16, v71
	v_and_b32_e32 v37, 0xffff0000, v71
	v_lshlrev_b32_e32 v102, 16, v70
	v_and_b32_e32 v103, 0xffff0000, v70
	v_lshlrev_b32_e32 v70, 16, v69
	v_and_b32_e32 v71, 0xffff0000, v69
	v_lshlrev_b32_e32 v104, 16, v68
	v_and_b32_e32 v105, 0xffff0000, v68
	s_waitcnt vmcnt(1)
	v_lshlrev_b32_e32 v68, 16, v75
	v_and_b32_e32 v69, 0xffff0000, v75
	v_lshlrev_b32_e32 v106, 16, v74
	v_and_b32_e32 v107, 0xffff0000, v74
	v_lshlrev_b32_e32 v74, 16, v73
	v_and_b32_e32 v75, 0xffff0000, v73
	v_lshlrev_b32_e32 v108, 16, v72
	v_and_b32_e32 v109, 0xffff0000, v72
	s_waitcnt vmcnt(0)
	v_lshlrev_b32_e32 v72, 16, v79
	v_and_b32_e32 v73, 0xffff0000, v79
	v_lshlrev_b32_e32 v110, 16, v78
	v_and_b32_e32 v111, 0xffff0000, v78
	v_lshlrev_b32_e32 v78, 16, v77
	v_and_b32_e32 v79, 0xffff0000, v77
	v_lshlrev_b32_e32 v112, 16, v76
	v_and_b32_e32 v113, 0xffff0000, v76
	v_mov_b32_e32 v114, v69
	v_mov_b32_e32 v115, v107
	v_mul_f32_e32 v116, v74, v74
	v_mul_f32_e32 v117, v75, v75
	v_mul_f32_e32 v120, v72, v72
	v_mul_f32_e32 v121, v73, v73
	v_mul_f32_e32 v124, v78, v78
	v_mul_f32_e32 v125, v79, v79
	v_mul_f32_e32 v126, v112, v112
	v_mul_f32_e32 v127, v113, v113
	v_mov_b32_e32 v76, v68
	v_mov_b32_e32 v77, v106
	v_mul_f32_e32 v122, v110, v110
	v_mul_f32_e32 v123, v111, v111
	v_mul_f32_e32 v114, v114, v114
	v_mul_f32_e32 v115, v115, v115
	v_add_f32_e32 v120, v120, v121
	v_add_f32_e32 v121, v124, v125
	v_add_f32_e32 v124, v126, v127
	v_add_f32_e32 v116, v116, v117
	v_add_f32_e32 v117, v61, v60
	v_add_f32_e32 v122, v122, v123
	v_pk_fma_f32 v[76:77], v[76:77], v[76:77], v[114:115]
	v_add_f32_e32 v114, v124, v121
	v_add_f32_e32 v115, v128, v117
	v_mul_f32_e32 v118, v108, v108
	v_mul_f32_e32 v119, v109, v109
	v_add_f32_e32 v114, v122, v114
	v_div_scale_f32 v117, s[0:1], v115, v115, 1.0
	v_add_f32_e32 v118, v118, v119
	v_add_f32_e32 v114, v120, v114
	v_rcp_f32_e32 v120, v117
	v_add_f32_e32 v114, v118, v114
	v_add_f32_e32 v114, v116, v114
	v_add_f32_e32 v77, v77, v114
	v_add_f32_e32 v76, v76, v77
	v_fma_f32 v77, -v117, v120, 1.0
	v_div_scale_f32 v119, vcc, 1.0, v115, 1.0
	ds_bpermute_b32 v114, v44, v76
	v_fmac_f32_e32 v120, v77, v120
	v_mul_f32_e32 v77, v119, v120
	v_fma_f32 v116, -v117, v77, v119
	v_fmac_f32_e32 v77, v116, v120
	v_fma_f32 v116, -v117, v77, v119
	s_waitcnt lgkmcnt(0)
; __device__ __forceinline__ float wave_sum(float v) {
; #pragma unroll
;     for (int o = 1; o < 64; o <<= 1) v += __shfl_xor(v, o);
;     return v;
; __device__ __forceinline__ void p3_finalize(Frame& F) {
;     ...
;         const float mx = fmaxf(fmaxf(ls[0], ls[1]), ls[2]);
;         float w0 = __builtin_amdgcn_exp2f(ls[0] - mx), w1 = __builtin_amdgcn_exp2f(ls[1] - mx), w2 = __builtin_amdgcn_exp2f(ls[2] - mx);
;         const float inv = 1.0f / (w0 + w1 + w2); w0 *= inv; w1 *= inv; w2 *= inv;
;         float a[16], b[16]; float sa = 0.f, sbq = 0.f;
; #pragma unroll
;         for (int q = 0; q < 2; ++q)
; #pragma unroll
;             for (int e = 0; e < 4; ++e) {
;                 const unsigned x0 = oa[0][q][e], x1 = oa[1][q][e], x2 = oa[2][q][e], y = (q == 0 ? ob0 : ob1)[e];
;                 const float lo = w0 * bflo(x0) + w1 * bflo(x1) + w2 * bflo(x2), hi = w0 * bfhi(x0) + w1 * bfhi(x1) + w2 * bfhi(x2);
;                 a[q * 8 + e * 2] = lo; a[q * 8 + e * 2 + 1] = hi; sa += lo * lo + hi * hi;
;                 const float bl = bflo(y), bh = bfhi(y); b[q * 8 + e * 2] = bl; b[q * 8 + e * 2 + 1] = bh; sbq += bl * bl + bh * bh; }
;         const float ra = 1.0f / sqrtf(wave_sum(sa) * (1.0f / 1024.0f) + RMS_EPS), rb = 1.0f / sqrtf(wave_sum(sbq) * (1.0f / 1024.0f) + RMS_EPS);
	v_add_f32_e32 v117, v76, v114
	v_div_fmas_f32 v76, v116, v120, v77
	ds_bpermute_b32 v116, v45, v117
	v_div_fixup_f32 v76, v76, v115, 1.0
	v_mul_f32_e32 v60, v60, v76
	v_mul_f32_e32 v61, v61, v76
	v_mul_f32_e32 v114, v128, v76
	v_mul_f32_e32 v76, v61, v80
	v_mul_f32_e32 v77, v60, v81
	v_mul_f32_e32 v80, v61, v82
	v_mul_f32_e32 v81, v60, v83
	v_mul_f32_e32 v82, v61, v86
	v_mul_f32_e32 v83, v60, v87
	v_mul_f32_e32 v86, v61, v88
	v_mul_f32_e32 v87, v60, v89
	v_mul_f32_e32 v88, v61, v92
	v_mul_f32_e32 v89, v60, v93
	v_mul_f32_e32 v92, v61, v94
	v_mul_f32_e32 v93, v60, v95
	v_mul_f32_e32 v94, v61, v98
	v_mul_f32_e32 v95, v60, v99
	v_mul_f32_e32 v98, v61, v100
	v_mul_f32_e32 v99, v60, v101
	v_pk_fma_f32 v[40:41], v[60:61], v[40:41], v[76:77]
	v_pk_fma_f32 v[58:59], v[60:61], v[58:59], v[80:81]
	v_pk_fma_f32 v[76:77], v[60:61], v[84:85], v[82:83]
	v_pk_fma_f32 v[82:83], v[60:61], v[96:97], v[94:95]
	v_pk_fma_f32 v[52:53], v[60:61], v[52:53], v[98:99]
	v_pk_fma_f32 v[56:57], v[60:61], v[56:57], v[86:87]
	v_pk_fma_f32 v[80:81], v[60:61], v[90:91], v[88:89]
	v_pk_fma_f32 v[54:55], v[60:61], v[54:55], v[92:93]
	v_pk_fma_f32 v[40:41], v[114:115], v[62:63], v[40:41] op_sel_hi:[0,1,1]
	v_pk_fma_f32 v[58:59], v[114:115], v[64:65], v[58:59] op_sel_hi:[0,1,1]
	v_pk_fma_f32 v[60:61], v[114:115], v[70:71], v[82:83] op_sel_hi:[0,1,1]
	v_pk_fma_f32 v[52:53], v[114:115], v[104:105], v[52:53] op_sel_hi:[0,1,1]
	v_pk_fma_f32 v[54:55], v[114:115], v[102:103], v[54:55] op_sel_hi:[0,1,1]
	s_waitcnt lgkmcnt(0)
	v_add_f32_e32 v86, v117, v116
	v_mov_b32_e32 v64, v41
	v_mov_b32_e32 v65, v59
	v_mul_f32_e32 v82, v60, v60
	v_mul_f32_e32 v83, v61, v61
	v_mul_f32_e32 v84, v52, v52
	v_mul_f32_e32 v85, v53, v53
	v_pk_fma_f32 v[36:37], v[114:115], v[36:37], v[80:81] op_sel_hi:[0,1,1]
	v_mov_b32_e32 v62, v40
	v_mov_b32_e32 v63, v58
	v_mul_f32_e32 v80, v54, v54
	v_mul_f32_e32 v81, v55, v55
	ds_bpermute_b32 v87, v46, v86
	v_mul_f32_e32 v64, v64, v64
	v_mul_f32_e32 v65, v65, v65
	v_add_f32_e32 v82, v82, v83
	v_add_f32_e32 v83, v84, v85
	v_pk_fma_f32 v[38:39], v[114:115], v[38:39], v[76:77] op_sel_hi:[0,1,1]
	v_pk_fma_f32 v[56:57], v[114:115], v[66:67], v[56:57] op_sel_hi:[0,1,1]
	v_mul_f32_e32 v76, v36, v36
	v_mul_f32_e32 v77, v37, v37
	v_add_f32_e32 v80, v80, v81
	v_pk_fma_f32 v[62:63], v[62:63], v[62:63], v[64:65]
	v_add_f32_e32 v64, v83, v82
	v_mul_f32_e32 v70, v56, v56
	v_mul_f32_e32 v71, v57, v57
	v_add_f32_e32 v76, v76, v77
	v_add_f32_e32 v64, v80, v64
	v_mul_f32_e32 v66, v38, v38
	v_mul_f32_e32 v67, v39, v39
	v_add_f32_e32 v70, v70, v71
	v_add_f32_e32 v64, v76, v64
	v_add_f32_e32 v66, v66, v67
	v_add_f32_e32 v64, v70, v64
	s_waitcnt lgkmcnt(0)
	v_add_f32_e32 v65, v86, v87
	v_add_f32_e32 v64, v66, v64
	ds_bpermute_b32 v67, v47, v65
	v_add_f32_e32 v63, v63, v64
	v_add_f32_e32 v62, v62, v63
	ds_bpermute_b32 v63, v44, v62
	s_waitcnt lgkmcnt(1)
	v_add_f32_e32 v64, v65, v67
	ds_bpermute_b32 v65, v48, v64
	s_waitcnt lgkmcnt(1)
	v_add_f32_e32 v62, v62, v63
	ds_bpermute_b32 v63, v45, v62
	s_waitcnt lgkmcnt(1)
	v_add_f32_e32 v64, v64, v65
	ds_bpermute_b32 v65, v49, v64
	s_waitcnt lgkmcnt(1)
	v_add_f32_e32 v62, v62, v63
	ds_bpermute_b32 v63, v46, v62
	s_waitcnt lgkmcnt(1)
	v_add_f32_e32 v64, v64, v65
	v_fmamk_f32 v64, v64, 0x3a800000, v50
	v_mul_f32_e32 v65, 0x4f800000, v64
	v_cmp_gt_f32_e32 vcc, s26, v64
	s_waitcnt lgkmcnt(0)
	v_add_f32_e32 v62, v62, v63
	v_cndmask_b32_e32 v63, v64, v65, vcc
	ds_bpermute_b32 v65, v47, v62
	v_sqrt_f32_e32 v64, v63
	s_waitcnt lgkmcnt(0)
	v_add_f32_e32 v62, v62, v65
	v_add_u32_e32 v66, -1, v64
	v_add_u32_e32 v67, 1, v64
	v_fma_f32 v65, -v66, v64, v63
	ds_bpermute_b32 v71, v48, v62
	v_fma_f32 v70, -v67, v64, v63
	v_cmp_ge_f32_e64 s[0:1], 0, v65
	s_waitcnt lgkmcnt(0)
	v_add_f32_e32 v62, v62, v71
	v_cndmask_b32_e64 v64, v64, v66, s[0:1]
	v_cmp_lt_f32_e64 s[0:1], 0, v70
	ds_bpermute_b32 v66, v49, v62
	s_waitcnt lgkmcnt(0)
; __device__ __forceinline__ void p3_finalize(Frame& F) {
;     ...
;         const float ra = 1.0f / sqrtf(wave_sum(sa) * (1.0f / 1024.0f) + RMS_EPS), rb = 1.0f / sqrtf(wave_sum(sbq) * (1.0f / 1024.0f) + RMS_EPS);
;     ...
;         float am = 0.f;
; #pragma unroll
;         for (int q = 0; q < 2; ++q) {
;             const f32x4 ga0 = *(const f32x4*)(F.a_out_g + 16 * lane + 8 * q), ga1 = *(const f32x4*)(F.a_out_g + 16 * lane + 8 * q + 4);
;             const f32x4 gb0 = *(const f32x4*)(F.b_out_g + 16 * lane + 8 * q), gb1 = *(const f32x4*)(F.b_out_g + 16 * lane + 8 * q + 4);
; #pragma unroll
;             for (int e = 0; e < 4; ++e) { a[8 * q + e] *= ra * ga0[e]; a[8 * q + 4 + e] *= ra * ga1[e]; b[8 * q + e] *= rb * gb0[e]; b[8 * q + 4 + e] *= rb * gb1[e];
;                 am = fmaxf(am, fmaxf(fmaxf(fabsf(a[8 * q + e]), fabsf(a[8 * q + 4 + e])), fmaxf(fabsf(b[8 * q + e]), fabsf(b[8 * q + 4 + e])))); } }
; #pragma unroll
;         for (int o = 1; o < 64; o <<= 1) am = fmaxf(am, __shfl_xor(am, o));
;         const float qinv = am > 0.f ? 127.0f / am : 0.f;
;         v4u oa8, ob8;
; #pragma unroll
;         for (int q = 0; q < 4; ++q) { unsigned wa = 0, wb = 0;
; #pragma unroll
;             for (int e = 0; e < 4; ++e) { wa |= ((unsigned)(int)__builtin_rintf(a[4 * q + e] * qinv) & 0xffu) << (8 * e); wb |= ((unsigned)(int)__builtin_rintf(b[4 * q + e] * qinv) & 0xffu) << (8 * e); }
;             oa8[q] = wa; ob8[q] = wb; }
;         *(v4u*)(MIXQ + (size_t)t * DM + 16 * lane) = oa8; *(v4u*)(MIXQ + (size_t)t * DM + 1024 + 16 * lane) = ob8;
;         if (lane == 0) SA[t] = am > 0.f ? am * (1.0f / 127.0f) : 1.0f;
;     ...
;         v4u o[2], o2[2];
; #pragma unroll
;         for (int q = 0; q < 2; ++q) {
;             const f32x4 ga0 = gaq[2 * q], ga1 = gaq[2 * q + 1];
;             const f32x4 gb0 = gbq[2 * q], gb1 = gbq[2 * q + 1];
;             o[q].x = pk2(a[8 * q + 0] * ra * ga0[0], a[8 * q + 1] * ra * ga0[1]); o[q].y = pk2(a[8 * q + 2] * ra * ga0[2], a[8 * q + 3] * ra * ga0[3]);
;             o[q].z = pk2(a[8 * q + 4] * ra * ga1[0], a[8 * q + 5] * ra * ga1[1]); o[q].w = pk2(a[8 * q + 6] * ra * ga1[2], a[8 * q + 7] * ra * ga1[3]);
;             o2[q].x = pk2(b[8 * q + 0] * rb * gb0[0], b[8 * q + 1] * rb * gb0[1]); o2[q].y = pk2(b[8 * q + 2] * rb * gb0[2], b[8 * q + 3] * rb * gb0[3]);
	v_add_f32_e32 v62, v62, v66
	v_cndmask_b32_e64 v64, v64, v67, s[0:1]
	v_mul_f32_e32 v65, 0x37800000, v64
	v_cndmask_b32_e32 v64, v64, v65, vcc
	v_cmp_class_f32_e32 vcc, v63, v51
	v_fmamk_f32 v62, v62, 0x3a800000, v50
	s_nop 0
	v_cndmask_b32_e32 v63, v64, v63, vcc
	v_div_scale_f32 v64, s[0:1], v63, v63, 1.0
	v_rcp_f32_e32 v67, v64
	v_cmp_gt_f32_e32 vcc, s26, v62
	v_div_scale_f32 v65, s[0:1], 1.0, v63, 1.0
	v_fma_f32 v70, -v64, v67, 1.0
	v_fmac_f32_e32 v67, v70, v67
	v_mul_f32_e32 v70, 0x4f800000, v62
	v_cndmask_b32_e32 v62, v62, v70, vcc
	v_sqrt_f32_e32 v70, v62
	v_mul_f32_e32 v66, v65, v67
	v_fma_f32 v71, -v64, v66, v65
	v_fmac_f32_e32 v66, v71, v67
	v_fma_f32 v64, -v64, v66, v65
	v_add_u32_e32 v65, -1, v70
	v_add_u32_e32 v71, 1, v70
	v_fma_f32 v76, -v65, v70, v62
	v_fma_f32 v77, -v71, v70, v62
	v_cmp_ge_f32_e64 s[4:5], 0, v76
	s_nop 1
	v_cndmask_b32_e64 v65, v70, v65, s[4:5]
	v_cmp_lt_f32_e64 s[4:5], 0, v77
	s_nop 1
	v_cndmask_b32_e64 v65, v65, v71, s[4:5]
	v_mul_f32_e32 v70, 0x37800000, v65
	v_cndmask_b32_e32 v65, v65, v70, vcc
	v_cmp_class_f32_e32 vcc, v62, v51
	s_nop 1
	v_cndmask_b32_e32 v62, v65, v62, vcc
	v_div_scale_f32 v65, s[4:5], v62, v62, 1.0
	v_rcp_f32_e32 v71, v65
	v_div_scale_f32 v70, vcc, 1.0, v62, 1.0
	v_fma_f32 v76, -v65, v71, 1.0
	v_fmac_f32_e32 v71, v76, v71
	v_mul_f32_e32 v76, v70, v71
	v_fma_f32 v77, -v65, v76, v70
	v_fmac_f32_e32 v76, v77, v71
	v_fma_f32 v65, -v65, v76, v70
	v_div_fmas_f32 v65, v65, v71, v76
	s_mov_b64 vcc, s[0:1]
	v_div_fixup_f32 v62, v65, v62, 1.0
	v_div_fmas_f32 v64, v64, v67, v66
	v_mul_f32_e32 v52, v52, v62
	v_mul_f32_e32 v53, v53, v62
	v_mul_f32_e32 v60, v60, v62
	v_mul_f32_e32 v61, v61, v62
	v_mul_f32_e32 v54, v54, v62
	v_mul_f32_e32 v55, v55, v62
	v_mul_f32_e32 v36, v36, v62
	v_mul_f32_e32 v37, v37, v62
	v_mul_f32_e32 v56, v56, v62
	v_mul_f32_e32 v57, v57, v62
	v_mul_f32_e32 v38, v38, v62
	v_mul_f32_e32 v39, v39, v62
	v_mul_f32_e32 v58, v58, v62
	v_mul_f32_e32 v59, v59, v62
	v_mul_f32_e32 v40, v40, v62
	v_mul_f32_e32 v41, v41, v62
	v_div_fixup_f32 v62, v64, v63, 1.0
	v_mul_f32_e32 v52, v16, v52
	v_mul_f32_e32 v53, v17, v53
	v_mul_f32_e32 v60, v18, v60
	v_mul_f32_e32 v61, v19, v61
	v_mul_f32_e32 v54, v20, v54
	v_mul_f32_e32 v55, v21, v55
	v_mul_f32_e32 v64, v22, v36
	v_mul_f32_e32 v65, v23, v37
	v_mul_f32_e32 v66, v26, v38
	v_mul_f32_e32 v67, v27, v39
	v_mul_f32_e32 v58, v28, v58
	v_mul_f32_e32 v59, v29, v59
	v_mul_f32_e32 v40, v30, v40
	v_mul_f32_e32 v41, v31, v41
	v_mul_f32_e32 v70, v62, v112
	v_mul_f32_e32 v71, v62, v113
	v_mul_f32_e32 v76, v62, v78
	v_mul_f32_e32 v77, v62, v79
	v_mul_f32_e32 v78, v62, v110
	v_mul_f32_e32 v79, v62, v111
	v_mul_f32_e32 v72, v62, v72
	v_mul_f32_e32 v73, v62, v73
	v_mul_f32_e32 v80, v62, v108
	v_mul_f32_e32 v81, v62, v109
	v_mul_f32_e32 v74, v62, v74
	v_mul_f32_e32 v75, v62, v75
	v_mul_f32_e32 v82, v62, v106
	v_mul_f32_e32 v83, v62, v107
	v_mul_f32_e32 v63, v62, v69
	v_mul_f32_e32 v62, v62, v68
	v_mul_f32_e32 v56, v24, v56
	v_mul_f32_e32 v57, v25, v57
	v_cvt_pk_bf16_f32 v36, v52, v53
	v_cvt_pk_bf16_f32 v37, v60, v61
	v_cvt_pk_bf16_f32 v38, v54, v55
	v_cvt_pk_bf16_f32 v39, v64, v65
	v_cvt_pk_bf16_f32 v53, v66, v67
	v_cvt_pk_bf16_f32 v54, v58, v59
	v_cvt_pk_bf16_f32 v55, v40, v41
	v_mul_f32_e32 v40, v0, v70
	v_mul_f32_e32 v41, v1, v71
	v_mul_f32_e32 v58, v2, v76
	v_mul_f32_e32 v59, v3, v77
	v_mul_f32_e32 v60, v4, v78
	v_mul_f32_e32 v61, v5, v79
	v_mul_f32_e32 v64, v6, v72
	v_mul_f32_e32 v65, v7, v73
	v_mul_f32_e32 v66, v8, v80
	v_mul_f32_e32 v67, v9, v81
	v_mul_f32_e32 v68, v10, v74
	v_mul_f32_e32 v69, v11, v75
	v_mul_f32_e32 v70, v12, v82
	v_mul_f32_e32 v71, v13, v83
	v_mul_f32_e32 v72, v14, v62
	v_mul_f32_e32 v73, v15, v63
	v_cvt_pk_bf16_f32 v52, v56, v57
	v_cvt_pk_bf16_f32 v56, v40, v41
	v_cvt_pk_bf16_f32 v57, v58, v59
	v_cvt_pk_bf16_f32 v58, v60, v61
	v_cvt_pk_bf16_f32 v59, v64, v65
	v_cvt_pk_bf16_f32 v60, v66, v67
	v_cvt_pk_bf16_f32 v61, v68, v69
	v_cvt_pk_bf16_f32 v62, v70, v71
	v_cvt_pk_bf16_f32 v63, v72, v73
	global_store_dwordx4 v[42:43], v[36:39], off
	global_store_dwordx4 v[42:43], v[52:55], off offset:16
	global_store_dwordx4 v[42:43], v[56:59], off offset:2048
	global_store_dwordx4 v[42:43], v[60:63], off offset:2064
	s_cbranch_scc1 .LBB0_441

; #define LAS __attribute__((address_space(3)))
; __device__ __forceinline__ unsigned pk2(float lo, float hi) { const f32x2 v = {lo, hi}; return __builtin_bit_cast(unsigned, __builtin_convertvector(v, bf16x2_t)); }
;     __device__ __forceinline__ void fused(typename pg8::AccT<I8_>::type (&acc)[2][2][4][2], const pg8::Unit& u, int wr, int wc, int fr, int fq, LAS unsigned char* lds, int wid, int lane) const {
;     ...
;         asm volatile("s_waitcnt lgkmcnt(0)" ::: "memory"); __builtin_amdgcn_s_barrier(); asm volatile("" ::: "memory");
; #pragma unroll
;         for (int ai = 0; ai < 2; ++ai)
; #pragma unroll
;             for (int m = 0; m < 4; ++m) {
;                 const int r = 128 * ai + 64 * wr + 16 * m + fr;
;                 const float sc = rsl[r];
; #pragma unroll
;                 for (int bj = 0; bj < 2; ++bj) { f32x4 v0, v1;
;                     if constexpr (I8_) { const int cb = u.pn * 256 + 128 * bj + 32 * wc + 8 * fq; const f32x4 w0 = *(const f32x4*)(sw + cb), w1 = *(const f32x4*)(sw + cb + 4);
;                         const pg8::i32x4 a0 = acc[ai][bj][m][0], a1 = acc[ai][bj][m][1];
;                         v0 = (f32x4){(float)a0[0], (float)a0[1], (float)a0[2], (float)a0[3]} * w0 * sc; v1 = (f32x4){(float)a1[0], (float)a1[1], (float)a1[2], (float)a1[3]} * w1 * sc; }
;                     else { v0 = acc[ai][bj][m][0] * sc; v1 = acc[ai][bj][m][1] * sc; }
;                     v4u w; w.x = pk2(v0[0], v0[1]); w.y = pk2(v0[2], v0[3]); w.z = pk2(v1[0], v1[1]); w.w = pk2(v1[2], v1[3]);
;                     const int c = 16 * bj + 4 * wc + fq;
;                     *(LAS v4u*)(lds + r * 512 + ((c ^ (r & 15)) << 4)) = w; } }
.LBB0_587:
	s_or_b64 exec, exec, s[2:3]
	s_lshl_b32 s0, s17, 8
	v_ashrrev_i32_e32 v173, 4, v169
	s_or_b32 s0, s0, s34
	v_lshl_add_u32 v132, v173, 3, s0
	v_ashrrev_i32_e32 v133, 31, v132
	v_lshl_add_u64 v[128:129], v[132:133], 2, s[10:11]
	v_add_u32_e32 v132, 0x80, v132
	s_waitcnt lgkmcnt(0)
	s_barrier
	v_ashrrev_i32_e32 v133, 31, v132
	global_load_dwordx4 v[136:139], v[128:129], off
	s_nop 0
	global_load_dwordx4 v[128:131], v[128:129], off offset:16
	v_lshl_add_u64 v[132:133], v[132:133], 2, s[10:11]
	global_load_dwordx4 v[140:143], v[132:133], off
	s_nop 0
	global_load_dwordx4 v[132:135], v[132:133], off offset:16
	s_add_i32 s0, 0, 0x22800
	v_or_b32_e32 v174, 16, v171
	v_cvt_f32_i32_e32 v177, v103
	v_lshl_add_u32 v103, v171, 2, s0
	v_cvt_f32_i32_e32 v125, v125
	v_cvt_f32_i32_e32 v124, v124
	v_cvt_f32_i32_e32 v127, v127
	v_cvt_f32_i32_e32 v126, v126
	v_cvt_f32_i32_e32 v121, v121
	v_cvt_f32_i32_e32 v120, v120
	v_cvt_f32_i32_e32 v123, v123
	v_cvt_f32_i32_e32 v122, v122
	v_cvt_f32_i32_e32 v175, v101
	v_add_u32_e32 v101, s26, v173
	v_lshl_add_u32 v173, v174, 2, s0
	v_lshl_add_u32 v178, v174, 9, 0
	ds_read_b32 v174, v103
	v_cvt_f32_i32_e32 v117, v117
	v_cvt_f32_i32_e32 v116, v116
	v_cvt_f32_i32_e32 v119, v119
	v_cvt_f32_i32_e32 v118, v118
	v_cvt_f32_i32_e32 v113, v113
	v_cvt_f32_i32_e32 v112, v112
	v_cvt_f32_i32_e32 v115, v115
	v_cvt_f32_i32_e32 v114, v114
	v_cvt_f32_i32_e32 v155, v105
	v_cvt_f32_i32_e32 v154, v104
	v_cvt_f32_i32_e32 v157, v107
	v_cvt_f32_i32_e32 v156, v106
	v_cvt_f32_i32_e32 v176, v102
	v_xor_b32_e32 v102, v101, v170
	v_add_u32_e32 v101, 16, v101
	v_lshl_add_u32 v148, v171, 9, 0
	v_lshlrev_b32_e32 v102, 4, v102
	v_xor_b32_e32 v101, v101, v170
	v_add_u32_e32 v179, v148, v102
	v_lshlrev_b32_e32 v101, 4, v101
	v_add_u32_e32 v180, v148, v101
	v_cvt_f32_i32_e32 v109, v109
	v_cvt_f32_i32_e32 v108, v108
	v_cvt_f32_i32_e32 v111, v111
	v_cvt_f32_i32_e32 v110, v110
	v_cvt_f32_i32_e32 v97, v97
	v_cvt_f32_i32_e32 v99, v99
	v_cvt_f32_i32_e32 v98, v98
	v_cvt_f32_i32_e32 v96, v96
	v_cvt_f32_i32_e32 v93, v93
	v_cvt_f32_i32_e32 v95, v95
	v_cvt_f32_i32_e32 v94, v94
	v_cvt_f32_i32_e32 v92, v92
	v_cvt_f32_i32_e32 v89, v89
	v_cvt_f32_i32_e32 v91, v91
	v_cvt_f32_i32_e32 v90, v90
	v_cvt_f32_i32_e32 v88, v88
	v_cvt_f32_i32_e32 v85, v85
	v_cvt_f32_i32_e32 v87, v87
	v_cvt_f32_i32_e32 v86, v86
	v_cvt_f32_i32_e32 v84, v84
	v_cvt_f32_i32_e32 v81, v81
	v_cvt_f32_i32_e32 v83, v83
	v_cvt_f32_i32_e32 v82, v82
	v_cvt_f32_i32_e32 v80, v80
	v_cvt_f32_i32_e32 v77, v77
	v_cvt_f32_i32_e32 v79, v79
	v_cvt_f32_i32_e32 v78, v78
	v_cvt_f32_i32_e32 v76, v76
	v_cvt_f32_i32_e32 v73, v73
	v_cvt_f32_i32_e32 v75, v75
	v_cvt_f32_i32_e32 v74, v74
	v_cvt_f32_i32_e32 v72, v72
	v_cvt_f32_i32_e32 v69, v69
	v_cvt_f32_i32_e32 v71, v71
	v_cvt_f32_i32_e32 v70, v70
	v_cvt_f32_i32_e32 v68, v68
	v_cvt_f32_i32_e32 v65, v65
	v_cvt_f32_i32_e32 v67, v67
	s_waitcnt vmcnt(0)
	v_mul_f32_e32 v104, v138, v126
	v_mul_f32_e32 v105, v139, v127
	v_mul_f32_e32 v106, v136, v124
	v_mul_f32_e32 v107, v137, v125
	v_mul_f32_e32 v122, v130, v122
	v_mul_f32_e32 v123, v131, v123
	v_mul_f32_e32 v120, v128, v120
	v_mul_f32_e32 v121, v129, v121
	s_waitcnt lgkmcnt(0)
	v_mul_f32_e32 v124, v174, v104
	v_mul_f32_e32 v125, v174, v105
	v_mul_f32_e32 v104, v174, v106
	v_mul_f32_e32 v105, v174, v107
	v_mul_f32_e32 v122, v174, v122
	v_mul_f32_e32 v123, v174, v123
	v_mul_f32_e32 v106, v174, v120
	v_mul_f32_e32 v107, v174, v121
	v_mul_f32_e32 v118, v142, v118
	v_mul_f32_e32 v119, v143, v119
	v_mul_f32_e32 v116, v140, v116
	v_mul_f32_e32 v117, v141, v117
	v_mul_f32_e32 v114, v134, v114
	v_mul_f32_e32 v115, v135, v115
	v_mul_f32_e32 v112, v132, v112
	v_mul_f32_e32 v113, v133, v113
	v_cvt_pk_bf16_f32 v104, v104, v105
	v_cvt_pk_bf16_f32 v105, v124, v125
	v_cvt_pk_bf16_f32 v106, v106, v107
	v_cvt_pk_bf16_f32 v107, v122, v123
	v_mul_f32_e32 v118, v174, v118
	v_mul_f32_e32 v119, v174, v119
	v_mul_f32_e32 v116, v174, v116
	v_mul_f32_e32 v117, v174, v117
	v_mul_f32_e32 v114, v174, v114
	v_mul_f32_e32 v115, v174, v115
	v_mul_f32_e32 v112, v174, v112
	v_mul_f32_e32 v113, v174, v113
	ds_write_b128 v179, v[104:107]
	v_cvt_pk_bf16_f32 v104, v116, v117
	v_cvt_pk_bf16_f32 v105, v118, v119
	v_cvt_pk_bf16_f32 v106, v112, v113
	v_cvt_pk_bf16_f32 v107, v114, v115
	ds_write_b128 v180, v[104:107]
	ds_read_b32 v112, v173
	v_cvt_f32_i32_e32 v174, v100
	v_mul_f32_e32 v104, v138, v110
	v_mul_f32_e32 v105, v139, v111
	v_mul_f32_e32 v106, v136, v108
	v_mul_f32_e32 v107, v137, v109
	v_mul_f32_e32 v108, v130, v156
	v_mul_f32_e32 v109, v131, v157
	v_mul_f32_e32 v110, v128, v154
	v_mul_f32_e32 v111, v129, v155
	s_waitcnt lgkmcnt(0)
	v_mul_f32_e32 v114, v104, v112
	v_mul_f32_e32 v115, v105, v112
	v_mul_f32_e32 v104, v106, v112
	v_mul_f32_e32 v105, v107, v112
	v_mul_f32_e32 v108, v108, v112
	v_mul_f32_e32 v109, v109, v112
	v_mul_f32_e32 v106, v110, v112
	v_mul_f32_e32 v107, v111, v112
	v_cvt_pk_bf16_f32 v104, v104, v105
	v_cvt_pk_bf16_f32 v105, v114, v115
	v_cvt_pk_bf16_f32 v106, v106, v107
	v_cvt_pk_bf16_f32 v107, v108, v109
	v_add_u32_e32 v100, v178, v102
	ds_write_b128 v100, v[104:107]
	v_mul_f32_e32 v104, v142, v176
	v_mul_f32_e32 v105, v143, v177
	v_mul_f32_e32 v106, v140, v174
	v_mul_f32_e32 v107, v141, v175
	v_mul_f32_e32 v98, v134, v98
	v_mul_f32_e32 v99, v135, v99
	v_mul_f32_e32 v96, v132, v96
	v_mul_f32_e32 v97, v133, v97
	v_mul_f32_e32 v104, v104, v112
	v_mul_f32_e32 v105, v105, v112
	v_mul_f32_e32 v106, v106, v112
	v_mul_f32_e32 v107, v107, v112
	v_mul_f32_e32 v108, v98, v112
	v_mul_f32_e32 v109, v99, v112
	v_mul_f32_e32 v98, v96, v112
	v_mul_f32_e32 v99, v97, v112
	v_cvt_pk_bf16_f32 v96, v106, v107
	v_cvt_pk_bf16_f32 v97, v104, v105
	v_cvt_pk_bf16_f32 v98, v98, v99
	v_cvt_pk_bf16_f32 v99, v108, v109
	v_add_u32_e32 v100, v178, v101
	ds_write_b128 v100, v[96:99]
	v_or_b32_e32 v97, 32, v171
	v_lshl_add_u32 v96, v97, 2, s0
	ds_read_b32 v96, v96
	v_lshl_add_u32 v97, v97, 9, 0
	v_mul_f32_e32 v94, v138, v94
	v_mul_f32_e32 v95, v139, v95
	v_mul_f32_e32 v92, v136, v92
	v_mul_f32_e32 v93, v137, v93
	v_mul_f32_e32 v90, v130, v90
	v_mul_f32_e32 v91, v131, v91
	v_mul_f32_e32 v88, v128, v88
	v_mul_f32_e32 v89, v129, v89
	s_waitcnt lgkmcnt(0)
; #define LAS __attribute__((address_space(3)))
; __device__ __forceinline__ unsigned pk2(float lo, float hi) { const f32x2 v = {lo, hi}; return __builtin_bit_cast(unsigned, __builtin_convertvector(v, bf16x2_t)); }
;     __device__ __forceinline__ void fused(typename pg8::AccT<I8_>::type (&acc)[2][2][4][2], const pg8::Unit& u, int wr, int wc, int fr, int fq, LAS unsigned char* lds, int wid, int lane) const {
;     ...
; #pragma unroll
;         for (int ai = 0; ai < 2; ++ai)
; #pragma unroll
;             for (int m = 0; m < 4; ++m) {
;                 const int r = 128 * ai + 64 * wr + 16 * m + fr;
;                 const float sc = rsl[r];
; #pragma unroll
;                 for (int bj = 0; bj < 2; ++bj) { f32x4 v0, v1;
;                     if constexpr (I8_) { const int cb = u.pn * 256 + 128 * bj + 32 * wc + 8 * fq; const f32x4 w0 = *(const f32x4*)(sw + cb), w1 = *(const f32x4*)(sw + cb + 4);
;                         const pg8::i32x4 a0 = acc[ai][bj][m][0], a1 = acc[ai][bj][m][1];
;                         v0 = (f32x4){(float)a0[0], (float)a0[1], (float)a0[2], (float)a0[3]} * w0 * sc; v1 = (f32x4){(float)a1[0], (float)a1[1], (float)a1[2], (float)a1[3]} * w1 * sc; }
;                     else { v0 = acc[ai][bj][m][0] * sc; v1 = acc[ai][bj][m][1] * sc; }
;                     v4u w; w.x = pk2(v0[0], v0[1]); w.y = pk2(v0[2], v0[3]); w.z = pk2(v1[0], v1[1]); w.w = pk2(v1[2], v1[3]);
;                     const int c = 16 * bj + 4 * wc + fq;
;                     *(LAS v4u*)(lds + r * 512 + ((c ^ (r & 15)) << 4)) = w; } }
	v_mul_f32_e32 v94, v94, v96
	v_mul_f32_e32 v95, v95, v96
	v_mul_f32_e32 v92, v92, v96
	v_mul_f32_e32 v93, v93, v96
	v_mul_f32_e32 v98, v90, v96
	v_mul_f32_e32 v99, v91, v96
	v_mul_f32_e32 v90, v88, v96
	v_mul_f32_e32 v91, v89, v96
	v_cvt_pk_bf16_f32 v88, v92, v93
	v_cvt_pk_bf16_f32 v89, v94, v95
	v_cvt_pk_bf16_f32 v90, v90, v91
	v_cvt_pk_bf16_f32 v91, v98, v99
	v_add_u32_e32 v92, v97, v102
	v_mul_f32_e32 v86, v142, v86
	v_mul_f32_e32 v87, v143, v87
	v_mul_f32_e32 v84, v140, v84
	v_mul_f32_e32 v85, v141, v85
	v_mul_f32_e32 v82, v134, v82
	v_mul_f32_e32 v83, v135, v83
	v_mul_f32_e32 v80, v132, v80
	v_mul_f32_e32 v81, v133, v81
	ds_write_b128 v92, v[88:91]
	v_mul_f32_e32 v86, v86, v96
	v_mul_f32_e32 v87, v87, v96
	v_mul_f32_e32 v84, v84, v96
	v_mul_f32_e32 v85, v85, v96
	v_mul_f32_e32 v88, v82, v96
	v_mul_f32_e32 v89, v83, v96
	v_mul_f32_e32 v82, v80, v96
	v_mul_f32_e32 v83, v81, v96
	v_cvt_pk_bf16_f32 v80, v84, v85
	v_cvt_pk_bf16_f32 v81, v86, v87
	v_cvt_pk_bf16_f32 v82, v82, v83
	v_cvt_pk_bf16_f32 v83, v88, v89
	v_add_u32_e32 v84, v97, v101
	ds_write_b128 v84, v[80:83]
	v_or_b32_e32 v81, 48, v171
	v_lshl_add_u32 v80, v81, 2, s0
	ds_read_b32 v80, v80
	v_cvt_f32_i32_e32 v66, v66
	v_cvt_f32_i32_e32 v64, v64
	v_lshl_add_u32 v81, v81, 9, 0
	v_mul_f32_e32 v78, v138, v78
	v_mul_f32_e32 v79, v139, v79
	v_mul_f32_e32 v76, v136, v76
	v_mul_f32_e32 v77, v137, v77
	v_mul_f32_e32 v74, v130, v74
	v_mul_f32_e32 v75, v131, v75
	v_mul_f32_e32 v72, v128, v72
	v_mul_f32_e32 v73, v129, v73
	s_waitcnt lgkmcnt(0)
	v_mul_f32_e32 v78, v78, v80
	v_mul_f32_e32 v79, v79, v80
	v_mul_f32_e32 v76, v76, v80
	v_mul_f32_e32 v77, v77, v80
	v_mul_f32_e32 v82, v74, v80
	v_mul_f32_e32 v83, v75, v80
	v_mul_f32_e32 v74, v72, v80
	v_mul_f32_e32 v75, v73, v80
	v_cvt_pk_bf16_f32 v72, v76, v77
	v_cvt_pk_bf16_f32 v73, v78, v79
	v_cvt_pk_bf16_f32 v74, v74, v75
	v_cvt_pk_bf16_f32 v75, v82, v83
	v_add_u32_e32 v76, v81, v102
	v_mul_f32_e32 v70, v142, v70
	v_mul_f32_e32 v71, v143, v71
	v_mul_f32_e32 v68, v140, v68
	v_mul_f32_e32 v69, v141, v69
	v_mul_f32_e32 v66, v134, v66
	v_mul_f32_e32 v67, v135, v67
	v_mul_f32_e32 v64, v132, v64
	v_mul_f32_e32 v65, v133, v65
	ds_write_b128 v76, v[72:75]
	v_mul_f32_e32 v70, v70, v80
	v_mul_f32_e32 v71, v71, v80
	v_mul_f32_e32 v68, v68, v80
	v_mul_f32_e32 v69, v69, v80
	v_mul_f32_e32 v72, v66, v80
	v_mul_f32_e32 v73, v67, v80
	v_mul_f32_e32 v66, v64, v80
	v_mul_f32_e32 v67, v65, v80
	v_cvt_pk_bf16_f32 v64, v68, v69
	v_cvt_pk_bf16_f32 v65, v70, v71
	v_cvt_pk_bf16_f32 v66, v66, v67
	v_cvt_pk_bf16_f32 v67, v72, v73
	v_add_u32_e32 v68, v81, v101
	ds_write_b128 v68, v[64:67]
	v_cvt_f32_i32_e32 v61, v61
	v_cvt_f32_i32_e32 v63, v63
	v_cvt_f32_i32_e32 v62, v62
	v_cvt_f32_i32_e32 v60, v60
	ds_read_b32 v64, v103 offset:512
	v_cvt_f32_i32_e32 v57, v57
	v_cvt_f32_i32_e32 v59, v59
	v_cvt_f32_i32_e32 v58, v58
	v_cvt_f32_i32_e32 v56, v56
	v_cvt_f32_i32_e32 v53, v53
	v_cvt_f32_i32_e32 v55, v55
	v_cvt_f32_i32_e32 v54, v54
	v_cvt_f32_i32_e32 v52, v52
	v_cvt_f32_i32_e32 v45, v45
	v_cvt_f32_i32_e32 v47, v47
	v_cvt_f32_i32_e32 v46, v46
	v_cvt_f32_i32_e32 v44, v44
	v_add_u32_e32 v65, 0x10000, v148
	v_mul_f32_e32 v62, v138, v62
	v_mul_f32_e32 v63, v139, v63
	v_mul_f32_e32 v60, v136, v60
	v_mul_f32_e32 v61, v137, v61
	v_mul_f32_e32 v58, v130, v58
	v_mul_f32_e32 v59, v131, v59
	v_mul_f32_e32 v56, v128, v56
	v_mul_f32_e32 v57, v129, v57
	s_waitcnt lgkmcnt(0)
	v_mul_f32_e32 v62, v62, v64
	v_mul_f32_e32 v63, v63, v64
	v_mul_f32_e32 v60, v60, v64
	v_mul_f32_e32 v61, v61, v64
	v_mul_f32_e32 v66, v58, v64
	v_mul_f32_e32 v67, v59, v64
	v_mul_f32_e32 v58, v56, v64
	v_mul_f32_e32 v59, v57, v64
	v_cvt_pk_bf16_f32 v56, v60, v61
	v_cvt_pk_bf16_f32 v57, v62, v63
	v_cvt_pk_bf16_f32 v58, v58, v59
	v_cvt_pk_bf16_f32 v59, v66, v67
	v_add_u32_e32 v60, v65, v102
	v_mul_f32_e32 v54, v142, v54
	v_mul_f32_e32 v55, v143, v55
	v_mul_f32_e32 v52, v140, v52
	v_mul_f32_e32 v53, v141, v53
	v_mul_f32_e32 v46, v134, v46
	v_mul_f32_e32 v47, v135, v47
	v_mul_f32_e32 v44, v132, v44
	v_mul_f32_e32 v45, v133, v45
	ds_write_b128 v60, v[56:59]
	v_mul_f32_e32 v54, v54, v64
	v_mul_f32_e32 v55, v55, v64
	v_mul_f32_e32 v52, v52, v64
	v_mul_f32_e32 v53, v53, v64
	v_mul_f32_e32 v56, v46, v64
	v_mul_f32_e32 v57, v47, v64
	v_mul_f32_e32 v46, v44, v64
	v_mul_f32_e32 v47, v45, v64
	v_cvt_pk_bf16_f32 v44, v52, v53
	v_cvt_pk_bf16_f32 v45, v54, v55
	v_cvt_pk_bf16_f32 v46, v46, v47
	v_cvt_pk_bf16_f32 v47, v56, v57
	v_add_u32_e32 v52, v65, v101
	ds_write_b128 v52, v[44:47]
	v_cvt_f32_i32_e32 v45, v49
	v_cvt_f32_i32_e32 v47, v51
	v_cvt_f32_i32_e32 v46, v50
	v_cvt_f32_i32_e32 v44, v48
	ds_read_b32 v48, v103 offset:576
	v_cvt_f32_i32_e32 v41, v41
	v_cvt_f32_i32_e32 v43, v43
	v_cvt_f32_i32_e32 v42, v42
	v_cvt_f32_i32_e32 v40, v40
	v_cvt_f32_i32_e32 v37, v37
	v_cvt_f32_i32_e32 v39, v39
	v_cvt_f32_i32_e32 v38, v38
	v_cvt_f32_i32_e32 v36, v36
	v_cvt_f32_i32_e32 v29, v29
	v_cvt_f32_i32_e32 v31, v31
	v_cvt_f32_i32_e32 v30, v30
	v_cvt_f32_i32_e32 v28, v28
	v_add_u32_e32 v49, 0x12000, v148
	v_mul_f32_e32 v46, v138, v46
	v_mul_f32_e32 v47, v139, v47
	v_mul_f32_e32 v44, v136, v44
	v_mul_f32_e32 v45, v137, v45
	v_mul_f32_e32 v42, v130, v42
	v_mul_f32_e32 v43, v131, v43
	v_mul_f32_e32 v40, v128, v40
	v_mul_f32_e32 v41, v129, v41
	s_waitcnt lgkmcnt(0)
; #define LAS __attribute__((address_space(3)))
; __device__ __forceinline__ unsigned pk2(float lo, float hi) { const f32x2 v = {lo, hi}; return __builtin_bit_cast(unsigned, __builtin_convertvector(v, bf16x2_t)); }
;     __device__ __forceinline__ void fused(typename pg8::AccT<I8_>::type (&acc)[2][2][4][2], const pg8::Unit& u, int wr, int wc, int fr, int fq, LAS unsigned char* lds, int wid, int lane) const {
;     ...
;                 for (int bj = 0; bj < 2; ++bj) { f32x4 v0, v1;
;                     if constexpr (I8_) { const int cb = u.pn * 256 + 128 * bj + 32 * wc + 8 * fq; const f32x4 w0 = *(const f32x4*)(sw + cb), w1 = *(const f32x4*)(sw + cb + 4);
;                         const pg8::i32x4 a0 = acc[ai][bj][m][0], a1 = acc[ai][bj][m][1];
;                         v0 = (f32x4){(float)a0[0], (float)a0[1], (float)a0[2], (float)a0[3]} * w0 * sc; v1 = (f32x4){(float)a1[0], (float)a1[1], (float)a1[2], (float)a1[3]} * w1 * sc; }
;                     else { v0 = acc[ai][bj][m][0] * sc; v1 = acc[ai][bj][m][1] * sc; }
;                     v4u w; w.x = pk2(v0[0], v0[1]); w.y = pk2(v0[2], v0[3]); w.z = pk2(v1[0], v1[1]); w.w = pk2(v1[2], v1[3]);
;                     const int c = 16 * bj + 4 * wc + fq;
;                     *(LAS v4u*)(lds + r * 512 + ((c ^ (r & 15)) << 4)) = w; } }
;         asm volatile("s_waitcnt lgkmcnt(0)" ::: "memory"); __builtin_amdgcn_s_barrier(); asm volatile("" ::: "memory");
;         const int ql = lane & 31, rowl = 32 * wid + ql;
;         p6_task<true>(ws, lane, u.pn, u.pm * 256 + rowl, nullptr, lds + rowl * 512, rowl & 15, lds + 131072 + 1024 + wid * 1024 + ql * 32);
	v_mul_f32_e32 v46, v46, v48
	v_mul_f32_e32 v47, v47, v48
	v_mul_f32_e32 v44, v44, v48
	v_mul_f32_e32 v45, v45, v48
	v_mul_f32_e32 v50, v42, v48
	v_mul_f32_e32 v51, v43, v48
	v_mul_f32_e32 v42, v40, v48
	v_mul_f32_e32 v43, v41, v48
	v_cvt_pk_bf16_f32 v40, v44, v45
	v_cvt_pk_bf16_f32 v41, v46, v47
	v_cvt_pk_bf16_f32 v42, v42, v43
	v_cvt_pk_bf16_f32 v43, v50, v51
	v_add_u32_e32 v44, v49, v102
	v_mul_f32_e32 v38, v142, v38
	v_mul_f32_e32 v39, v143, v39
	v_mul_f32_e32 v36, v140, v36
	v_mul_f32_e32 v37, v141, v37
	v_mul_f32_e32 v30, v134, v30
	v_mul_f32_e32 v31, v135, v31
	v_mul_f32_e32 v28, v132, v28
	v_mul_f32_e32 v29, v133, v29
	ds_write_b128 v44, v[40:43]
	v_mul_f32_e32 v38, v38, v48
	v_mul_f32_e32 v39, v39, v48
	v_mul_f32_e32 v36, v36, v48
	v_mul_f32_e32 v37, v37, v48
	v_mul_f32_e32 v40, v30, v48
	v_mul_f32_e32 v41, v31, v48
	v_mul_f32_e32 v30, v28, v48
	v_mul_f32_e32 v31, v29, v48
	v_cvt_pk_bf16_f32 v28, v36, v37
	v_cvt_pk_bf16_f32 v29, v38, v39
	v_cvt_pk_bf16_f32 v30, v30, v31
	v_cvt_pk_bf16_f32 v31, v40, v41
	v_add_u32_e32 v36, v49, v101
	ds_write_b128 v36, v[28:31]
	v_cvt_f32_i32_e32 v29, v33
	v_cvt_f32_i32_e32 v31, v35
	v_cvt_f32_i32_e32 v30, v34
	v_cvt_f32_i32_e32 v28, v32
	ds_read_b32 v32, v103 offset:640
	v_cvt_f32_i32_e32 v25, v25
	v_cvt_f32_i32_e32 v27, v27
	v_cvt_f32_i32_e32 v26, v26
	v_cvt_f32_i32_e32 v24, v24
	v_cvt_f32_i32_e32 v21, v21
	v_cvt_f32_i32_e32 v23, v23
	v_cvt_f32_i32_e32 v22, v22
	v_cvt_f32_i32_e32 v20, v20
	v_cvt_f32_i32_e32 v13, v13
	v_cvt_f32_i32_e32 v15, v15
	v_cvt_f32_i32_e32 v14, v14
	v_cvt_f32_i32_e32 v12, v12
	v_add_u32_e32 v33, 0x14000, v148
	v_mul_f32_e32 v30, v138, v30
	v_mul_f32_e32 v31, v139, v31
	v_mul_f32_e32 v28, v136, v28
	v_mul_f32_e32 v29, v137, v29
	v_mul_f32_e32 v26, v130, v26
	v_mul_f32_e32 v27, v131, v27
	v_mul_f32_e32 v24, v128, v24
	v_mul_f32_e32 v25, v129, v25
	s_waitcnt lgkmcnt(0)
	v_mul_f32_e32 v30, v30, v32
	v_mul_f32_e32 v31, v31, v32
	v_mul_f32_e32 v28, v28, v32
	v_mul_f32_e32 v29, v29, v32
	v_mul_f32_e32 v34, v26, v32
	v_mul_f32_e32 v35, v27, v32
	v_mul_f32_e32 v26, v24, v32
	v_mul_f32_e32 v27, v25, v32
	v_cvt_pk_bf16_f32 v24, v28, v29
	v_cvt_pk_bf16_f32 v25, v30, v31
	v_cvt_pk_bf16_f32 v26, v26, v27
	v_cvt_pk_bf16_f32 v27, v34, v35
	v_add_u32_e32 v28, v33, v102
	v_mul_f32_e32 v22, v142, v22
	v_mul_f32_e32 v23, v143, v23
	v_mul_f32_e32 v20, v140, v20
	v_mul_f32_e32 v21, v141, v21
	v_mul_f32_e32 v14, v134, v14
	v_mul_f32_e32 v15, v135, v15
	v_mul_f32_e32 v12, v132, v12
	v_mul_f32_e32 v13, v133, v13
	ds_write_b128 v28, v[24:27]
	v_mul_f32_e32 v22, v22, v32
	v_mul_f32_e32 v23, v23, v32
	v_mul_f32_e32 v20, v20, v32
	v_mul_f32_e32 v21, v21, v32
	v_mul_f32_e32 v24, v14, v32
	v_mul_f32_e32 v25, v15, v32
	v_mul_f32_e32 v14, v12, v32
	v_mul_f32_e32 v15, v13, v32
	v_cvt_pk_bf16_f32 v12, v20, v21
	v_cvt_pk_bf16_f32 v13, v22, v23
	v_cvt_pk_bf16_f32 v14, v14, v15
	v_cvt_pk_bf16_f32 v15, v24, v25
	v_add_u32_e32 v20, v33, v101
	ds_write_b128 v20, v[12:15]
	v_cvt_f32_i32_e32 v13, v17
	v_cvt_f32_i32_e32 v15, v19
	v_cvt_f32_i32_e32 v14, v18
	v_cvt_f32_i32_e32 v12, v16
	ds_read_b32 v16, v103 offset:704
	v_cvt_f32_i32_e32 v9, v9
	v_cvt_f32_i32_e32 v11, v11
	v_cvt_f32_i32_e32 v10, v10
	v_cvt_f32_i32_e32 v8, v8
	v_cvt_f32_i32_e32 v5, v5
	v_cvt_f32_i32_e32 v7, v7
	v_cvt_f32_i32_e32 v6, v6
	v_cvt_f32_i32_e32 v4, v4
	v_cvt_f32_i32_e32 v1, v1
	v_cvt_f32_i32_e32 v3, v3
	v_cvt_f32_i32_e32 v2, v2
	v_cvt_f32_i32_e32 v0, v0
	v_add_u32_e32 v17, 0x16000, v148
	v_mul_f32_e32 v14, v138, v14
	v_mul_f32_e32 v15, v139, v15
	v_mul_f32_e32 v12, v136, v12
	v_mul_f32_e32 v13, v137, v13
	v_mul_f32_e32 v10, v130, v10
	v_mul_f32_e32 v11, v131, v11
	v_mul_f32_e32 v8, v128, v8
	v_mul_f32_e32 v9, v129, v9
	s_waitcnt lgkmcnt(0)
	v_mul_f32_e32 v14, v14, v16
	v_mul_f32_e32 v15, v15, v16
	v_mul_f32_e32 v12, v12, v16
	v_mul_f32_e32 v13, v13, v16
	v_mul_f32_e32 v18, v10, v16
	v_mul_f32_e32 v19, v11, v16
	v_mul_f32_e32 v10, v8, v16
	v_mul_f32_e32 v11, v9, v16
	v_cvt_pk_bf16_f32 v8, v12, v13
	v_cvt_pk_bf16_f32 v9, v14, v15
	v_cvt_pk_bf16_f32 v10, v10, v11
	v_cvt_pk_bf16_f32 v11, v18, v19
	v_add_u32_e32 v12, v17, v102
	v_mul_f32_e32 v6, v142, v6
	v_mul_f32_e32 v7, v143, v7
	v_mul_f32_e32 v4, v140, v4
	v_mul_f32_e32 v5, v141, v5
	v_mul_f32_e32 v2, v134, v2
	v_mul_f32_e32 v3, v135, v3
	v_mul_f32_e32 v0, v132, v0
	v_mul_f32_e32 v1, v133, v1
	s_lshl_b32 s0, s17, 1
	ds_write_b128 v12, v[8:11]
	v_mul_f32_e32 v6, v6, v16
	v_mul_f32_e32 v7, v7, v16
	v_mul_f32_e32 v4, v4, v16
	v_mul_f32_e32 v5, v5, v16
	v_mul_f32_e32 v8, v2, v16
	v_mul_f32_e32 v9, v3, v16
	v_mul_f32_e32 v2, v0, v16
	v_mul_f32_e32 v3, v1, v16
	s_ashr_i32 s1, s0, 31
	v_cvt_pk_bf16_f32 v0, v4, v5
	v_cvt_pk_bf16_f32 v1, v6, v7
	v_cvt_pk_bf16_f32 v2, v2, v3
	v_cvt_pk_bf16_f32 v3, v8, v9
	v_add_u32_e32 v4, v17, v101
	v_ashrrev_i32_e32 v84, 5, v169
	s_lshl_b64 s[2:3], s[0:1], 15
	ds_write_b128 v4, v[0:3]
	s_add_u32 s4, s6, s2
	v_lshlrev_b32_e32 v0, 8, v169
	v_lshlrev_b32_e32 v80, 3, v84
	s_addc_u32 s5, s7, s3
	v_and_b32_e32 v148, 0x1f00, v0
	v_ashrrev_i32_e32 v81, 31, v80
	v_lshl_add_u64 v[0:1], s[4:5], 0, v[148:149]
	v_lshlrev_b64 v[56:57], 1, v[80:81]
	s_waitcnt lgkmcnt(0)
	s_barrier
; #define LAS __attribute__((address_space(3)))
; #define P6_LOADKF(BUF, STEP) do { const bf16* skb_ = SK + (size_t)(h * 2 + ((STEP) >> 2)) * 128 * 128 + (size_t)ql * 128 + 8 * hh + (size_t)((STEP) & 3) * 32 * 128; \
;             _Pragma("unroll") for (int ks_ = 0; ks_ < 8; ++ks_) kfa[BUF][ks_] = *(const bf16x8*)(skb_ + 16 * ks_); } while (0)
; template <bool FROM_LDS>
; __device__ __forceinline__ void p6_task(unsigned char* ws, int lane, int h, int tok, const bf16* qrow_g, const LAS unsigned char* qrow_l, int rsw, LAS unsigned char* scr) {
;     ...
;         P6_LOADKF(0, 0);
; #pragma unroll
;         for (int p = 0; p < 2; ++p) {
;             bf16x8 qf[8];
; #pragma unroll
;             for (int ks = 0; ks < 8; ++ks) qf[ks] = FROM_LDS ? *(const LAS bf16x8*)(qrow_l + (((16 * p + 2 * ks + hh) ^ rsw) << 4)) : *(const bf16x8*)(qrow_g + p * 128 + 8 * hh + 16 * ks);
;             int g0[16], g1[16];
; #pragma unroll
;             for (int kt = 0; kt < 4; ++kt) { f32x16 s = (f32x16){};
;                 const int step = 4 * p + kt;
; #pragma unroll
;                 for (int ks = 0; ks < 8; ++ks) s = __builtin_amdgcn_mfma_f32_32x32x16_bf16(kfa[0][ks], qf[ks], s, 0, 0, 0);
;                 __builtin_amdgcn_sched_barrier(0);
;                 if (step + 1 < 8) { P6_LOADKF(0, step + 1); }
;                 __builtin_amdgcn_sched_barrier(0);
;                 int g[16];
; #pragma unroll
;                 for (int reg = 0; reg < 16; ++reg) { const int n = 32 * kt + (reg & 3) + 8 * (reg >> 2) + 4 * hh; g[reg] = (f2key(s[reg]) & ~127) | n; }
;                 p6_sort16(g);
	v_lshl_add_u64 v[58:59], v[0:1], 0, v[56:57]
	global_load_dwordx4 v[0:3], v[58:59], off
	global_load_dwordx4 v[24:27], v[58:59], off offset:32
	global_load_dwordx4 v[28:31], v[58:59], off offset:64
	global_load_dwordx4 v[36:39], v[58:59], off offset:96
	global_load_dwordx4 v[48:51], v[58:59], off offset:128
	v_and_b32_e32 v60, 31, v169
	v_or_b32_e32 v61, s77, v60
	v_lshl_add_u32 v122, v61, 9, 0
	v_xor_b32_e32 v4, v84, v170
	v_lshl_add_u32 v4, v4, 4, v122
	ds_read_b128 v[20:23], v4
	v_add_u32_e32 v4, 2, v84
	v_xor_b32_e32 v4, v4, v170
	v_lshl_add_u32 v4, v4, 4, v122
	ds_read_b128 v[16:19], v4
	s_waitcnt vmcnt(4) lgkmcnt(1)
	v_mfma_f32_32x32x16_bf16 v[0:15], v[0:3], v[20:23], 0
	v_add_u32_e32 v32, 4, v84
	v_add_u32_e32 v85, 8, v84
	v_add_u32_e32 v91, 10, v84
	v_add_u32_e32 v82, v172, v61
	v_lshl_add_u32 v90, v60, 5, s28
	v_lshlrev_b32_e32 v100, 2, v84
	s_waitcnt vmcnt(3) lgkmcnt(0)
	v_mfma_f32_32x32x16_bf16 v[0:15], v[24:27], v[16:19], v[0:15]
	v_xor_b32_e32 v24, v32, v170
	v_lshl_add_u32 v24, v24, 4, v122
	ds_read_b128 v[44:47], v24
	v_add_u32_e32 v24, 6, v84
	v_xor_b32_e32 v24, v24, v170
	v_lshl_add_u32 v24, v24, 4, v122
	ds_read_b128 v[32:35], v24
	s_waitcnt vmcnt(2) lgkmcnt(1)
	v_mfma_f32_32x32x16_bf16 v[0:15], v[28:31], v[44:47], v[0:15]
	global_load_dwordx4 v[24:27], v[58:59], off offset:160
	global_load_dwordx4 v[52:55], v[58:59], off offset:192
	v_xor_b32_e32 v28, v85, v170
	v_lshl_add_u32 v28, v28, 4, v122
	ds_read_b128 v[40:43], v28
	v_xor_b32_e32 v28, v91, v170
	v_lshl_add_u32 v28, v28, 4, v122
	ds_read_b128 v[28:31], v28
	s_waitcnt vmcnt(3) lgkmcnt(2)
	v_mfma_f32_32x32x16_bf16 v[0:15], v[36:39], v[32:35], v[0:15]
	v_lshl_add_u64 v[36:37], s[6:7], 0, v[148:149]
	v_lshl_add_u64 v[86:87], v[36:37], 0, v[56:57]
	v_add_u32_e32 v36, 12, v84
	s_waitcnt vmcnt(2) lgkmcnt(1)
	v_mfma_f32_32x32x16_bf16 v[0:15], v[48:51], v[40:43], v[0:15]
	global_load_dwordx4 v[48:51], v[58:59], off offset:224
	s_waitcnt vmcnt(2) lgkmcnt(0)
	v_mfma_f32_32x32x16_bf16 v[0:15], v[24:27], v[28:31], v[0:15]
	v_xor_b32_e32 v24, v36, v170
	v_lshl_add_u32 v24, v24, 4, v122
	ds_read_b128 v[36:39], v24
	v_add_u32_e32 v24, 14, v84
	v_xor_b32_e32 v24, v24, v170
	v_lshl_add_u32 v24, v24, 4, v122
	ds_read_b128 v[24:27], v24
	s_waitcnt vmcnt(1) lgkmcnt(1)
	v_mfma_f32_32x32x16_bf16 v[0:15], v[52:55], v[36:39], v[0:15]
	v_and_b32_e32 v53, 64, v231
	v_xor_b32_e32 v52, 32, v231
	v_add_u32_e32 v53, 64, v53
	v_cmp_lt_i32_e32 vcc, v52, v53
	s_nop 1
	v_cndmask_b32_e32 v52, v231, v52, vcc
	v_lshlrev_b32_e32 v83, 2, v52
	s_waitcnt vmcnt(0) lgkmcnt(0)
	v_mfma_f32_32x32x16_bf16 v[0:15], v[48:51], v[24:27], v[0:15]
	v_lshl_add_u64 v[88:89], v[86:87], 0, s[2:3]
	v_add_co_u32_e32 v48, vcc, s39, v88
	s_nop 1
	v_addc_co_u32_e32 v49, vcc, 0, v89, vcc
	global_load_dwordx4 v[72:75], v[48:49], off
	global_load_dwordx4 v[76:79], v[48:49], off offset:32
	global_load_dwordx4 v[68:71], v[48:49], off offset:64
	global_load_dwordx4 v[64:67], v[48:49], off offset:96
	global_load_dwordx4 v[60:63], v[48:49], off offset:128
	global_load_dwordx4 v[56:59], v[48:49], off offset:160
	global_load_dwordx4 v[52:55], v[48:49], off offset:192
	s_nop 0
	global_load_dwordx4 v[48:51], v[48:49], off offset:224
	v_lshl_add_u32 v92, v84, 1, v84
	v_ashrrev_i32_e32 v106, 31, v0
	v_ashrrev_i32_e32 v109, 31, v7
	v_ashrrev_i32_e32 v110, 31, v4
	v_ashrrev_i32_e32 v113, 31, v15
	v_ashrrev_i32_e32 v114, 31, v12
	v_ashrrev_i32_e32 v116, 31, v8
	v_ashrrev_i32_e32 v117, 31, v11
	v_add_u32_e32 v99, v85, v92
	v_add_u32_e32 v101, v91, v92
	v_add_u32_e32 v102, 11, v100
	v_add_u32_e32 v93, 16, v100
	v_add_u32_e32 v91, 19, v100
	v_add_u32_e32 v95, 24, v100
	v_add_u32_e32 v97, 27, v100
	v_and_b32_e32 v106, 0x7fffff80, v106
	v_and_b32_e32 v0, 0xffffff80, v0
	v_ashrrev_i32_e32 v107, 31, v3
	v_and_b32_e32 v3, 0xffffff80, v3
	v_and_b32_e32 v109, 0x7fffff80, v109
	v_and_b32_e32 v7, 0xffffff80, v7
	v_and_b32_e32 v110, 0x7fffff80, v110
	v_and_b32_e32 v4, 0xffffff80, v4
	v_and_b32_e32 v113, 0x7fffff80, v113
	v_and_b32_e32 v15, 0xffffff80, v15
	v_and_b32_e32 v114, 0x7fffff80, v114
	v_and_b32_e32 v12, 0xffffff80, v12
	v_and_b32_e32 v116, 0x7fffff80, v116
	v_and_b32_e32 v8, 0xffffff80, v8
	v_and_b32_e32 v117, 0x7fffff80, v117
	v_and_b32_e32 v11, 0xffffff80, v11
	v_bitop3_b32 v0, v106, v100, v0 bitop3:0xde
	v_ashrrev_i32_e32 v106, 31, v1
	v_and_b32_e32 v1, 0xffffff80, v1
	v_bitop3_b32 v3, v107, v3, s50 bitop3:0x6c
	v_ashrrev_i32_e32 v107, 31, v2
	v_and_b32_e32 v2, 0xffffff80, v2
	v_bitop3_b32 v7, v109, v102, v7 bitop3:0xde
	v_ashrrev_i32_e32 v109, 31, v6
	v_bitop3_b32 v4, v110, v99, v4 bitop3:0xde
	v_ashrrev_i32_e32 v110, 31, v5
	v_bitop3_b32 v15, v113, v97, v15 bitop3:0xde
	v_ashrrev_i32_e32 v113, 31, v14
	v_bitop3_b32 v12, v114, v95, v12 bitop3:0xde
	v_ashrrev_i32_e32 v114, 31, v13
	v_bitop3_b32 v8, v116, v93, v8 bitop3:0xde
	v_ashrrev_i32_e32 v116, 31, v9
	v_bitop3_b32 v11, v117, v91, v11 bitop3:0xde
	v_ashrrev_i32_e32 v117, 31, v10
	v_or_b32_e32 v105, 1, v100
	v_or_b32_e32 v103, 2, v100
	v_or_b32_e32 v104, 3, v100
	v_add_u32_e32 v98, 9, v100
	v_add_u32_e32 v92, 17, v100
	v_add_u32_e32 v85, 18, v100
	v_add_u32_e32 v94, 25, v100
	v_add_u32_e32 v96, 26, v100
	v_bitop3_b32 v1, v106, v1, s50 bitop3:0x6c
	v_bitop3_b32 v2, v107, v2, s50 bitop3:0x6c
	v_and_b32_e32 v109, 0x7fffff80, v109
	v_and_b32_e32 v6, 0xffffff80, v6
	v_and_b32_e32 v110, 0x7fffff80, v110
	v_and_b32_e32 v5, 0xffffff80, v5
	v_and_b32_e32 v113, 0x7fffff80, v113
	v_and_b32_e32 v14, 0xffffff80, v14
	v_and_b32_e32 v114, 0x7fffff80, v114
	v_and_b32_e32 v13, 0xffffff80, v13
	v_and_b32_e32 v116, 0x7fffff80, v116
	v_and_b32_e32 v9, 0xffffff80, v9
	v_and_b32_e32 v117, 0x7fffff80, v117
; #define P6_LOADKF(BUF, STEP) do { const bf16* skb_ = SK + (size_t)(h * 2 + ((STEP) >> 2)) * 128 * 128 + (size_t)ql * 128 + 8 * hh + (size_t)((STEP) & 3) * 32 * 128; \
;             _Pragma("unroll") for (int ks_ = 0; ks_ < 8; ++ks_) kfa[BUF][ks_] = *(const bf16x8*)(skb_ + 16 * ks_); } while (0)
; template <bool FROM_LDS>
; __device__ __forceinline__ void p6_task(unsigned char* ws, int lane, int h, int tok, const bf16* qrow_g, const LAS unsigned char* qrow_l, int rsw, LAS unsigned char* scr) {
;     ...
;                 for (int ks = 0; ks < 8; ++ks) s = __builtin_amdgcn_mfma_f32_32x32x16_bf16(kfa[0][ks], qf[ks], s, 0, 0, 0);
;                 __builtin_amdgcn_sched_barrier(0);
;                 if (step + 1 < 8) { P6_LOADKF(0, step + 1); }
;                 __builtin_amdgcn_sched_barrier(0);
;                 int g[16];
; #pragma unroll
;                 for (int reg = 0; reg < 16; ++reg) { const int n = 32 * kt + (reg & 3) + 8 * (reg >> 2) + 4 * hh; g[reg] = (f2key(s[reg]) & ~127) | n; }
;                 p6_sort16(g);
;                 if (kt == 0) {
; #pragma unroll
;                     for (int i = 0; i < 16; ++i) g0[i] = g[i];
;                 } else if (kt == 1) p6_top16(g0, g);
;                 else if (kt == 2) {
; #pragma unroll
;                     for (int i = 0; i < 16; ++i) g1[i] = g[i];
;                 } else p6_top16(g1, g);
	v_and_b32_e32 v10, 0xffffff80, v10
	v_or_b32_e32 v1, v1, v105
	v_or_b32_e32 v3, v3, v104
	v_or_b32_e32 v2, v2, v103
	v_bitop3_b32 v6, v109, v101, v6 bitop3:0xde
	v_bitop3_b32 v5, v110, v98, v5 bitop3:0xde
	v_bitop3_b32 v14, v113, v96, v14 bitop3:0xde
	v_bitop3_b32 v13, v114, v94, v13 bitop3:0xde
	v_bitop3_b32 v9, v116, v92, v9 bitop3:0xde
	v_bitop3_b32 v10, v117, v85, v10 bitop3:0xde
	v_max_i32_e32 v106, v0, v1
	v_min_i32_e32 v107, v3, v2
	v_min_i32_e32 v0, v0, v1
	v_max_i32_e32 v1, v3, v2
	v_max_i32_e32 v109, v7, v6
	v_min_i32_e32 v110, v4, v5
	v_min_i32_e32 v6, v7, v6
	v_max_i32_e32 v4, v4, v5
	v_max_i32_e32 v113, v15, v14
	v_min_i32_e32 v114, v12, v13
	v_min_i32_e32 v14, v15, v14
	v_max_i32_e32 v12, v12, v13
	v_max_i32_e32 v116, v8, v9
	v_min_i32_e32 v117, v11, v10
	v_min_i32_e32 v8, v8, v9
	v_max_i32_e32 v9, v11, v10
	v_max_i32_e32 v108, v106, v107
	v_max_i32_e32 v2, v0, v1
	v_min_i32_e32 v111, v109, v110
	v_min_i32_e32 v5, v6, v4
	v_min_i32_e32 v106, v106, v107
	v_min_i32_e32 v0, v0, v1
	v_max_i32_e32 v107, v109, v110
	v_max_i32_e32 v4, v6, v4
	v_max_i32_e32 v115, v113, v114
	v_max_i32_e32 v13, v14, v12
	v_min_i32_e32 v118, v116, v117
	v_min_i32_e32 v10, v8, v9
	v_min_i32_e32 v113, v113, v114
	v_min_i32_e32 v12, v14, v12
	v_max_i32_e32 v114, v116, v117
	v_max_i32_e32 v8, v8, v9
	v_max_i32_e32 v3, v108, v2
	v_min_i32_e32 v7, v111, v5
	v_max_i32_e32 v1, v106, v0
	v_min_i32_e32 v6, v107, v4
	v_min_i32_e32 v2, v108, v2
	v_max_i32_e32 v5, v111, v5
	v_min_i32_e32 v0, v106, v0
	v_max_i32_e32 v4, v107, v4
	v_max_i32_e32 v15, v115, v13
	v_min_i32_e32 v11, v118, v10
	v_max_i32_e32 v14, v113, v12
	v_min_i32_e32 v9, v114, v8
	v_min_i32_e32 v13, v115, v13
	v_max_i32_e32 v10, v118, v10
	v_min_i32_e32 v12, v113, v12
	v_max_i32_e32 v8, v114, v8
	v_max_i32_e32 v112, v3, v7
	v_max_i32_e32 v109, v1, v6
	v_max_i32_e32 v108, v2, v5
	v_max_i32_e32 v106, v0, v4
	v_min_i32_e32 v119, v15, v11
	v_min_i32_e32 v116, v14, v9
	v_min_i32_e32 v115, v13, v10
	v_min_i32_e32 v113, v12, v8
	v_min_i32_e32 v3, v3, v7
	v_min_i32_e32 v1, v1, v6
	v_min_i32_e32 v2, v2, v5
	v_min_i32_e32 v0, v0, v4
	v_max_i32_e32 v5, v15, v11
	v_max_i32_e32 v7, v14, v9
	v_max_i32_e32 v10, v13, v10
	v_max_i32_e32 v8, v12, v8
	v_max_i32_e32 v110, v112, v109
	v_max_i32_e32 v107, v108, v106
	v_min_i32_e32 v117, v119, v116
	v_min_i32_e32 v114, v115, v113
	v_max_i32_e32 v6, v3, v1
	v_max_i32_e32 v4, v2, v0
	v_min_i32_e32 v9, v5, v7
	v_min_i32_e32 v11, v10, v8
	v_min_i32_e32 v12, v112, v109
	v_min_i32_e32 v13, v108, v106
	v_max_i32_e32 v111, v110, v107
	v_min_i32_e32 v118, v117, v114
	v_max_i32_e32 v121, v6, v4
	v_min_i32_e32 v123, v9, v11
	v_max_i32_e32 v106, v12, v13
	v_max_i32_e32 v108, v119, v116
	v_max_i32_e32 v109, v115, v113
	v_min_i32_e32 v115, v3, v1
	v_min_i32_e32 v116, v2, v0
	v_max_i32_e32 v126, v5, v7
	v_max_i32_e32 v127, v10, v8
	v_min_i32_e32 v107, v110, v107
	v_max_i32_e32 v110, v117, v114
	v_min_i32_e32 v117, v6, v4
	v_max_i32_e32 v132, v9, v11
	v_min_i32_e32 v135, v12, v13
	s_waitcnt vmcnt(7)
	v_mfma_f32_32x32x16_bf16 v[0:15], v[72:75], v[20:23], 0
	v_max_i32_e32 v72, v108, v109
	v_min_i32_e32 v74, v115, v116
	v_max_i32_e32 v75, v126, v127
	v_min_i32_e32 v112, v108, v109
	v_max_i32_e32 v119, v115, v116
	v_min_i32_e32 v128, v126, v127
	v_min_i32_e32 v114, v107, v110
	s_waitcnt vmcnt(6)
	v_mfma_f32_32x32x16_bf16 v[0:15], v[76:79], v[16:19], v[0:15]
	v_min_i32_e32 v133, v117, v132
	v_min_i32_e32 v73, v135, v72
	v_min_i32_e32 v108, v74, v75
	v_min_i32_e32 v113, v106, v112
	v_min_i32_e32 v129, v119, v128
	v_min_i32_e32 v120, v111, v118
	v_min_i32_e32 v124, v121, v123
	s_waitcnt vmcnt(5)
	v_mfma_f32_32x32x16_bf16 v[0:15], v[68:71], v[44:47], v[0:15]
	v_max_i32_e32 v68, v114, v133
	v_max_i32_e32 v69, v73, v108
	v_min_i32_e32 v130, v113, v129
	v_max_i32_e32 v77, v113, v129
	v_min_i32_e32 v129, v68, v69
	v_max_i32_e32 v137, v68, v69
	v_max_i32_e32 v68, v119, v128
	s_waitcnt vmcnt(4)
	v_mfma_f32_32x32x16_bf16 v[0:15], v[64:67], v[32:35], v[0:15]
	v_max_i32_e32 v64, v111, v118
	v_max_i32_e32 v65, v121, v123
	v_max_i32_e32 v67, v106, v112
	v_max_i32_e32 v70, v74, v75
	v_min_i32_e32 v125, v120, v124
	v_min_i32_e32 v134, v114, v133
	v_min_i32_e32 v109, v73, v108
	s_waitcnt vmcnt(3)
	v_mfma_f32_32x32x16_bf16 v[0:15], v[60:63], v[40:43], v[0:15]
	v_max_i32_e32 v60, v107, v110
	v_max_i32_e32 v61, v117, v132
	v_max_i32_e32 v63, v135, v72
	v_max_i32_e32 v76, v120, v124
	v_min_i32_e32 v66, v64, v65
	v_min_i32_e32 v69, v67, v68
	v_min_i32_e32 v62, v60, v61
	s_waitcnt vmcnt(2)
	v_mfma_f32_32x32x16_bf16 v[0:15], v[56:59], v[28:31], v[0:15]
	v_min_i32_e32 v71, v63, v70
	v_max_i32_e32 v56, v64, v65
	v_max_i32_e32 v57, v67, v68
	v_min_i32_e32 v131, v125, v130
	v_min_i32_e32 v126, v134, v109
	v_max_i32_e32 v125, v125, v130
	v_max_i32_e32 v130, v134, v109
	s_waitcnt vmcnt(1)
	v_mfma_f32_32x32x16_bf16 v[0:15], v[52:55], v[36:39], v[0:15]
	v_max_i32_e32 v52, v60, v61
	v_max_i32_e32 v53, v63, v70
	v_min_i32_e32 v124, v76, v77
	v_max_i32_e32 v136, v76, v77
	v_min_i32_e32 v123, v66, v69
	v_min_i32_e32 v128, v62, v71
	v_max_i32_e32 v135, v66, v69
	v_max_i32_e32 v139, v62, v71
	v_min_i32_e32 v141, v56, v57
	v_min_i32_e32 v142, v52, v53
	v_max_i32_e32 v148, v56, v57
	v_max_i32_e32 v154, v52, v53
	v_min_i32_e32 v127, v131, v126
	v_min_i32_e32 v134, v125, v130
	v_min_i32_e32 v133, v124, v129
	v_min_i32_e32 v138, v136, v137
	v_min_i32_e32 v132, v123, v128
	v_min_i32_e32 v140, v135, v139
	v_min_i32_e32 v143, v141, v142
	v_min_i32_e32 v155, v148, v154
	s_waitcnt vmcnt(0)
; #define P6_LOADKF(BUF, STEP) do { const bf16* skb_ = SK + (size_t)(h * 2 + ((STEP) >> 2)) * 128 * 128 + (size_t)ql * 128 + 8 * hh + (size_t)((STEP) & 3) * 32 * 128; \
;             _Pragma("unroll") for (int ks_ = 0; ks_ < 8; ++ks_) kfa[BUF][ks_] = *(const bf16x8*)(skb_ + 16 * ks_); } while (0)
; template <bool FROM_LDS>
; __device__ __forceinline__ void p6_task(unsigned char* ws, int lane, int h, int tok, const bf16* qrow_g, const LAS unsigned char* qrow_l, int rsw, LAS unsigned char* scr) {
;     ...
;                 for (int ks = 0; ks < 8; ++ks) s = __builtin_amdgcn_mfma_f32_32x32x16_bf16(kfa[0][ks], qf[ks], s, 0, 0, 0);
;                 __builtin_amdgcn_sched_barrier(0);
;                 if (step + 1 < 8) { P6_LOADKF(0, step + 1); }
;                 __builtin_amdgcn_sched_barrier(0);
;                 int g[16];
; #pragma unroll
;                 for (int reg = 0; reg < 16; ++reg) { const int n = 32 * kt + (reg & 3) + 8 * (reg >> 2) + 4 * hh; g[reg] = (f2key(s[reg]) & ~127) | n; }
;                 p6_sort16(g);
;                 if (kt == 0) {
; #pragma unroll
;                     for (int i = 0; i < 16; ++i) g0[i] = g[i];
;                 } else if (kt == 1) p6_top16(g0, g);
;                 else if (kt == 2) {
; #pragma unroll
;                     for (int i = 0; i < 16; ++i) g1[i] = g[i];
;                 } else p6_top16(g1, g);
	v_mfma_f32_32x32x16_bf16 v[0:15], v[48:51], v[24:27], v[0:15]
	v_add_co_u32_e32 v48, vcc, s46, v88
	s_nop 1
	v_addc_co_u32_e32 v49, vcc, 0, v89, vcc
	global_load_dwordx4 v[76:79], v[48:49], off
	global_load_dwordx4 v[72:75], v[48:49], off offset:32
	global_load_dwordx4 v[68:71], v[48:49], off offset:64
	global_load_dwordx4 v[64:67], v[48:49], off offset:96
	global_load_dwordx4 v[60:63], v[48:49], off offset:128
	global_load_dwordx4 v[56:59], v[48:49], off offset:160
	global_load_dwordx4 v[52:55], v[48:49], off offset:192
	s_nop 0
	global_load_dwordx4 v[48:51], v[48:49], off offset:224
	v_ashrrev_i32_e32 v156, 31, v0
	v_ashrrev_i32_e32 v157, 31, v3
	v_ashrrev_i32_e32 v172, 31, v7
	v_ashrrev_i32_e32 v173, 31, v4
	v_ashrrev_i32_e32 v176, 31, v15
	v_ashrrev_i32_e32 v177, 31, v12
	v_ashrrev_i32_e32 v179, 31, v8
	v_ashrrev_i32_e32 v180, 31, v11
	v_add_u32_e32 v121, 32, v100
	v_add_u32_e32 v119, 35, v100
	v_add_u32_e32 v115, 40, v100
	v_add_u32_e32 v117, 43, v100
	v_add_u32_e32 v109, 48, v100
	v_add_u32_e32 v107, 51, v100
	v_add_u32_e32 v111, 56, v100
	v_add_u32_e32 v113, 59, v100
	v_and_b32_e32 v156, 0x7fffff80, v156
	v_and_b32_e32 v0, 0xffffff80, v0
	v_and_b32_e32 v157, 0x7fffff80, v157
	v_and_b32_e32 v3, 0xffffff80, v3
	v_and_b32_e32 v172, 0x7fffff80, v172
	v_and_b32_e32 v7, 0xffffff80, v7
	v_and_b32_e32 v173, 0x7fffff80, v173
	v_and_b32_e32 v4, 0xffffff80, v4
	v_and_b32_e32 v176, 0x7fffff80, v176
	v_and_b32_e32 v15, 0xffffff80, v15
	v_and_b32_e32 v177, 0x7fffff80, v177
	v_and_b32_e32 v12, 0xffffff80, v12
	v_and_b32_e32 v179, 0x7fffff80, v179
	v_and_b32_e32 v8, 0xffffff80, v8
	v_and_b32_e32 v180, 0x7fffff80, v180
	v_and_b32_e32 v11, 0xffffff80, v11
	v_bitop3_b32 v0, v156, v121, v0 bitop3:0xde
	v_ashrrev_i32_e32 v156, 31, v1
	v_bitop3_b32 v3, v157, v119, v3 bitop3:0xde
	v_ashrrev_i32_e32 v157, 31, v2
	v_bitop3_b32 v7, v172, v117, v7 bitop3:0xde
	v_ashrrev_i32_e32 v172, 31, v6
	v_bitop3_b32 v4, v173, v115, v4 bitop3:0xde
	v_ashrrev_i32_e32 v173, 31, v5
	v_bitop3_b32 v15, v176, v113, v15 bitop3:0xde
	v_ashrrev_i32_e32 v176, 31, v14
	v_bitop3_b32 v12, v177, v111, v12 bitop3:0xde
	v_ashrrev_i32_e32 v177, 31, v13
	v_bitop3_b32 v8, v179, v109, v8 bitop3:0xde
	v_ashrrev_i32_e32 v179, 31, v9
	v_bitop3_b32 v11, v180, v107, v11 bitop3:0xde
	v_ashrrev_i32_e32 v180, 31, v10
	v_add_u32_e32 v120, 33, v100
	v_add_u32_e32 v118, 34, v100
	v_add_u32_e32 v114, 41, v100
	v_add_u32_e32 v116, 42, v100
	v_add_u32_e32 v108, 49, v100
	v_add_u32_e32 v106, 50, v100
	v_add_u32_e32 v110, 57, v100
	v_add_u32_e32 v112, 58, v100
	v_and_b32_e32 v156, 0x7fffff80, v156
	v_and_b32_e32 v1, 0xffffff80, v1
	v_and_b32_e32 v157, 0x7fffff80, v157
	v_and_b32_e32 v2, 0xffffff80, v2
	v_and_b32_e32 v172, 0x7fffff80, v172
	v_and_b32_e32 v6, 0xffffff80, v6
	v_and_b32_e32 v173, 0x7fffff80, v173
	v_and_b32_e32 v5, 0xffffff80, v5
	v_and_b32_e32 v176, 0x7fffff80, v176
	v_and_b32_e32 v14, 0xffffff80, v14
	v_and_b32_e32 v177, 0x7fffff80, v177
	v_and_b32_e32 v13, 0xffffff80, v13
	v_and_b32_e32 v179, 0x7fffff80, v179
	v_and_b32_e32 v9, 0xffffff80, v9
	v_and_b32_e32 v180, 0x7fffff80, v180
	v_and_b32_e32 v10, 0xffffff80, v10
	v_bitop3_b32 v1, v156, v120, v1 bitop3:0xde
	v_bitop3_b32 v2, v157, v118, v2 bitop3:0xde
	v_bitop3_b32 v6, v172, v116, v6 bitop3:0xde
	v_bitop3_b32 v5, v173, v114, v5 bitop3:0xde
	v_bitop3_b32 v14, v176, v112, v14 bitop3:0xde
	v_bitop3_b32 v13, v177, v110, v13 bitop3:0xde
	v_bitop3_b32 v9, v179, v108, v9 bitop3:0xde
	v_bitop3_b32 v10, v180, v106, v10 bitop3:0xde
	v_max_i32_e32 v156, v0, v1
	v_min_i32_e32 v157, v3, v2
	v_min_i32_e32 v0, v0, v1
	v_max_i32_e32 v1, v3, v2
	v_max_i32_e32 v172, v7, v6
	v_min_i32_e32 v173, v4, v5
	v_min_i32_e32 v6, v7, v6
	v_max_i32_e32 v4, v4, v5
	v_max_i32_e32 v176, v15, v14
	v_min_i32_e32 v177, v12, v13
	v_min_i32_e32 v14, v15, v14
	v_max_i32_e32 v12, v12, v13
	v_max_i32_e32 v179, v8, v9
	v_min_i32_e32 v180, v11, v10
	v_min_i32_e32 v8, v8, v9
	v_max_i32_e32 v9, v11, v10
	v_max_i32_e32 v171, v156, v157
	v_max_i32_e32 v2, v0, v1
	v_min_i32_e32 v174, v172, v173
	v_min_i32_e32 v5, v6, v4
	v_min_i32_e32 v156, v156, v157
	v_min_i32_e32 v0, v0, v1
	v_max_i32_e32 v157, v172, v173
	v_max_i32_e32 v4, v6, v4
	v_max_i32_e32 v178, v176, v177
	v_max_i32_e32 v13, v14, v12
	v_min_i32_e32 v181, v179, v180
	v_min_i32_e32 v10, v8, v9
	v_min_i32_e32 v176, v176, v177
	v_min_i32_e32 v12, v14, v12
	v_max_i32_e32 v177, v179, v180
	v_max_i32_e32 v8, v8, v9
	v_max_i32_e32 v3, v171, v2
	v_min_i32_e32 v7, v174, v5
	v_max_i32_e32 v1, v156, v0
	v_min_i32_e32 v6, v157, v4
	v_min_i32_e32 v2, v171, v2
	v_max_i32_e32 v5, v174, v5
	v_min_i32_e32 v0, v156, v0
	v_max_i32_e32 v4, v157, v4
	v_max_i32_e32 v15, v178, v13
	v_min_i32_e32 v11, v181, v10
	v_max_i32_e32 v14, v176, v12
	v_min_i32_e32 v9, v177, v8
	v_min_i32_e32 v13, v178, v13
	v_max_i32_e32 v10, v181, v10
	v_min_i32_e32 v12, v176, v12
	v_max_i32_e32 v8, v177, v8
	v_max_i32_e32 v175, v3, v7
	v_max_i32_e32 v172, v1, v6
	v_max_i32_e32 v171, v2, v5
	v_max_i32_e32 v156, v0, v4
	v_min_i32_e32 v182, v15, v11
	v_min_i32_e32 v179, v14, v9
	v_min_i32_e32 v178, v13, v10
	v_min_i32_e32 v176, v12, v8
	v_min_i32_e32 v3, v3, v7
	v_min_i32_e32 v1, v1, v6
	v_min_i32_e32 v2, v2, v5
	v_min_i32_e32 v0, v0, v4
	v_max_i32_e32 v7, v15, v11
	v_max_i32_e32 v9, v14, v9
	v_max_i32_e32 v10, v13, v10
	v_max_i32_e32 v8, v12, v8
	v_max_i32_e32 v173, v175, v172
	v_max_i32_e32 v157, v171, v156
	v_min_i32_e32 v180, v182, v179
	v_min_i32_e32 v177, v178, v176
	v_max_i32_e32 v6, v3, v1
	v_max_i32_e32 v4, v2, v0
	v_min_i32_e32 v11, v7, v9
	v_min_i32_e32 v12, v10, v8
	v_min_i32_e32 v172, v175, v172
	v_min_i32_e32 v156, v171, v156
	v_max_i32_e32 v175, v182, v179
; #define P6_LOADKF(BUF, STEP) do { const bf16* skb_ = SK + (size_t)(h * 2 + ((STEP) >> 2)) * 128 * 128 + (size_t)ql * 128 + 8 * hh + (size_t)((STEP) & 3) * 32 * 128; \
;             _Pragma("unroll") for (int ks_ = 0; ks_ < 8; ++ks_) kfa[BUF][ks_] = *(const bf16x8*)(skb_ + 16 * ks_); } while (0)
; template <bool FROM_LDS>
; __device__ __forceinline__ void p6_task(unsigned char* ws, int lane, int h, int tok, const bf16* qrow_g, const LAS unsigned char* qrow_l, int rsw, LAS unsigned char* scr) {
;     ...
;                 for (int ks = 0; ks < 8; ++ks) s = __builtin_amdgcn_mfma_f32_32x32x16_bf16(kfa[0][ks], qf[ks], s, 0, 0, 0);
;                 __builtin_amdgcn_sched_barrier(0);
;                 if (step + 1 < 8) { P6_LOADKF(0, step + 1); }
;                 __builtin_amdgcn_sched_barrier(0);
;                 int g[16];
; #pragma unroll
;                 for (int reg = 0; reg < 16; ++reg) { const int n = 32 * kt + (reg & 3) + 8 * (reg >> 2) + 4 * hh; g[reg] = (f2key(s[reg]) & ~127) | n; }
;                 p6_sort16(g);
;                 if (kt == 0) {
; #pragma unroll
;                     for (int i = 0; i < 16; ++i) g0[i] = g[i];
;                 } else if (kt == 1) p6_top16(g0, g);
;                 else if (kt == 2) {
; #pragma unroll
;                     for (int i = 0; i < 16; ++i) g1[i] = g[i];
;                 } else p6_top16(g1, g);
	v_max_i32_e32 v176, v178, v176
	v_min_i32_e32 v1, v3, v1
	v_min_i32_e32 v0, v2, v0
	v_max_i32_e32 v3, v7, v9
	v_max_i32_e32 v7, v10, v8
	v_max_i32_e32 v174, v173, v157
	v_min_i32_e32 v181, v180, v177
	v_max_i32_e32 v5, v6, v4
	v_min_i32_e32 v13, v11, v12
	v_max_i32_e32 v171, v172, v156
	v_min_i32_e32 v178, v175, v176
	v_max_i32_e32 v2, v1, v0
	v_min_i32_e32 v8, v3, v7
	v_min_i32_e32 v183, v174, v181
	v_min_i32_e32 v14, v5, v13
	v_min_i32_e32 v179, v171, v178
	v_min_i32_e32 v9, v2, v8
	v_min_i32_e32 v15, v183, v14
	v_min_i32_e32 v10, v179, v9
	v_min_i32_e32 v157, v173, v157
	v_max_i32_e32 v173, v180, v177
	v_min_i32_e32 v4, v6, v4
	v_max_i32_e32 v6, v11, v12
	v_min_i32_e32 v156, v172, v156
	v_max_i32_e32 v172, v175, v176
	v_min_i32_e32 v0, v1, v0
	v_max_i32_e32 v1, v3, v7
	v_max_i32_e32 v14, v183, v14
	v_max_i32_e32 v9, v179, v9
	v_min_i32_e32 v182, v15, v10
	v_min_i32_e32 v177, v157, v173
	v_min_i32_e32 v11, v4, v6
	v_min_i32_e32 v175, v156, v172
	v_min_i32_e32 v3, v0, v1
	v_max_i32_e32 v10, v15, v10
	v_min_i32_e32 v15, v14, v9
	v_max_i32_e32 v9, v14, v9
	v_max_i32_e32 v14, v174, v181
	v_max_i32_e32 v5, v5, v13
	v_max_i32_e32 v171, v171, v178
	v_max_i32_e32 v2, v2, v8
	v_max_i32_e32 v157, v157, v173
	v_max_i32_e32 v4, v4, v6
	v_max_i32_e32 v156, v156, v172
	v_max_i32_e32 v0, v0, v1
	v_min_i32_e32 v12, v177, v11
	v_min_i32_e32 v7, v175, v3
	v_max_i32_e32 v11, v177, v11
	v_max_i32_e32 v3, v175, v3
	v_min_i32_e32 v13, v14, v5
	v_min_i32_e32 v8, v171, v2
	v_min_i32_e32 v6, v157, v4
	v_min_i32_e32 v1, v156, v0
	v_min_i32_e32 v176, v12, v7
	v_max_i32_e32 v7, v12, v7
	v_min_i32_e32 v175, v11, v3
	v_max_i32_e32 v3, v11, v3
	v_min_i32_e32 v174, v13, v8
	v_min_i32_e32 v172, v6, v1
	v_max_i32_e32 v8, v13, v8
	v_max_i32_e32 v1, v6, v1
	v_max_i32_e32 v5, v14, v5
	v_max_i32_e32 v2, v171, v2
	v_max_i32_e32 v4, v157, v4
	v_max_i32_e32 v0, v156, v0
	v_min_i32_e32 v180, v182, v176
	v_min_i32_e32 v12, v10, v7
	v_min_i32_e32 v11, v9, v3
	v_min_i32_e32 v173, v174, v172
	v_min_i32_e32 v6, v8, v1
	v_min_i32_e32 v13, v5, v2
	v_min_i32_e32 v14, v4, v0
	v_max_i32_e32 v2, v5, v2
	v_max_i32_e32 v0, v4, v0
	v_min_i32_e32 v177, v15, v175
	v_min_i32_e32 v156, v13, v14
	v_min_i32_e32 v4, v2, v0
	v_max3_i32 v5, v148, v154, v180
	v_max3_i32 v148, v155, v182, v176
	v_max3_i32 v12, v141, v142, v12
	v_max3_i32 v141, v143, v10, v7
	v_max3_i32 v123, v123, v128, v11
	v_max3_i32 v128, v132, v9, v3
	v_max3_i32 v3, v136, v137, v173
	v_max3_i32 v7, v138, v174, v172
	v_max3_i32 v6, v124, v129, v6
	v_max3_i32 v135, v135, v139, v177
	v_max3_i32 v139, v140, v15, v175
	v_max3_i32 v124, v133, v8, v1
	v_max3_i32 v125, v125, v130, v156
	v_max3_i32 v129, v134, v13, v14
	v_max3_i32 v126, v131, v126, v4
	v_max3_i32 v127, v127, v2, v0
	v_max_i32_e32 v130, v5, v3
	v_min_i32_e32 v131, v5, v3
	v_max_i32_e32 v132, v148, v7
	v_min_i32_e32 v133, v148, v7
	v_max_i32_e32 v134, v12, v6
	v_min_i32_e32 v136, v12, v6
	s_waitcnt vmcnt(7)
	v_mfma_f32_32x32x16_bf16 v[0:15], v[76:79], v[20:23], 0
	v_max_i32_e32 v137, v141, v124
	v_min_i32_e32 v76, v141, v124
	v_max_i32_e32 v77, v135, v125
	v_min_i32_e32 v78, v135, v125
	v_max_i32_e32 v79, v139, v129
	v_min_i32_e32 v124, v139, v129
	v_max_i32_e32 v125, v123, v126
	s_waitcnt vmcnt(6)
	v_mfma_f32_32x32x16_bf16 v[0:15], v[72:75], v[16:19], v[0:15]
	v_min_i32_e32 v123, v123, v126
	v_max_i32_e32 v72, v128, v127
	v_min_i32_e32 v73, v128, v127
	v_max_i32_e32 v74, v130, v77
	v_min_i32_e32 v75, v130, v77
	v_max_i32_e32 v77, v132, v79
	v_min_i32_e32 v126, v132, v79
	s_waitcnt vmcnt(5)
	v_mfma_f32_32x32x16_bf16 v[0:15], v[68:71], v[44:47], v[0:15]
	v_max_i32_e32 v79, v134, v125
	v_min_i32_e32 v68, v134, v125
	v_max_i32_e32 v69, v137, v72
	v_min_i32_e32 v70, v137, v72
	v_max_i32_e32 v71, v131, v78
	v_min_i32_e32 v128, v131, v78
	v_max_i32_e32 v127, v133, v124
	s_waitcnt vmcnt(4)
	v_mfma_f32_32x32x16_bf16 v[0:15], v[64:67], v[32:35], v[0:15]
	v_min_i32_e32 v131, v133, v124
	v_max_i32_e32 v64, v136, v123
	v_min_i32_e32 v65, v136, v123
	v_max_i32_e32 v66, v76, v73
	v_min_i32_e32 v67, v76, v73
	v_max_i32_e32 v73, v74, v79
	v_min_i32_e32 v72, v74, v79
	s_waitcnt vmcnt(3)
	v_mfma_f32_32x32x16_bf16 v[0:15], v[60:63], v[40:43], v[0:15]
	v_max_i32_e32 v76, v77, v69
	v_min_i32_e32 v79, v77, v69
	v_max_i32_e32 v77, v75, v68
	v_min_i32_e32 v74, v75, v68
	v_max_i32_e32 v125, v126, v70
	v_min_i32_e32 v123, v126, v70
	v_max_i32_e32 v78, v71, v64
	s_waitcnt vmcnt(2)
	v_mfma_f32_32x32x16_bf16 v[0:15], v[56:59], v[28:31], v[0:15]
	v_min_i32_e32 v75, v71, v64
	v_max_i32_e32 v129, v127, v66
	v_min_i32_e32 v127, v127, v66
	v_max_i32_e32 v126, v128, v65
	v_min_i32_e32 v124, v128, v65
	v_max_i32_e32 v130, v131, v67
	v_min_i32_e32 v128, v131, v67
	s_waitcnt vmcnt(1)
	v_mfma_f32_32x32x16_bf16 v[0:15], v[52:55], v[36:39], v[0:15]
	v_min_i32_e32 v194, v73, v76
	v_min_i32_e32 v196, v72, v79
	v_min_i32_e32 v195, v77, v125
	v_min_i32_e32 v135, v74, v123
	v_min_i32_e32 v134, v78, v129
	v_min_i32_e32 v133, v75, v127
	v_min_i32_e32 v132, v126, v130
	v_min_i32_e32 v131, v124, v128
	s_waitcnt vmcnt(0)
; #define P6_LOADKF(BUF, STEP) do { const bf16* skb_ = SK + (size_t)(h * 2 + ((STEP) >> 2)) * 128 * 128 + (size_t)ql * 128 + 8 * hh + (size_t)((STEP) & 3) * 32 * 128; \
;             _Pragma("unroll") for (int ks_ = 0; ks_ < 8; ++ks_) kfa[BUF][ks_] = *(const bf16x8*)(skb_ + 16 * ks_); } while (0)
; template <bool FROM_LDS>
; __device__ __forceinline__ void p6_task(unsigned char* ws, int lane, int h, int tok, const bf16* qrow_g, const LAS unsigned char* qrow_l, int rsw, LAS unsigned char* scr) {
;     ...
;             for (int kt = 0; kt < 4; ++kt) { f32x16 s = (f32x16){};
;                 const int step = 4 * p + kt;
; #pragma unroll
;                 for (int ks = 0; ks < 8; ++ks) s = __builtin_amdgcn_mfma_f32_32x32x16_bf16(kfa[0][ks], qf[ks], s, 0, 0, 0);
;                 __builtin_amdgcn_sched_barrier(0);
;                 if (step + 1 < 8) { P6_LOADKF(0, step + 1); }
;                 __builtin_amdgcn_sched_barrier(0);
;                 int g[16];
; #pragma unroll
;                 for (int reg = 0; reg < 16; ++reg) { const int n = 32 * kt + (reg & 3) + 8 * (reg >> 2) + 4 * hh; g[reg] = (f2key(s[reg]) & ~127) | n; }
;                 p6_sort16(g);
;                 if (kt == 0) {
; #pragma unroll
;                     for (int i = 0; i < 16; ++i) g0[i] = g[i];
;                 } else if (kt == 1) p6_top16(g0, g);
;                 else if (kt == 2) {
; #pragma unroll
;                     for (int i = 0; i < 16; ++i) g1[i] = g[i];
;                 } else p6_top16(g1, g);
	v_mfma_f32_32x32x16_bf16 v[0:15], v[48:51], v[24:27], v[0:15]
	v_add_co_u32_e32 v48, vcc, s47, v88
	s_nop 1
	v_addc_co_u32_e32 v49, vcc, 0, v89, vcc
	global_load_dwordx4 v[178:181], v[48:49], off
	global_load_dwordx4 v[182:185], v[48:49], off offset:32
	global_load_dwordx4 v[68:71], v[48:49], off offset:64
	global_load_dwordx4 v[64:67], v[48:49], off offset:96
	global_load_dwordx4 v[60:63], v[48:49], off offset:128
	global_load_dwordx4 v[56:59], v[48:49], off offset:160
	global_load_dwordx4 v[52:55], v[48:49], off offset:192
	s_nop 0
	global_load_dwordx4 v[48:51], v[48:49], off offset:224
	v_ashrrev_i32_e32 v88, 31, v0
	v_add_u32_e32 v171, 64, v100
	v_and_b32_e32 v88, 0x7fffff80, v88
	v_and_b32_e32 v0, 0xffffff80, v0
	v_bitop3_b32 v0, v88, v171, v0 bitop3:0xde
	v_ashrrev_i32_e32 v88, 31, v1
	v_add_u32_e32 v172, 0x41, v100
	v_and_b32_e32 v88, 0x7fffff80, v88
	v_and_b32_e32 v1, 0xffffff80, v1
	v_bitop3_b32 v1, v88, v172, v1 bitop3:0xde
	v_ashrrev_i32_e32 v88, 31, v2
	v_add_u32_e32 v148, 0x42, v100
	v_and_b32_e32 v88, 0x7fffff80, v88
	v_and_b32_e32 v2, 0xffffff80, v2
	v_bitop3_b32 v2, v88, v148, v2 bitop3:0xde
	v_ashrrev_i32_e32 v88, 31, v3
	v_add_u32_e32 v175, 0x43, v100
	v_and_b32_e32 v88, 0x7fffff80, v88
	v_and_b32_e32 v3, 0xffffff80, v3
	v_bitop3_b32 v3, v88, v175, v3 bitop3:0xde
	v_ashrrev_i32_e32 v88, 31, v4
	v_add_u32_e32 v140, 0x48, v100
	v_and_b32_e32 v88, 0x7fffff80, v88
	v_and_b32_e32 v4, 0xffffff80, v4
	v_bitop3_b32 v4, v88, v140, v4 bitop3:0xde
	v_ashrrev_i32_e32 v88, 31, v5
	v_add_u32_e32 v142, 0x49, v100
	v_and_b32_e32 v88, 0x7fffff80, v88
	v_and_b32_e32 v5, 0xffffff80, v5
	v_bitop3_b32 v5, v88, v142, v5 bitop3:0xde
	v_ashrrev_i32_e32 v88, 31, v6
	v_add_u32_e32 v173, 0x4a, v100
	v_and_b32_e32 v88, 0x7fffff80, v88
	v_and_b32_e32 v6, 0xffffff80, v6
	v_bitop3_b32 v6, v88, v173, v6 bitop3:0xde
	v_ashrrev_i32_e32 v88, 31, v7
	v_add_u32_e32 v176, 0x4b, v100
	v_and_b32_e32 v88, 0x7fffff80, v88
	v_and_b32_e32 v7, 0xffffff80, v7
	v_bitop3_b32 v7, v88, v176, v7 bitop3:0xde
	v_ashrrev_i32_e32 v88, 31, v8
	v_add_u32_e32 v137, 0x50, v100
	v_and_b32_e32 v88, 0x7fffff80, v88
	v_and_b32_e32 v8, 0xffffff80, v8
	v_bitop3_b32 v8, v88, v137, v8 bitop3:0xde
	v_ashrrev_i32_e32 v88, 31, v9
	v_add_u32_e32 v138, 0x51, v100
	v_and_b32_e32 v88, 0x7fffff80, v88
	v_and_b32_e32 v9, 0xffffff80, v9
	v_bitop3_b32 v9, v88, v138, v9 bitop3:0xde
	v_ashrrev_i32_e32 v88, 31, v10
	v_add_u32_e32 v136, 0x52, v100
	v_and_b32_e32 v88, 0x7fffff80, v88
	v_and_b32_e32 v10, 0xffffff80, v10
	v_bitop3_b32 v10, v88, v136, v10 bitop3:0xde
	v_ashrrev_i32_e32 v88, 31, v11
	v_add_u32_e32 v139, 0x53, v100
	v_and_b32_e32 v88, 0x7fffff80, v88
	v_and_b32_e32 v11, 0xffffff80, v11
	v_bitop3_b32 v11, v88, v139, v11 bitop3:0xde
	v_ashrrev_i32_e32 v88, 31, v12
	v_add_u32_e32 v141, 0x58, v100
	v_and_b32_e32 v88, 0x7fffff80, v88
	v_and_b32_e32 v12, 0xffffff80, v12
	v_bitop3_b32 v12, v88, v141, v12 bitop3:0xde
	v_ashrrev_i32_e32 v88, 31, v13
	v_add_u32_e32 v143, 0x59, v100
	v_and_b32_e32 v88, 0x7fffff80, v88
	v_and_b32_e32 v13, 0xffffff80, v13
	v_bitop3_b32 v13, v88, v143, v13 bitop3:0xde
	v_ashrrev_i32_e32 v88, 31, v14
	v_add_u32_e32 v174, 0x5a, v100
	v_and_b32_e32 v88, 0x7fffff80, v88
	v_and_b32_e32 v14, 0xffffff80, v14
	v_bitop3_b32 v14, v88, v174, v14 bitop3:0xde
	v_ashrrev_i32_e32 v88, 31, v15
	v_add_u32_e32 v177, 0x5b, v100
	v_and_b32_e32 v88, 0x7fffff80, v88
	v_and_b32_e32 v15, 0xffffff80, v15
	v_bitop3_b32 v15, v88, v177, v15 bitop3:0xde
	v_max_i32_e32 v88, v0, v1
	v_min_i32_e32 v0, v0, v1
	v_max_i32_e32 v1, v3, v2
	v_min_i32_e32 v2, v3, v2
	v_max_i32_e32 v3, v4, v5
	v_min_i32_e32 v4, v4, v5
	v_max_i32_e32 v5, v7, v6
	v_min_i32_e32 v6, v7, v6
	v_max_i32_e32 v7, v8, v9
	v_min_i32_e32 v8, v8, v9
	v_max_i32_e32 v9, v11, v10
	v_min_i32_e32 v10, v11, v10
	v_max_i32_e32 v11, v12, v13
	v_min_i32_e32 v12, v12, v13
	v_max_i32_e32 v13, v15, v14
	v_min_i32_e32 v14, v15, v14
	v_max_i32_e32 v15, v88, v2
	v_min_i32_e32 v2, v88, v2
	v_max_i32_e32 v88, v0, v1
	v_min_i32_e32 v0, v0, v1
	v_max_i32_e32 v1, v6, v3
	v_min_i32_e32 v3, v6, v3
	v_max_i32_e32 v6, v5, v4
	v_min_i32_e32 v4, v5, v4
	v_max_i32_e32 v5, v7, v10
	v_min_i32_e32 v7, v7, v10
	v_max_i32_e32 v10, v8, v9
	v_min_i32_e32 v8, v8, v9
	v_max_i32_e32 v9, v14, v11
	v_min_i32_e32 v11, v14, v11
	v_max_i32_e32 v14, v13, v12
	v_min_i32_e32 v12, v13, v12
	v_max_i32_e32 v13, v15, v88
	v_min_i32_e32 v15, v15, v88
	v_max_i32_e32 v88, v2, v0
	v_min_i32_e32 v0, v2, v0
	v_max_i32_e32 v2, v4, v3
	v_min_i32_e32 v3, v4, v3
	v_max_i32_e32 v4, v6, v1
	v_min_i32_e32 v1, v6, v1
	v_max_i32_e32 v6, v5, v10
	v_min_i32_e32 v5, v5, v10
	v_max_i32_e32 v10, v7, v8
	v_min_i32_e32 v7, v7, v8
	v_max_i32_e32 v8, v12, v11
	v_min_i32_e32 v11, v12, v11
	v_max_i32_e32 v12, v14, v9
	v_min_i32_e32 v9, v14, v9
	v_max_i32_e32 v14, v13, v3
	v_min_i32_e32 v3, v13, v3
	v_max_i32_e32 v13, v15, v2
	v_min_i32_e32 v2, v15, v2
	v_max_i32_e32 v15, v88, v1
	v_min_i32_e32 v1, v88, v1
	v_max_i32_e32 v88, v0, v4
	v_min_i32_e32 v0, v0, v4
	v_max_i32_e32 v4, v11, v6
	v_min_i32_e32 v6, v11, v6
	v_max_i32_e32 v11, v8, v5
	v_min_i32_e32 v5, v8, v5
	v_max_i32_e32 v8, v9, v10
	v_min_i32_e32 v9, v9, v10
	v_max_i32_e32 v10, v12, v7
	v_min_i32_e32 v7, v12, v7
	v_max_i32_e32 v12, v14, v15
	v_min_i32_e32 v14, v14, v15
	v_max_i32_e32 v15, v13, v88
	v_min_i32_e32 v13, v13, v88
	v_max_i32_e32 v88, v3, v1
	v_min_i32_e32 v1, v3, v1
	v_max_i32_e32 v3, v2, v0
	v_min_i32_e32 v0, v2, v0
	v_max_i32_e32 v2, v9, v6
	v_min_i32_e32 v6, v9, v6
	v_max_i32_e32 v9, v7, v5
	v_min_i32_e32 v5, v7, v5
	v_max_i32_e32 v7, v8, v4
	v_min_i32_e32 v4, v8, v4
	v_max_i32_e32 v8, v10, v11
	v_min_i32_e32 v10, v10, v11
	v_max_i32_e32 v11, v12, v15
	v_min_i32_e32 v12, v12, v15
	v_max_i32_e32 v15, v14, v13
	v_max_i32_e32 v155, v1, v0
	v_min_i32_e32 v156, v1, v0
	v_max_i32_e32 v0, v5, v6
	v_min_i32_e32 v1, v5, v6
	v_max_i32_e32 v157, v9, v2
	v_min_i32_e32 v2, v9, v2
	v_min_i32_e32 v89, v14, v13
	v_max_i32_e32 v154, v88, v3
	v_min_i32_e32 v88, v88, v3
	v_max_i32_e32 v186, v10, v4
	v_min_i32_e32 v187, v10, v4
	v_max_i32_e32 v188, v8, v7
	v_min_i32_e32 v189, v8, v7
	v_max_i32_e32 v190, v11, v1
	v_min_i32_e32 v191, v11, v1
	v_max_i32_e32 v192, v12, v0
	v_min_i32_e32 v193, v12, v0
	v_max_i32_e32 v197, v15, v2
	v_min_i32_e32 v198, v15, v2
	s_waitcnt vmcnt(7)
; #define P6_LOADKF(BUF, STEP) do { const bf16* skb_ = SK + (size_t)(h * 2 + ((STEP) >> 2)) * 128 * 128 + (size_t)ql * 128 + 8 * hh + (size_t)((STEP) & 3) * 32 * 128; \
;             _Pragma("unroll") for (int ks_ = 0; ks_ < 8; ++ks_) kfa[BUF][ks_] = *(const bf16x8*)(skb_ + 16 * ks_); } while (0)
; template <bool FROM_LDS>
; __device__ __forceinline__ void p6_task(unsigned char* ws, int lane, int h, int tok, const bf16* qrow_g, const LAS unsigned char* qrow_l, int rsw, LAS unsigned char* scr) {
;     ...
;             for (int kt = 0; kt < 4; ++kt) { f32x16 s = (f32x16){};
;                 const int step = 4 * p + kt;
; #pragma unroll
;                 for (int ks = 0; ks < 8; ++ks) s = __builtin_amdgcn_mfma_f32_32x32x16_bf16(kfa[0][ks], qf[ks], s, 0, 0, 0);
;                 __builtin_amdgcn_sched_barrier(0);
;                 if (step + 1 < 8) { P6_LOADKF(0, step + 1); }
;                 __builtin_amdgcn_sched_barrier(0);
;                 int g[16];
; #pragma unroll
;                 for (int reg = 0; reg < 16; ++reg) { const int n = 32 * kt + (reg & 3) + 8 * (reg >> 2) + 4 * hh; g[reg] = (f2key(s[reg]) & ~127) | n; }
;                 p6_sort16(g);
;                 if (kt == 0) {
; #pragma unroll
;                     for (int i = 0; i < 16; ++i) g0[i] = g[i];
;                 } else if (kt == 1) p6_top16(g0, g);
;                 else if (kt == 2) {
; #pragma unroll
;                     for (int i = 0; i < 16; ++i) g1[i] = g[i];
;                 } else p6_top16(g1, g);
	v_mfma_f32_32x32x16_bf16 v[0:15], v[178:181], v[20:23], 0
	v_max_i32_e32 v199, v89, v157
	v_min_i32_e32 v20, v89, v157
	v_max_i32_e32 v21, v154, v187
	v_min_i32_e32 v22, v154, v187
	v_max_i32_e32 v23, v88, v186
	v_min_i32_e32 v88, v88, v186
	v_max_i32_e32 v89, v155, v189
	s_waitcnt vmcnt(6)
	v_mfma_f32_32x32x16_bf16 v[0:15], v[182:185], v[16:19], v[0:15]
	v_min_i32_e32 v154, v155, v189
	v_max_i32_e32 v16, v156, v188
	v_min_i32_e32 v17, v156, v188
	v_max_i32_e32 v18, v190, v21
	v_min_i32_e32 v19, v190, v21
	v_max_i32_e32 v21, v192, v23
	v_min_i32_e32 v23, v192, v23
	s_waitcnt vmcnt(5)
	v_mfma_f32_32x32x16_bf16 v[0:15], v[68:71], v[44:47], v[0:15]
	v_max_i32_e32 v155, v197, v89
	v_min_i32_e32 v44, v197, v89
	v_max_i32_e32 v45, v199, v16
	v_min_i32_e32 v16, v199, v16
	v_max_i32_e32 v46, v191, v22
	v_min_i32_e32 v22, v191, v22
	v_max_i32_e32 v47, v193, v88
	s_waitcnt vmcnt(4)
	v_mfma_f32_32x32x16_bf16 v[0:15], v[64:67], v[32:35], v[0:15]
	v_min_i32_e32 v68, v193, v88
	v_max_i32_e32 v32, v198, v154
	v_min_i32_e32 v33, v198, v154
	v_max_i32_e32 v34, v20, v17
	v_min_i32_e32 v17, v20, v17
	v_max_i32_e32 v20, v18, v155
	v_min_i32_e32 v66, v18, v155
	s_waitcnt vmcnt(3)
	v_mfma_f32_32x32x16_bf16 v[0:15], v[60:63], v[40:43], v[0:15]
	v_max_i32_e32 v67, v21, v45
	v_min_i32_e32 v21, v21, v45
	v_max_i32_e32 v60, v19, v44
	v_min_i32_e32 v61, v19, v44
	v_max_i32_e32 v62, v23, v16
	v_min_i32_e32 v23, v23, v16
	v_max_i32_e32 v63, v46, v32
	s_waitcnt vmcnt(2)
	v_mfma_f32_32x32x16_bf16 v[0:15], v[56:59], v[28:31], v[0:15]
	v_min_i32_e32 v69, v46, v32
	v_max_i32_e32 v28, v47, v34
	v_min_i32_e32 v29, v47, v34
	v_max_i32_e32 v30, v22, v33
	v_min_i32_e32 v22, v22, v33
	v_max_i32_e32 v31, v68, v17
	v_min_i32_e32 v68, v68, v17
	s_waitcnt vmcnt(1)
	v_mfma_f32_32x32x16_bf16 v[0:15], v[52:55], v[36:39], v[0:15]
	v_min_i32_e32 v70, v20, v67
	v_min_i32_e32 v71, v66, v21
	v_min_i32_e32 v88, v60, v62
	v_min_i32_e32 v89, v61, v23
	v_min_i32_e32 v154, v63, v28
	v_min_i32_e32 v155, v69, v29
	v_min_i32_e32 v156, v30, v31
	v_min_i32_e32 v157, v22, v68
	s_waitcnt vmcnt(0)
	v_mfma_f32_32x32x16_bf16 v[0:15], v[48:51], v[24:27], v[0:15]
	s_or_b32 s2, s0, 1
	s_ashr_i32 s3, s2, 31
	s_lshl_b64 s[2:3], s[2:3], 15
	v_lshl_add_u64 v[64:65], v[86:87], 0, s[2:3]
	global_load_dwordx4 v[16:19], v[64:65], off
	global_load_dwordx4 v[56:59], v[64:65], off offset:32
	global_load_dwordx4 v[52:55], v[64:65], off offset:64
	global_load_dwordx4 v[48:51], v[64:65], off offset:96
	global_load_dwordx4 v[44:47], v[64:65], off offset:128
	global_load_dwordx4 v[40:43], v[64:65], off offset:160
	global_load_dwordx4 v[36:39], v[64:65], off offset:192
	global_load_dwordx4 v[32:35], v[64:65], off offset:224
	v_ashrrev_i32_e32 v24, 31, v0
	v_ashrrev_i32_e32 v25, 31, v3
	v_ashrrev_i32_e32 v27, 31, v7
	v_ashrrev_i32_e32 v86, 31, v4
	v_ashrrev_i32_e32 v198, 31, v15
	v_ashrrev_i32_e32 v199, 31, v12
	v_ashrrev_i32_e32 v201, 31, v8
	v_ashrrev_i32_e32 v202, 31, v11
	v_add_u32_e32 v193, 0x60, v100
	v_add_u32_e32 v191, 0x63, v100
	v_add_u32_e32 v187, 0x68, v100
	v_add_u32_e32 v189, 0x6b, v100
	v_add_u32_e32 v181, 0x70, v100
	v_add_u32_e32 v179, 0x73, v100
	v_add_u32_e32 v183, 0x78, v100
	v_add_u32_e32 v185, 0x7b, v100
	v_and_b32_e32 v24, 0x7fffff80, v24
	v_and_b32_e32 v0, 0xffffff80, v0
	v_and_b32_e32 v25, 0x7fffff80, v25
	v_and_b32_e32 v3, 0xffffff80, v3
	v_and_b32_e32 v27, 0x7fffff80, v27
	v_and_b32_e32 v7, 0xffffff80, v7
	v_and_b32_e32 v86, 0x7fffff80, v86
	v_and_b32_e32 v4, 0xffffff80, v4
	v_and_b32_e32 v198, 0x7fffff80, v198
	v_and_b32_e32 v15, 0xffffff80, v15
	v_and_b32_e32 v199, 0x7fffff80, v199
	v_and_b32_e32 v12, 0xffffff80, v12
	v_and_b32_e32 v201, 0x7fffff80, v201
	v_and_b32_e32 v8, 0xffffff80, v8
	v_and_b32_e32 v202, 0x7fffff80, v202
	v_and_b32_e32 v11, 0xffffff80, v11
	v_bitop3_b32 v0, v24, v193, v0 bitop3:0xde
	v_ashrrev_i32_e32 v24, 31, v1
	v_bitop3_b32 v3, v25, v191, v3 bitop3:0xde
	v_ashrrev_i32_e32 v25, 31, v2
	v_bitop3_b32 v7, v27, v189, v7 bitop3:0xde
	v_ashrrev_i32_e32 v27, 31, v6
	v_bitop3_b32 v4, v86, v187, v4 bitop3:0xde
	v_ashrrev_i32_e32 v86, 31, v5
	v_bitop3_b32 v15, v198, v185, v15 bitop3:0xde
	v_ashrrev_i32_e32 v198, 31, v14
	v_bitop3_b32 v12, v199, v183, v12 bitop3:0xde
	v_ashrrev_i32_e32 v199, 31, v13
	v_bitop3_b32 v8, v201, v181, v8 bitop3:0xde
	v_ashrrev_i32_e32 v201, 31, v9
	v_bitop3_b32 v11, v202, v179, v11 bitop3:0xde
	v_ashrrev_i32_e32 v202, 31, v10
	v_add_u32_e32 v192, 0x61, v100
	v_add_u32_e32 v190, 0x62, v100
	v_add_u32_e32 v186, 0x69, v100
	v_add_u32_e32 v188, 0x6a, v100
	v_add_u32_e32 v180, 0x71, v100
	v_add_u32_e32 v178, 0x72, v100
	v_add_u32_e32 v182, 0x79, v100
	v_add_u32_e32 v184, 0x7a, v100
	v_and_b32_e32 v24, 0x7fffff80, v24
	v_and_b32_e32 v1, 0xffffff80, v1
	v_and_b32_e32 v25, 0x7fffff80, v25
	v_and_b32_e32 v2, 0xffffff80, v2
	v_and_b32_e32 v27, 0x7fffff80, v27
	v_and_b32_e32 v6, 0xffffff80, v6
	v_and_b32_e32 v86, 0x7fffff80, v86
	v_and_b32_e32 v5, 0xffffff80, v5
	v_and_b32_e32 v198, 0x7fffff80, v198
	v_and_b32_e32 v14, 0xffffff80, v14
	v_and_b32_e32 v199, 0x7fffff80, v199
	v_and_b32_e32 v13, 0xffffff80, v13
	v_and_b32_e32 v201, 0x7fffff80, v201
	v_and_b32_e32 v9, 0xffffff80, v9
	v_and_b32_e32 v202, 0x7fffff80, v202
	v_and_b32_e32 v10, 0xffffff80, v10
	v_bitop3_b32 v1, v24, v192, v1 bitop3:0xde
	v_bitop3_b32 v2, v25, v190, v2 bitop3:0xde
	v_bitop3_b32 v6, v27, v188, v6 bitop3:0xde
	v_bitop3_b32 v5, v86, v186, v5 bitop3:0xde
	v_bitop3_b32 v14, v198, v184, v14 bitop3:0xde
	v_bitop3_b32 v13, v199, v182, v13 bitop3:0xde
	v_bitop3_b32 v9, v201, v180, v9 bitop3:0xde
	v_bitop3_b32 v10, v202, v178, v10 bitop3:0xde
	v_max_i32_e32 v24, v0, v1
	v_min_i32_e32 v25, v3, v2
; template <bool FROM_LDS>
; __device__ __forceinline__ void p6_task(unsigned char* ws, int lane, int h, int tok, const bf16* qrow_g, const LAS unsigned char* qrow_l, int rsw, LAS unsigned char* scr) {
;     ...
;                 for (int reg = 0; reg < 16; ++reg) { const int n = 32 * kt + (reg & 3) + 8 * (reg >> 2) + 4 * hh; g[reg] = (f2key(s[reg]) & ~127) | n; }
;                 p6_sort16(g);
;                 if (kt == 0) {
; #pragma unroll
;                     for (int i = 0; i < 16; ++i) g0[i] = g[i];
;                 } else if (kt == 1) p6_top16(g0, g);
;                 else if (kt == 2) {
; #pragma unroll
;                     for (int i = 0; i < 16; ++i) g1[i] = g[i];
;                 } else p6_top16(g1, g);
;             }
;             p6_top16(g0, g1);
	v_min_i32_e32 v0, v0, v1
	v_max_i32_e32 v1, v3, v2
	v_max_i32_e32 v27, v7, v6
	v_min_i32_e32 v86, v4, v5
	v_min_i32_e32 v6, v7, v6
	v_max_i32_e32 v4, v4, v5
	v_max_i32_e32 v198, v15, v14
	v_min_i32_e32 v199, v12, v13
	v_min_i32_e32 v14, v15, v14
	v_max_i32_e32 v12, v12, v13
	v_max_i32_e32 v201, v8, v9
	v_min_i32_e32 v202, v11, v10
	v_min_i32_e32 v8, v8, v9
	v_max_i32_e32 v9, v11, v10
	v_max_i32_e32 v26, v24, v25
	v_max_i32_e32 v2, v0, v1
	v_min_i32_e32 v87, v27, v86
	v_min_i32_e32 v5, v6, v4
	v_min_i32_e32 v24, v24, v25
	v_min_i32_e32 v0, v0, v1
	v_max_i32_e32 v25, v27, v86
	v_max_i32_e32 v4, v6, v4
	v_max_i32_e32 v200, v198, v199
	v_max_i32_e32 v13, v14, v12
	v_min_i32_e32 v203, v201, v202
	v_min_i32_e32 v10, v8, v9
	v_min_i32_e32 v198, v198, v199
	v_min_i32_e32 v12, v14, v12
	v_max_i32_e32 v199, v201, v202
	v_max_i32_e32 v8, v8, v9
	v_max_i32_e32 v3, v26, v2
	v_min_i32_e32 v7, v87, v5
	v_max_i32_e32 v1, v24, v0
	v_min_i32_e32 v6, v25, v4
	v_min_i32_e32 v2, v26, v2
	v_max_i32_e32 v5, v87, v5
	v_min_i32_e32 v0, v24, v0
	v_max_i32_e32 v4, v25, v4
	v_max_i32_e32 v15, v200, v13
	v_min_i32_e32 v11, v203, v10
	v_max_i32_e32 v14, v198, v12
	v_min_i32_e32 v9, v199, v8
	v_min_i32_e32 v13, v200, v13
	v_max_i32_e32 v10, v203, v10
	v_min_i32_e32 v12, v198, v12
	v_max_i32_e32 v8, v199, v8
	v_max_i32_e32 v197, v3, v7
	v_max_i32_e32 v27, v1, v6
	v_max_i32_e32 v26, v2, v5
	v_max_i32_e32 v24, v0, v4
	v_min_i32_e32 v204, v15, v11
	v_min_i32_e32 v201, v14, v9
	v_min_i32_e32 v200, v13, v10
	v_min_i32_e32 v198, v12, v8
	v_min_i32_e32 v3, v3, v7
	v_min_i32_e32 v1, v1, v6
	v_min_i32_e32 v2, v2, v5
	v_min_i32_e32 v0, v0, v4
	v_max_i32_e32 v7, v15, v11
	v_max_i32_e32 v9, v14, v9
	v_max_i32_e32 v10, v13, v10
	v_max_i32_e32 v8, v12, v8
	v_max_i32_e32 v86, v197, v27
	v_max_i32_e32 v25, v26, v24
	v_min_i32_e32 v202, v204, v201
	v_min_i32_e32 v199, v200, v198
	v_max_i32_e32 v6, v3, v1
	v_max_i32_e32 v4, v2, v0
	v_min_i32_e32 v11, v7, v9
	v_min_i32_e32 v12, v10, v8
	v_min_i32_e32 v27, v197, v27
	v_min_i32_e32 v24, v26, v24
	v_max_i32_e32 v197, v204, v201
	v_max_i32_e32 v198, v200, v198
	v_min_i32_e32 v1, v3, v1
	v_min_i32_e32 v0, v2, v0
	v_max_i32_e32 v3, v7, v9
	v_max_i32_e32 v7, v10, v8
	v_max_i32_e32 v87, v86, v25
	v_min_i32_e32 v203, v202, v199
	v_max_i32_e32 v5, v6, v4
	v_min_i32_e32 v13, v11, v12
	v_max_i32_e32 v26, v27, v24
	v_min_i32_e32 v200, v197, v198
	v_max_i32_e32 v2, v1, v0
	v_min_i32_e32 v8, v3, v7
	v_min_i32_e32 v25, v86, v25
	v_max_i32_e32 v86, v202, v199
	v_min_i32_e32 v4, v6, v4
	v_max_i32_e32 v6, v11, v12
	v_min_i32_e32 v24, v27, v24
	v_max_i32_e32 v27, v197, v198
	v_min_i32_e32 v0, v1, v0
	v_max_i32_e32 v1, v3, v7
	v_min_i32_e32 v205, v87, v203
	v_min_i32_e32 v14, v5, v13
	v_min_i32_e32 v201, v26, v200
	v_min_i32_e32 v9, v2, v8
	v_min_i32_e32 v199, v25, v86
	v_min_i32_e32 v11, v4, v6
	v_min_i32_e32 v197, v24, v27
	v_min_i32_e32 v3, v0, v1
	v_min_i32_e32 v15, v205, v14
	v_min_i32_e32 v10, v201, v9
	v_min_i32_e32 v12, v199, v11
	v_min_i32_e32 v7, v197, v3
	v_min_i32_e32 v204, v15, v10
	v_min_i32_e32 v198, v12, v7
	v_min_i32_e32 v202, v204, v198
	v_max3_i32 v20, v20, v67, v202
	v_max_i32_e32 v67, v87, v203
	v_max_i32_e32 v5, v5, v13
	v_max_i32_e32 v26, v26, v200
	v_max_i32_e32 v2, v2, v8
	v_max_i32_e32 v25, v25, v86
	v_max_i32_e32 v4, v4, v6
	v_max_i32_e32 v24, v24, v27
	v_max_i32_e32 v0, v0, v1
	v_min_i32_e32 v13, v67, v5
	v_min_i32_e32 v8, v26, v2
	v_min_i32_e32 v6, v25, v4
	v_min_i32_e32 v1, v24, v0
	v_min_i32_e32 v87, v13, v8
	v_min_i32_e32 v27, v6, v1
	v_min_i32_e32 v86, v87, v27
	v_max_i32_e32 v14, v205, v14
	v_max_i32_e32 v9, v201, v9
	v_max_i32_e32 v11, v199, v11
	v_max_i32_e32 v3, v197, v3
	v_max_i32_e32 v5, v67, v5
	v_max_i32_e32 v2, v26, v2
	v_max_i32_e32 v4, v25, v4
	v_max_i32_e32 v0, v24, v0
	v_max3_i32 v28, v63, v28, v86
	v_min_i32_e32 v86, v14, v9
	v_min_i32_e32 v197, v11, v3
	v_min_i32_e32 v26, v5, v2
	v_min_i32_e32 v24, v4, v0
	v_max_i32_e32 v10, v15, v10
	v_max_i32_e32 v7, v12, v7
	v_max_i32_e32 v8, v13, v8
	v_max_i32_e32 v1, v6, v1
	v_max_i32_e32 v9, v14, v9
	v_max_i32_e32 v3, v11, v3
	v_max_i32_e32 v2, v5, v2
	v_max_i32_e32 v0, v4, v0
	v_min_i32_e32 v199, v86, v197
	v_min_i32_e32 v25, v26, v24
	v_min_i32_e32 v12, v10, v7
	v_min_i32_e32 v6, v8, v1
	v_min_i32_e32 v11, v9, v3
	v_min_i32_e32 v4, v2, v0
	v_max3_i32 v60, v60, v62, v199
	v_max3_i32 v25, v30, v31, v25
	v_max3_i32 v12, v66, v21, v12
	v_max3_i32 v6, v69, v29, v6
	v_max3_i32 v11, v61, v23, v11
	v_max3_i32 v4, v22, v68, v4
	v_max3_i32 v21, v70, v204, v198
	v_max3_i32 v22, v154, v87, v27
	v_max3_i32 v27, v88, v86, v197
	v_max3_i32 v24, v156, v26, v24
	v_max3_i32 v7, v71, v10, v7
	v_max3_i32 v1, v155, v8, v1
	v_max3_i32 v3, v89, v9, v3
	v_max3_i32 v0, v157, v2, v0
	v_min_i32_e32 v63, v20, v28
	v_min_i32_e32 v30, v60, v25
	v_min_i32_e32 v13, v12, v6
	v_min_i32_e32 v5, v11, v4
	v_min_i32_e32 v23, v21, v22
	v_min_i32_e32 v26, v27, v24
	v_min_i32_e32 v8, v7, v1
	v_min_i32_e32 v2, v3, v0
	v_max_i32_e32 v20, v20, v28
	v_max_i32_e32 v25, v60, v25
	v_max_i32_e32 v6, v12, v6
	v_max_i32_e32 v4, v11, v4
	v_max_i32_e32 v21, v21, v22
	v_max_i32_e32 v22, v27, v24
	v_max_i32_e32 v1, v7, v1
	v_max_i32_e32 v0, v3, v0
	v_min_i32_e32 v31, v63, v30
	v_min_i32_e32 v14, v13, v5
	v_min_i32_e32 v29, v23, v26
	v_min_i32_e32 v9, v8, v2
	v_max_i32_e32 v30, v63, v30
	v_max_i32_e32 v5, v13, v5
	v_max_i32_e32 v23, v23, v26
	v_max_i32_e32 v2, v8, v2
	v_min_i32_e32 v28, v20, v25
	v_min_i32_e32 v11, v6, v4
	v_min_i32_e32 v24, v21, v22
	v_min_i32_e32 v3, v1, v0
	v_max_i32_e32 v20, v20, v25
	v_max_i32_e32 v4, v6, v4
	v_max_i32_e32 v21, v21, v22
	v_max_i32_e32 v0, v1, v0
	v_min_i32_e32 v15, v31, v14
; #define LAS __attribute__((address_space(3)))
; #define P6_LOADKF(BUF, STEP) do { const bf16* skb_ = SK + (size_t)(h * 2 + ((STEP) >> 2)) * 128 * 128 + (size_t)ql * 128 + 8 * hh + (size_t)((STEP) & 3) * 32 * 128; \
;             _Pragma("unroll") for (int ks_ = 0; ks_ < 8; ++ks_) kfa[BUF][ks_] = *(const bf16x8*)(skb_ + 16 * ks_); } while (0)
; template <bool FROM_LDS>
; __device__ __forceinline__ void p6_task(unsigned char* ws, int lane, int h, int tok, const bf16* qrow_g, const LAS unsigned char* qrow_l, int rsw, LAS unsigned char* scr) {
;     ...
;         for (int p = 0; p < 2; ++p) {
;             bf16x8 qf[8];
; #pragma unroll
;             for (int ks = 0; ks < 8; ++ks) qf[ks] = FROM_LDS ? *(const LAS bf16x8*)(qrow_l + (((16 * p + 2 * ks + hh) ^ rsw) << 4)) : *(const bf16x8*)(qrow_g + p * 128 + 8 * hh + 16 * ks);
;             int g0[16], g1[16];
; #pragma unroll
;             for (int kt = 0; kt < 4; ++kt) { f32x16 s = (f32x16){};
;                 const int step = 4 * p + kt;
; #pragma unroll
;                 for (int ks = 0; ks < 8; ++ks) s = __builtin_amdgcn_mfma_f32_32x32x16_bf16(kfa[0][ks], qf[ks], s, 0, 0, 0);
;                 __builtin_amdgcn_sched_barrier(0);
;                 if (step + 1 < 8) { P6_LOADKF(0, step + 1); }
;                 __builtin_amdgcn_sched_barrier(0);
;                 int g[16];
; #pragma unroll
;                 for (int reg = 0; reg < 16; ++reg) { const int n = 32 * kt + (reg & 3) + 8 * (reg >> 2) + 4 * hh; g[reg] = (f2key(s[reg]) & ~127) | n; }
;                 p6_sort16(g);
;                 if (kt == 0) {
; #pragma unroll
;                     for (int i = 0; i < 16; ++i) g0[i] = g[i];
;                 } else if (kt == 1) p6_top16(g0, g);
;                 else if (kt == 2) {
; #pragma unroll
;                     for (int i = 0; i < 16; ++i) g1[i] = g[i];
;                 } else p6_top16(g1, g);
;             }
;             p6_top16(g0, g1);
;             p6_top16_partner(g0);
	v_min_i32_e32 v10, v29, v9
	v_max_i32_e32 v14, v31, v14
	v_max_i32_e32 v9, v29, v9
	v_min_i32_e32 v13, v30, v5
	v_min_i32_e32 v8, v23, v2
	v_max_i32_e32 v5, v30, v5
	v_max_i32_e32 v2, v23, v2
	v_min_i32_e32 v12, v28, v11
	v_min_i32_e32 v7, v24, v3
	v_max_i32_e32 v11, v28, v11
	v_max_i32_e32 v3, v24, v3
	v_min_i32_e32 v6, v20, v4
	v_min_i32_e32 v1, v21, v0
	v_max_i32_e32 v4, v20, v4
	v_max_i32_e32 v0, v21, v0
	v_min_i32_e32 v61, v15, v10
	v_min_i32_e32 v29, v14, v9
	v_min_i32_e32 v26, v13, v8
	v_min_i32_e32 v23, v5, v2
	v_min_i32_e32 v27, v12, v7
	v_min_i32_e32 v24, v11, v3
	v_min_i32_e32 v22, v6, v1
	v_min_i32_e32 v20, v4, v0
	v_max3_i32 v21, v73, v76, v61
	v_max3_i32 v10, v194, v15, v10
	v_max3_i32 v15, v72, v79, v29
	v_max3_i32 v9, v196, v14, v9
	v_max3_i32 v14, v77, v125, v26
	v_max3_i32 v8, v195, v13, v8
	v_max3_i32 v13, v74, v123, v23
	v_max3_i32 v2, v135, v5, v2
	v_max3_i32 v5, v78, v129, v27
	v_max3_i32 v7, v134, v12, v7
	v_max3_i32 v12, v75, v127, v24
	v_max3_i32 v3, v133, v11, v3
	v_max3_i32 v11, v126, v130, v22
	v_max3_i32 v1, v132, v6, v1
	v_max3_i32 v6, v124, v128, v20
	v_max3_i32 v0, v131, v4, v0
	v_max_i32_e32 v4, v21, v5
	v_min_i32_e32 v5, v21, v5
	v_max_i32_e32 v20, v10, v7
	v_min_i32_e32 v7, v10, v7
	v_max_i32_e32 v10, v15, v12
	v_min_i32_e32 v12, v15, v12
	v_max_i32_e32 v15, v9, v3
	v_min_i32_e32 v3, v9, v3
	v_max_i32_e32 v9, v14, v11
	v_min_i32_e32 v11, v14, v11
	v_max_i32_e32 v14, v8, v1
	v_min_i32_e32 v1, v8, v1
	v_max_i32_e32 v8, v13, v6
	v_min_i32_e32 v6, v13, v6
	v_max_i32_e32 v13, v2, v0
	v_min_i32_e32 v0, v2, v0
	v_max_i32_e32 v2, v4, v9
	v_min_i32_e32 v4, v4, v9
	v_max_i32_e32 v9, v20, v14
	v_min_i32_e32 v14, v20, v14
	v_max_i32_e32 v20, v10, v8
	v_min_i32_e32 v8, v10, v8
	v_max_i32_e32 v10, v15, v13
	v_min_i32_e32 v13, v15, v13
	v_max_i32_e32 v15, v5, v11
	v_min_i32_e32 v5, v5, v11
	v_max_i32_e32 v11, v7, v1
	v_min_i32_e32 v1, v7, v1
	v_max_i32_e32 v7, v12, v6
	v_min_i32_e32 v6, v12, v6
	v_max_i32_e32 v12, v3, v0
	v_min_i32_e32 v0, v3, v0
	v_max_i32_e32 v3, v2, v20
	v_min_i32_e32 v2, v2, v20
	v_max_i32_e32 v20, v9, v10
	v_min_i32_e32 v9, v9, v10
	v_max_i32_e32 v10, v4, v8
	v_min_i32_e32 v4, v4, v8
	v_max_i32_e32 v8, v14, v13
	v_min_i32_e32 v13, v14, v13
	v_max_i32_e32 v14, v15, v7
	v_min_i32_e32 v7, v15, v7
	v_max_i32_e32 v15, v11, v12
	v_min_i32_e32 v11, v11, v12
	v_max_i32_e32 v12, v5, v6
	v_min_i32_e32 v5, v5, v6
	v_max_i32_e32 v6, v1, v0
	v_min_i32_e32 v0, v1, v0
	v_add_u32_e32 v1, 16, v84
	v_xor_b32_e32 v1, v1, v170
	v_lshl_add_u32 v1, v1, 4, v122
	ds_read_b128 v[194:197], v1
	v_max_i32_e32 v88, v5, v0
	v_min_i32_e32 v76, v5, v0
	v_add_u32_e32 v0, 24, v84
	v_xor_b32_e32 v0, v0, v170
	v_lshl_add_u32 v0, v0, 4, v122
	v_max_i32_e32 v71, v3, v20
	v_min_i32_e32 v67, v3, v20
	ds_read_b128 v[210:213], v0
	v_add_u32_e32 v1, 18, v84
	s_waitcnt vmcnt(7) lgkmcnt(1)
	v_mfma_f32_32x32x16_bf16 v[16:31], v[16:19], v[194:197], 0
	v_xor_b32_e32 v1, v1, v170
	v_lshl_add_u32 v1, v1, 4, v122
	ds_read_b128 v[198:201], v1
	v_add_u32_e32 v0, 26, v84
	v_xor_b32_e32 v0, v0, v170
	v_lshl_add_u32 v0, v0, 4, v122
	ds_read_b128 v[214:217], v0
	v_add_u32_e32 v1, 20, v84
	s_waitcnt vmcnt(6) lgkmcnt(1)
	v_mfma_f32_32x32x16_bf16 v[16:31], v[56:59], v[198:201], v[16:31]
	v_xor_b32_e32 v1, v1, v170
	v_lshl_add_u32 v1, v1, 4, v122
	ds_read_b128 v[202:205], v1
	v_add_u32_e32 v0, 28, v84
	v_xor_b32_e32 v0, v0, v170
	v_lshl_add_u32 v0, v0, 4, v122
	ds_read_b128 v[218:221], v0
	v_add_u32_e32 v1, 22, v84
	s_waitcnt vmcnt(5) lgkmcnt(1)
	v_mfma_f32_32x32x16_bf16 v[16:31], v[52:55], v[202:205], v[16:31]
	v_xor_b32_e32 v1, v1, v170
	v_lshl_add_u32 v1, v1, 4, v122
	ds_read_b128 v[206:209], v1
	v_add_u32_e32 v0, 30, v84
	v_xor_b32_e32 v0, v0, v170
	v_lshl_add_u32 v0, v0, 4, v122
	ds_read_b128 v[222:225], v0
	s_waitcnt vmcnt(4) lgkmcnt(1)
	v_mfma_f32_32x32x16_bf16 v[16:31], v[48:51], v[206:209], v[16:31]
	v_max_i32_e32 v69, v2, v9
	v_min_i32_e32 v66, v2, v9
	v_max_i32_e32 v72, v10, v8
	v_min_i32_e32 v68, v10, v8
	v_max_i32_e32 v70, v4, v13
	v_min_i32_e32 v73, v4, v13
	v_max_i32_e32 v79, v14, v15
	s_waitcnt vmcnt(3)
	v_mfma_f32_32x32x16_bf16 v[16:31], v[44:47], v[210:213], v[16:31]
	v_min_i32_e32 v75, v14, v15
	v_max_i32_e32 v77, v7, v11
	v_min_i32_e32 v74, v7, v11
	v_max_i32_e32 v86, v12, v6
	v_min_i32_e32 v78, v12, v6
	ds_bpermute_b32 v126, v83, v76
	ds_bpermute_b32 v87, v83, v88
	s_waitcnt vmcnt(2)
	v_mfma_f32_32x32x16_bf16 v[16:31], v[40:43], v[214:217], v[16:31]
	ds_bpermute_b32 v124, v83, v78
	ds_bpermute_b32 v89, v83, v86
	ds_bpermute_b32 v128, v83, v74
	ds_bpermute_b32 v125, v83, v77
	ds_bpermute_b32 v127, v83, v75
	ds_bpermute_b32 v123, v83, v79
	ds_bpermute_b32 v132, v83, v73
	s_waitcnt vmcnt(1)
	v_mfma_f32_32x32x16_bf16 v[16:31], v[36:39], v[218:221], v[16:31]
	ds_bpermute_b32 v130, v83, v70
	ds_bpermute_b32 v133, v83, v68
	ds_bpermute_b32 v122, v83, v72
	ds_bpermute_b32 v135, v83, v66
	ds_bpermute_b32 v131, v83, v69
	ds_bpermute_b32 v134, v83, v67
	ds_bpermute_b32 v129, v83, v71
	s_waitcnt vmcnt(0) lgkmcnt(14)
	v_mfma_f32_32x32x16_bf16 v[16:31], v[32:35], v[222:225], v[16:31]
	v_add_co_u32_e32 v4, vcc, s39, v64
	s_nop 1
	v_addc_co_u32_e32 v5, vcc, 0, v65, vcc
	global_load_dwordx4 v[0:3], v[4:5], off
	global_load_dwordx4 v[32:35], v[4:5], off offset:32
	global_load_dwordx4 v[36:39], v[4:5], off offset:64
	global_load_dwordx4 v[40:43], v[4:5], off offset:96
	global_load_dwordx4 v[44:47], v[4:5], off offset:128
	global_load_dwordx4 v[48:51], v[4:5], off offset:160
	global_load_dwordx4 v[52:55], v[4:5], off offset:192
	global_load_dwordx4 v[56:59], v[4:5], off offset:224
	s_waitcnt vmcnt(7)
	v_mfma_f32_32x32x16_bf16 v[0:15], v[0:3], v[194:197], 0
	s_waitcnt vmcnt(6)
; #define P6_LOADKF(BUF, STEP) do { const bf16* skb_ = SK + (size_t)(h * 2 + ((STEP) >> 2)) * 128 * 128 + (size_t)ql * 128 + 8 * hh + (size_t)((STEP) & 3) * 32 * 128; \
;             _Pragma("unroll") for (int ks_ = 0; ks_ < 8; ++ks_) kfa[BUF][ks_] = *(const bf16x8*)(skb_ + 16 * ks_); } while (0)
; template <bool FROM_LDS>
; __device__ __forceinline__ void p6_task(unsigned char* ws, int lane, int h, int tok, const bf16* qrow_g, const LAS unsigned char* qrow_l, int rsw, LAS unsigned char* scr) {
;     ...
;             for (int kt = 0; kt < 4; ++kt) { f32x16 s = (f32x16){};
;                 const int step = 4 * p + kt;
; #pragma unroll
;                 for (int ks = 0; ks < 8; ++ks) s = __builtin_amdgcn_mfma_f32_32x32x16_bf16(kfa[0][ks], qf[ks], s, 0, 0, 0);
;                 __builtin_amdgcn_sched_barrier(0);
;                 if (step + 1 < 8) { P6_LOADKF(0, step + 1); }
;                 __builtin_amdgcn_sched_barrier(0);
;                 int g[16];
; #pragma unroll
;                 for (int reg = 0; reg < 16; ++reg) { const int n = 32 * kt + (reg & 3) + 8 * (reg >> 2) + 4 * hh; g[reg] = (f2key(s[reg]) & ~127) | n; }
;                 p6_sort16(g);
	v_mfma_f32_32x32x16_bf16 v[0:15], v[32:35], v[198:201], v[0:15]
	s_waitcnt vmcnt(5)
	v_mfma_f32_32x32x16_bf16 v[0:15], v[36:39], v[202:205], v[0:15]
	s_waitcnt vmcnt(4)
	v_mfma_f32_32x32x16_bf16 v[0:15], v[40:43], v[206:209], v[0:15]
	s_waitcnt vmcnt(3)
	v_mfma_f32_32x32x16_bf16 v[0:15], v[44:47], v[210:213], v[0:15]
	s_waitcnt vmcnt(2)
	v_mfma_f32_32x32x16_bf16 v[0:15], v[48:51], v[214:217], v[0:15]
	s_waitcnt vmcnt(1)
	v_mfma_f32_32x32x16_bf16 v[0:15], v[52:55], v[218:221], v[0:15]
	s_waitcnt vmcnt(0)
	v_mfma_f32_32x32x16_bf16 v[0:15], v[56:59], v[222:225], v[0:15]
	v_add_co_u32_e32 v48, vcc, s46, v64
	s_nop 1
	v_addc_co_u32_e32 v49, vcc, 0, v65, vcc
	global_load_dwordx4 v[32:35], v[48:49], off
	global_load_dwordx4 v[36:39], v[48:49], off offset:32
	global_load_dwordx4 v[40:43], v[48:49], off offset:64
	global_load_dwordx4 v[44:47], v[48:49], off offset:96
	global_load_dwordx4 v[226:229], v[48:49], off offset:128
	global_load_dwordx4 v[232:235], v[48:49], off offset:160
	global_load_dwordx4 v[236:239], v[48:49], off offset:192
	global_load_dwordx4 v[240:243], v[48:49], off offset:224
	s_waitcnt vmcnt(7)
	v_mfma_f32_32x32x16_bf16 v[48:63], v[32:35], v[194:197], 0
	s_waitcnt vmcnt(6)
	v_mfma_f32_32x32x16_bf16 v[48:63], v[36:39], v[198:201], v[48:63]
	s_waitcnt vmcnt(5)
	v_mfma_f32_32x32x16_bf16 v[48:63], v[40:43], v[202:205], v[48:63]
	s_waitcnt vmcnt(4)
	v_mfma_f32_32x32x16_bf16 v[48:63], v[44:47], v[206:209], v[48:63]
	s_waitcnt vmcnt(3)
	v_mfma_f32_32x32x16_bf16 v[48:63], v[226:229], v[210:213], v[48:63]
	s_waitcnt vmcnt(2)
	v_mfma_f32_32x32x16_bf16 v[48:63], v[232:235], v[214:217], v[48:63]
	s_waitcnt vmcnt(1)
	v_mfma_f32_32x32x16_bf16 v[48:63], v[236:239], v[218:221], v[48:63]
	s_waitcnt vmcnt(0)
	v_mfma_f32_32x32x16_bf16 v[48:63], v[240:243], v[222:225], v[48:63]
	v_add_co_u32_e32 v36, vcc, s47, v64
	s_nop 1
	v_addc_co_u32_e32 v37, vcc, 0, v65, vcc
	global_load_dwordx4 v[32:35], v[36:37], off
	global_load_dwordx4 v[226:229], v[36:37], off offset:32
	global_load_dwordx4 v[232:235], v[36:37], off offset:64
	global_load_dwordx4 v[236:239], v[36:37], off offset:96
	global_load_dwordx4 v[240:243], v[36:37], off offset:128
	global_load_dwordx4 v[244:247], v[36:37], off offset:160
	global_load_dwordx4 v[248:251], v[36:37], off offset:192
	global_load_dwordx4 v[154:157], v[36:37], off offset:224
	s_waitcnt vmcnt(7)
	v_mfma_f32_32x32x16_bf16 v[32:47], v[32:35], v[194:197], 0
	s_waitcnt vmcnt(6)
	v_mfma_f32_32x32x16_bf16 v[32:47], v[226:229], v[198:201], v[32:47]
	s_waitcnt vmcnt(5)
	v_mfma_f32_32x32x16_bf16 v[32:47], v[232:235], v[202:205], v[32:47]
	s_waitcnt vmcnt(4)
	v_mfma_f32_32x32x16_bf16 v[32:47], v[236:239], v[206:209], v[32:47]
	s_waitcnt vmcnt(3)
	v_mfma_f32_32x32x16_bf16 v[32:47], v[240:243], v[210:213], v[32:47]
	s_waitcnt vmcnt(2)
	v_mfma_f32_32x32x16_bf16 v[32:47], v[244:247], v[214:217], v[32:47]
	s_waitcnt vmcnt(1)
	v_mfma_f32_32x32x16_bf16 v[32:47], v[248:251], v[218:221], v[32:47]
	s_waitcnt vmcnt(0)
	v_mfma_f32_32x32x16_bf16 v[32:47], v[154:157], v[222:225], v[32:47]
	v_ashrrev_i32_e32 v157, 31, v60
	v_and_b32_e32 v157, 0x7fffff80, v157
	v_and_b32_e32 v60, 0xffffff80, v60
	v_bitop3_b32 v60, v157, v141, v60 bitop3:0xde
	v_ashrrev_i32_e32 v157, 31, v56
	v_and_b32_e32 v157, 0x7fffff80, v157
	v_and_b32_e32 v56, 0xffffff80, v56
	v_bitop3_b32 v56, v157, v137, v56 bitop3:0xde
	v_ashrrev_i32_e32 v137, 31, v57
	v_and_b32_e32 v137, 0x7fffff80, v137
	v_and_b32_e32 v57, 0xffffff80, v57
	v_ashrrev_i32_e32 v156, 31, v63
	v_bitop3_b32 v57, v137, v138, v57 bitop3:0xde
	v_ashrrev_i32_e32 v138, 31, v59
	v_and_b32_e32 v156, 0x7fffff80, v156
	v_and_b32_e32 v63, 0xffffff80, v63
	v_and_b32_e32 v138, 0x7fffff80, v138
	v_and_b32_e32 v59, 0xffffff80, v59
	v_bitop3_b32 v63, v156, v177, v63 bitop3:0xde
	v_ashrrev_i32_e32 v156, 31, v62
	v_ashrrev_i32_e32 v141, 31, v61
	v_bitop3_b32 v59, v138, v139, v59 bitop3:0xde
	v_ashrrev_i32_e32 v138, 31, v58
	v_and_b32_e32 v156, 0x7fffff80, v156
	v_and_b32_e32 v62, 0xffffff80, v62
	v_and_b32_e32 v141, 0x7fffff80, v141
	v_and_b32_e32 v61, 0xffffff80, v61
	v_and_b32_e32 v138, 0x7fffff80, v138
	v_and_b32_e32 v58, 0xffffff80, v58
	v_bitop3_b32 v62, v156, v174, v62 bitop3:0xde
	v_bitop3_b32 v61, v141, v143, v61 bitop3:0xde
	v_bitop3_b32 v58, v138, v136, v58 bitop3:0xde
	v_ashrrev_i32_e32 v177, 31, v44
	v_max_i32_e32 v156, v63, v62
	v_min_i32_e32 v141, v60, v61
	v_min_i32_e32 v62, v63, v62
	v_max_i32_e32 v60, v60, v61
	v_max_i32_e32 v137, v56, v57
	v_min_i32_e32 v136, v59, v58
	v_min_i32_e32 v56, v56, v57
	v_max_i32_e32 v57, v59, v58
	v_and_b32_e32 v177, 0x7fffff80, v177
	v_and_b32_e32 v44, 0xffffff80, v44
	v_ashrrev_i32_e32 v64, 31, v48
	v_ashrrev_i32_e32 v154, 31, v55
	v_max_i32_e32 v143, v156, v141
	v_max_i32_e32 v61, v62, v60
	v_min_i32_e32 v138, v137, v136
	v_min_i32_e32 v58, v56, v57
	v_min_i32_e32 v141, v156, v141
	v_min_i32_e32 v60, v62, v60
	v_max_i32_e32 v136, v137, v136
	v_max_i32_e32 v56, v56, v57
	v_bitop3_b32 v44, v177, v183, v44 bitop3:0xde
	v_ashrrev_i32_e32 v183, 31, v40
	v_and_b32_e32 v64, 0x7fffff80, v64
	v_and_b32_e32 v48, 0xffffff80, v48
	v_and_b32_e32 v154, 0x7fffff80, v154
	v_and_b32_e32 v55, 0xffffff80, v55
	v_max_i32_e32 v63, v143, v61
	v_min_i32_e32 v59, v138, v58
	v_max_i32_e32 v62, v141, v60
	v_min_i32_e32 v57, v136, v56
	v_min_i32_e32 v61, v143, v61
	v_max_i32_e32 v58, v138, v58
	v_min_i32_e32 v60, v141, v60
	v_max_i32_e32 v56, v136, v56
	v_and_b32_e32 v183, 0x7fffff80, v183
	v_and_b32_e32 v40, 0xffffff80, v40
	v_bitop3_b32 v48, v64, v171, v48 bitop3:0xde
	v_ashrrev_i32_e32 v64, 31, v49
	v_bitop3_b32 v55, v154, v176, v55 bitop3:0xde
	v_ashrrev_i32_e32 v154, 31, v54
	v_min_i32_e32 v139, v63, v59
; template <bool FROM_LDS>
; __device__ __forceinline__ void p6_task(unsigned char* ws, int lane, int h, int tok, const bf16* qrow_g, const LAS unsigned char* qrow_l, int rsw, LAS unsigned char* scr) {
;     ...
;                 int g[16];
; #pragma unroll
;                 for (int reg = 0; reg < 16; ++reg) { const int n = 32 * kt + (reg & 3) + 8 * (reg >> 2) + 4 * hh; g[reg] = (f2key(s[reg]) & ~127) | n; }
;                 p6_sort16(g);
;                 if (kt == 0) {
; #pragma unroll
;                     for (int i = 0; i < 16; ++i) g0[i] = g[i];
;                 } else if (kt == 1) p6_top16(g0, g);
;                 else if (kt == 2) {
; #pragma unroll
;                     for (int i = 0; i < 16; ++i) g1[i] = g[i];
;                 } else p6_top16(g1, g);
	v_min_i32_e32 v137, v62, v57
	v_min_i32_e32 v138, v61, v58
	v_min_i32_e32 v136, v60, v56
	v_bitop3_b32 v40, v183, v181, v40 bitop3:0xde
	v_ashrrev_i32_e32 v181, 31, v41
	v_and_b32_e32 v64, 0x7fffff80, v64
	v_and_b32_e32 v49, 0xffffff80, v49
	v_and_b32_e32 v154, 0x7fffff80, v154
	v_and_b32_e32 v54, 0xffffff80, v54
	v_min_i32_e32 v156, v139, v137
	v_min_i32_e32 v141, v138, v136
	v_and_b32_e32 v181, 0x7fffff80, v181
	v_and_b32_e32 v41, 0xffffff80, v41
	v_bitop3_b32 v49, v64, v172, v49 bitop3:0xde
	v_ashrrev_i32_e32 v65, 31, v51
	v_bitop3_b32 v54, v154, v173, v54 bitop3:0xde
	v_ashrrev_i32_e32 v155, 31, v52
	v_min_i32_e32 v143, v156, v141
	v_max_i32_e32 v141, v156, v141
	v_ashrrev_i32_e32 v156, 31, v32
	v_ashrrev_i32_e32 v170, 31, v35
	v_ashrrev_i32_e32 v172, 31, v39
	v_ashrrev_i32_e32 v173, 31, v36
	v_ashrrev_i32_e32 v176, 31, v47
	v_bitop3_b32 v41, v181, v180, v41 bitop3:0xde
	v_ashrrev_i32_e32 v181, 31, v43
	v_and_b32_e32 v65, 0x7fffff80, v65
	v_and_b32_e32 v51, 0xffffff80, v51
	v_and_b32_e32 v155, 0x7fffff80, v155
	v_and_b32_e32 v52, 0xffffff80, v52
	v_and_b32_e32 v156, 0x7fffff80, v156
	v_and_b32_e32 v32, 0xffffff80, v32
	v_and_b32_e32 v170, 0x7fffff80, v170
	v_and_b32_e32 v35, 0xffffff80, v35
	v_and_b32_e32 v172, 0x7fffff80, v172
	v_and_b32_e32 v39, 0xffffff80, v39
	v_and_b32_e32 v173, 0x7fffff80, v173
	v_and_b32_e32 v36, 0xffffff80, v36
	v_and_b32_e32 v176, 0x7fffff80, v176
	v_and_b32_e32 v47, 0xffffff80, v47
	v_and_b32_e32 v181, 0x7fffff80, v181
	v_and_b32_e32 v43, 0xffffff80, v43
	v_bitop3_b32 v51, v65, v175, v51 bitop3:0xde
	v_ashrrev_i32_e32 v65, 31, v50
	v_bitop3_b32 v52, v155, v140, v52 bitop3:0xde
	v_ashrrev_i32_e32 v140, 31, v53
	v_bitop3_b32 v32, v156, v193, v32 bitop3:0xde
	v_ashrrev_i32_e32 v156, 31, v33
	v_bitop3_b32 v35, v170, v191, v35 bitop3:0xde
	v_ashrrev_i32_e32 v170, 31, v34
	v_bitop3_b32 v39, v172, v189, v39 bitop3:0xde
	v_ashrrev_i32_e32 v172, 31, v38
	v_bitop3_b32 v36, v173, v187, v36 bitop3:0xde
	v_ashrrev_i32_e32 v173, 31, v37
	v_bitop3_b32 v47, v176, v185, v47 bitop3:0xde
	v_ashrrev_i32_e32 v176, 31, v46
	v_ashrrev_i32_e32 v177, 31, v45
	v_bitop3_b32 v43, v181, v179, v43 bitop3:0xde
	v_ashrrev_i32_e32 v179, 31, v42
	v_and_b32_e32 v65, 0x7fffff80, v65
	v_and_b32_e32 v50, 0xffffff80, v50
	v_and_b32_e32 v140, 0x7fffff80, v140
	v_and_b32_e32 v53, 0xffffff80, v53
	v_and_b32_e32 v156, 0x7fffff80, v156
	v_and_b32_e32 v33, 0xffffff80, v33
	v_and_b32_e32 v170, 0x7fffff80, v170
	v_and_b32_e32 v34, 0xffffff80, v34
	v_and_b32_e32 v172, 0x7fffff80, v172
	v_and_b32_e32 v38, 0xffffff80, v38
	v_and_b32_e32 v173, 0x7fffff80, v173
	v_and_b32_e32 v37, 0xffffff80, v37
	v_and_b32_e32 v176, 0x7fffff80, v176
	v_and_b32_e32 v46, 0xffffff80, v46
	v_and_b32_e32 v177, 0x7fffff80, v177
	v_and_b32_e32 v45, 0xffffff80, v45
	v_and_b32_e32 v179, 0x7fffff80, v179
	v_and_b32_e32 v42, 0xffffff80, v42
	v_bitop3_b32 v50, v65, v148, v50 bitop3:0xde
	v_bitop3_b32 v53, v140, v142, v53 bitop3:0xde
	v_bitop3_b32 v33, v156, v192, v33 bitop3:0xde
	v_bitop3_b32 v34, v170, v190, v34 bitop3:0xde
	v_bitop3_b32 v38, v172, v188, v38 bitop3:0xde
	v_bitop3_b32 v37, v173, v186, v37 bitop3:0xde
	v_bitop3_b32 v46, v176, v184, v46 bitop3:0xde
	v_bitop3_b32 v45, v177, v182, v45 bitop3:0xde
	v_bitop3_b32 v42, v179, v178, v42 bitop3:0xde
	v_max_i32_e32 v64, v48, v49
	v_min_i32_e32 v65, v51, v50
	v_min_i32_e32 v48, v48, v49
	v_max_i32_e32 v49, v51, v50
	v_max_i32_e32 v154, v55, v54
	v_min_i32_e32 v140, v52, v53
	v_min_i32_e32 v54, v55, v54
	v_max_i32_e32 v52, v52, v53
	v_max_i32_e32 v156, v32, v33
	v_min_i32_e32 v170, v35, v34
	v_min_i32_e32 v32, v32, v33
	v_max_i32_e32 v33, v35, v34
	v_max_i32_e32 v172, v39, v38
	v_min_i32_e32 v173, v36, v37
	v_min_i32_e32 v38, v39, v38
	v_max_i32_e32 v36, v36, v37
	v_max_i32_e32 v176, v47, v46
	v_min_i32_e32 v177, v44, v45
	v_min_i32_e32 v46, v47, v46
	v_max_i32_e32 v44, v44, v45
	v_max_i32_e32 v180, v40, v41
	v_min_i32_e32 v178, v43, v42
	v_min_i32_e32 v40, v40, v41
	v_max_i32_e32 v41, v43, v42
	v_max_i32_e32 v148, v64, v65
	v_max_i32_e32 v50, v48, v49
	v_min_i32_e32 v142, v154, v140
	v_min_i32_e32 v53, v54, v52
	v_min_i32_e32 v64, v64, v65
	v_min_i32_e32 v48, v48, v49
	v_max_i32_e32 v65, v154, v140
	v_max_i32_e32 v52, v54, v52
	v_max_i32_e32 v171, v156, v170
	v_max_i32_e32 v34, v32, v33
	v_min_i32_e32 v174, v172, v173
	v_min_i32_e32 v37, v38, v36
	v_min_i32_e32 v156, v156, v170
	v_min_i32_e32 v32, v32, v33
	v_max_i32_e32 v170, v172, v173
	v_max_i32_e32 v36, v38, v36
	v_max_i32_e32 v182, v176, v177
	v_max_i32_e32 v45, v46, v44
	v_min_i32_e32 v179, v180, v178
	v_min_i32_e32 v42, v40, v41
	v_min_i32_e32 v176, v176, v177
	v_min_i32_e32 v44, v46, v44
	v_max_i32_e32 v177, v180, v178
	v_max_i32_e32 v40, v40, v41
	v_max_i32_e32 v51, v148, v50
	v_min_i32_e32 v55, v142, v53
	v_max_i32_e32 v49, v64, v48
	v_min_i32_e32 v54, v65, v52
	v_min_i32_e32 v50, v148, v50
	v_max_i32_e32 v53, v142, v53
	v_min_i32_e32 v48, v64, v48
	v_max_i32_e32 v52, v65, v52
	v_max_i32_e32 v35, v171, v34
	v_min_i32_e32 v39, v174, v37
	v_max_i32_e32 v33, v156, v32
	v_min_i32_e32 v38, v170, v36
	v_min_i32_e32 v34, v171, v34
	v_max_i32_e32 v37, v174, v37
	v_min_i32_e32 v32, v156, v32
	v_max_i32_e32 v36, v170, v36
	v_max_i32_e32 v47, v182, v45
	v_min_i32_e32 v43, v179, v42
	v_max_i32_e32 v46, v176, v44
	v_min_i32_e32 v41, v177, v40
	v_min_i32_e32 v45, v182, v45
	v_max_i32_e32 v42, v179, v42
	v_min_i32_e32 v44, v176, v44
	v_max_i32_e32 v40, v177, v40
	v_max_i32_e32 v155, v51, v55
	v_max_i32_e32 v140, v49, v54
	v_max_i32_e32 v142, v50, v53
	v_max_i32_e32 v64, v48, v52
	v_max_i32_e32 v175, v35, v39
	v_max_i32_e32 v172, v33, v38
	v_max_i32_e32 v171, v34, v37
; template <bool FROM_LDS>
; __device__ __forceinline__ void p6_task(unsigned char* ws, int lane, int h, int tok, const bf16* qrow_g, const LAS unsigned char* qrow_l, int rsw, LAS unsigned char* scr) {
;     ...
;                 p6_sort16(g);
;                 if (kt == 0) {
; #pragma unroll
;                     for (int i = 0; i < 16; ++i) g0[i] = g[i];
;                 } else if (kt == 1) p6_top16(g0, g);
;                 else if (kt == 2) {
; #pragma unroll
;                     for (int i = 0; i < 16; ++i) g1[i] = g[i];
;                 } else p6_top16(g1, g);
;             }
;             p6_top16(g0, g1);
	v_max_i32_e32 v156, v32, v36
	v_min_i32_e32 v181, v47, v43
	v_min_i32_e32 v178, v46, v41
	v_min_i32_e32 v179, v45, v42
	v_min_i32_e32 v176, v44, v40
	v_min_i32_e32 v35, v35, v39
	v_min_i32_e32 v33, v33, v38
	v_min_i32_e32 v34, v34, v37
	v_min_i32_e32 v32, v32, v36
	v_max_i32_e32 v39, v47, v43
	v_max_i32_e32 v41, v46, v41
	v_max_i32_e32 v42, v45, v42
	v_max_i32_e32 v40, v44, v40
	v_max_i32_e32 v154, v155, v140
	v_max_i32_e32 v65, v142, v64
	v_min_i32_e32 v51, v51, v55
	v_min_i32_e32 v49, v49, v54
	v_min_i32_e32 v50, v50, v53
	v_min_i32_e32 v48, v48, v52
	v_max_i32_e32 v55, v63, v59
	v_max_i32_e32 v57, v62, v57
	v_max_i32_e32 v58, v61, v58
	v_max_i32_e32 v56, v60, v56
	v_max_i32_e32 v173, v175, v172
	v_max_i32_e32 v170, v171, v156
	v_min_i32_e32 v180, v181, v178
	v_min_i32_e32 v177, v179, v176
	v_max_i32_e32 v38, v35, v33
	v_max_i32_e32 v36, v34, v32
	v_min_i32_e32 v43, v39, v41
	v_min_i32_e32 v44, v42, v40
	v_min_i32_e32 v172, v175, v172
	v_min_i32_e32 v156, v171, v156
	v_max_i32_e32 v175, v181, v178
	v_max_i32_e32 v176, v179, v176
	v_min_i32_e32 v33, v35, v33
	v_min_i32_e32 v32, v34, v32
	v_max_i32_e32 v35, v39, v41
	v_max_i32_e32 v39, v42, v40
	v_max_i32_e32 v148, v154, v65
	v_max_i32_e32 v54, v51, v49
	v_max_i32_e32 v52, v50, v48
	v_min_i32_e32 v59, v55, v57
	v_min_i32_e32 v60, v58, v56
	v_min_i32_e32 v140, v155, v140
	v_min_i32_e32 v64, v142, v64
	v_max_i32_e32 v137, v139, v137
	v_max_i32_e32 v136, v138, v136
	v_min_i32_e32 v49, v51, v49
	v_min_i32_e32 v48, v50, v48
	v_max_i32_e32 v51, v55, v57
	v_max_i32_e32 v55, v58, v56
	v_min_i32_e32 v65, v154, v65
	v_max_i32_e32 v174, v173, v170
	v_min_i32_e32 v182, v180, v177
	v_max_i32_e32 v37, v38, v36
	v_min_i32_e32 v45, v43, v44
	v_max_i32_e32 v171, v172, v156
	v_min_i32_e32 v178, v175, v176
	v_max_i32_e32 v34, v33, v32
	v_min_i32_e32 v40, v35, v39
	v_min_i32_e32 v170, v173, v170
	v_max_i32_e32 v173, v180, v177
	v_min_i32_e32 v36, v38, v36
	v_max_i32_e32 v38, v43, v44
	v_min_i32_e32 v156, v172, v156
	v_max_i32_e32 v172, v175, v176
	v_min_i32_e32 v32, v33, v32
	v_max_i32_e32 v33, v35, v39
	v_max_i32_e32 v157, v148, v143
	v_max_i32_e32 v53, v54, v52
	v_min_i32_e32 v61, v59, v60
	v_max_i32_e32 v142, v140, v64
	v_min_i32_e32 v138, v137, v136
	v_max_i32_e32 v50, v49, v48
	v_min_i32_e32 v56, v51, v55
	v_max_i32_e32 v154, v65, v141
	v_min_i32_e32 v52, v54, v52
	v_max_i32_e32 v54, v59, v60
	v_min_i32_e32 v64, v140, v64
	v_max_i32_e32 v136, v137, v136
	v_min_i32_e32 v48, v49, v48
	v_max_i32_e32 v49, v51, v55
	v_min_i32_e32 v183, v174, v182
	v_min_i32_e32 v46, v37, v45
	v_min_i32_e32 v179, v171, v178
	v_min_i32_e32 v41, v34, v40
	v_min_i32_e32 v177, v170, v173
	v_min_i32_e32 v43, v36, v38
	v_min_i32_e32 v175, v156, v172
	v_min_i32_e32 v35, v32, v33
	v_min_i32_e32 v143, v148, v143
	v_min_i32_e32 v65, v65, v141
	v_max_i32_e32 v141, v174, v182
	v_max_i32_e32 v37, v37, v45
	v_max_i32_e32 v148, v171, v178
	v_max_i32_e32 v34, v34, v40
	v_max_i32_e32 v170, v170, v173
	v_max_i32_e32 v36, v36, v38
	v_max_i32_e32 v156, v156, v172
	v_max_i32_e32 v32, v32, v33
	v_max_i32_e32 v62, v53, v61
	v_max_i32_e32 v139, v142, v138
	v_max_i32_e32 v57, v50, v56
	v_max_i32_e32 v59, v52, v54
	v_max_i32_e32 v137, v64, v136
	v_max_i32_e32 v51, v48, v49
	v_min_i32_e32 v47, v183, v46
	v_min_i32_e32 v42, v179, v41
	v_min_i32_e32 v44, v177, v43
	v_min_i32_e32 v39, v175, v35
	v_min_i32_e32 v53, v53, v61
	v_min_i32_e32 v138, v142, v138
	v_min_i32_e32 v50, v50, v56
	v_min_i32_e32 v52, v52, v54
	v_min_i32_e32 v64, v64, v136
	v_min_i32_e32 v48, v48, v49
	v_min_i32_e32 v45, v141, v37
	v_min_i32_e32 v40, v148, v34
	v_min_i32_e32 v38, v170, v36
	v_min_i32_e32 v33, v156, v32
	v_max_i32_e32 v37, v141, v37
	v_max_i32_e32 v34, v148, v34
	v_max_i32_e32 v36, v170, v36
	v_max_i32_e32 v32, v156, v32
	v_max_i32_e32 v63, v157, v62
	v_max_i32_e32 v58, v139, v57
	v_max_i32_e32 v60, v154, v59
	v_max_i32_e32 v55, v137, v51
	v_min_i32_e32 v181, v47, v42
	v_min_i32_e32 v176, v44, v39
	v_max_i32_e32 v61, v143, v53
	v_max_i32_e32 v56, v138, v50
	v_max_i32_e32 v54, v65, v52
	v_max_i32_e32 v49, v64, v48
	v_min_i32_e32 v53, v143, v53
	v_min_i32_e32 v50, v138, v50
	v_min_i32_e32 v52, v65, v52
	v_min_i32_e32 v48, v64, v48
	v_min_i32_e32 v65, v37, v34
	v_min_i32_e32 v141, v36, v32
	v_max_i32_e32 v42, v47, v42
	v_max_i32_e32 v39, v44, v39
	v_max_i32_e32 v155, v63, v58
	v_max_i32_e32 v140, v60, v55
	v_max_i32_e32 v46, v183, v46
	v_max_i32_e32 v41, v179, v41
	v_max_i32_e32 v43, v177, v43
	v_max_i32_e32 v35, v175, v35
	v_max_i32_e32 v138, v53, v50
	v_max_i32_e32 v64, v52, v48
	v_min_i32_e32 v143, v65, v141
	v_min_i32_e32 v58, v63, v58
	v_min_i32_e32 v55, v60, v55
	v_min_i32_e32 v44, v42, v39
	v_max_i32_e32 v136, v54, v49
	v_min_i32_e32 v171, v45, v40
	v_min_i32_e32 v172, v38, v33
	v_min_i32_e32 v62, v157, v62
	v_min_i32_e32 v57, v139, v57
	v_min_i32_e32 v59, v154, v59
	v_min_i32_e32 v51, v137, v51
	v_min_i32_e32 v154, v46, v41
	v_min_i32_e32 v157, v43, v35
	v_max3_i32 v143, v138, v64, v143
	v_max3_i32 v44, v58, v55, v44
	v_min_i32_e32 v47, v61, v56
	v_min_i32_e32 v49, v54, v49
	v_max_i32_e32 v40, v45, v40
	v_max_i32_e32 v33, v38, v33
	v_max_i32_e32 v41, v46, v41
	v_max_i32_e32 v35, v43, v35
	v_min_i32_e32 v60, v138, v64
	v_min_i32_e32 v55, v58, v55
	v_ashrrev_i32_e32 v64, 31, v28
	v_max_i32_e32 v137, v59, v51
	v_min_i32_e32 v38, v40, v33
	v_min_i32_e32 v54, v62, v57
	v_min_i32_e32 v51, v59, v51
	v_min_i32_e32 v43, v41, v35
	v_max3_i32 v55, v55, v42, v39
	v_min_i32_e32 v39, v47, v49
	v_and_b32_e32 v64, 0x7fffff80, v64
	v_and_b32_e32 v28, 0xffffff80, v28
	v_max_i32_e32 v142, v61, v56
	v_max_i32_e32 v139, v62, v57
	v_max3_i32 v45, v47, v49, v38
	v_max3_i32 v46, v54, v51, v43
; template <bool FROM_LDS>
; __device__ __forceinline__ void p6_task(unsigned char* ws, int lane, int h, int tok, const bf16* qrow_g, const LAS unsigned char* qrow_l, int rsw, LAS unsigned char* scr) {
;     ...
;                 int g[16];
; #pragma unroll
;                 for (int reg = 0; reg < 16; ++reg) { const int n = 32 * kt + (reg & 3) + 8 * (reg >> 2) + 4 * hh; g[reg] = (f2key(s[reg]) & ~127) | n; }
;                 p6_sort16(g);
;                 if (kt == 0) {
; #pragma unroll
;                     for (int i = 0; i < 16; ++i) g0[i] = g[i];
;                 } else if (kt == 1) p6_top16(g0, g);
;                 else if (kt == 2) {
; #pragma unroll
;                     for (int i = 0; i < 16; ++i) g1[i] = g[i];
;                 } else p6_top16(g1, g);
;             }
;             p6_top16(g0, g1);
	v_min_i32_e32 v43, v53, v50
	v_min_i32_e32 v48, v52, v48
	v_max_i32_e32 v34, v37, v34
	v_max_i32_e32 v36, v36, v32
	v_max3_i32 v47, v39, v40, v33
	v_min_i32_e32 v33, v54, v51
	v_bitop3_b32 v28, v64, v95, v28 bitop3:0xde
	v_ashrrev_i32_e32 v64, 31, v29
	v_min_i32_e32 v180, v181, v176
	v_min_i32_e32 v173, v171, v172
	v_min_i32_e32 v175, v154, v157
	v_min_i32_e32 v32, v34, v36
	v_min_i32_e32 v53, v155, v140
	v_min_i32_e32 v56, v142, v136
	v_min_i32_e32 v59, v139, v137
	v_max3_i32 v49, v33, v41, v35
	v_min_i32_e32 v33, v43, v48
	v_and_b32_e32 v64, 0x7fffff80, v64
	v_and_b32_e32 v29, 0xffffff80, v29
	v_max3_i32 v180, v155, v140, v180
	v_max3_i32 v173, v142, v136, v173
	v_max3_i32 v175, v139, v137, v175
	v_max3_i32 v50, v43, v48, v32
	v_max3_i32 v53, v53, v181, v176
	v_max3_i32 v56, v56, v171, v172
	v_max3_i32 v59, v59, v154, v157
	v_max3_i32 v60, v60, v65, v141
	v_max3_i32 v48, v33, v34, v36
	v_bitop3_b32 v29, v64, v94, v29 bitop3:0xde
	v_ashrrev_i32_e32 v94, 31, v24
	v_min_i32_e32 v174, v180, v173
	v_min_i32_e32 v148, v175, v143
	v_min_i32_e32 v38, v44, v45
	v_min_i32_e32 v52, v46, v50
	v_min_i32_e32 v57, v53, v56
	v_min_i32_e32 v61, v59, v60
	v_min_i32_e32 v39, v55, v47
	v_min_i32_e32 v40, v49, v48
	v_and_b32_e32 v94, 0x7fffff80, v94
	v_and_b32_e32 v24, 0xffffff80, v24
	v_min_i32_e32 v37, v38, v52
	v_max_i32_e32 v41, v174, v148
	v_max_i32_e32 v43, v38, v52
	v_max_i32_e32 v51, v57, v61
	v_max_i32_e32 v52, v39, v40
	v_bitop3_b32 v24, v94, v93, v24 bitop3:0xde
	v_ashrrev_i32_e32 v93, 31, v25
	v_min_i32_e32 v62, v57, v61
	v_min_i32_e32 v35, v39, v40
	v_min_i32_e32 v38, v41, v43
	v_min_i32_e32 v39, v51, v52
	v_max_i32_e32 v40, v41, v43
	v_max_i32_e32 v41, v51, v52
	v_max_i32_e32 v51, v180, v173
	v_max_i32_e32 v52, v175, v143
	v_max_i32_e32 v57, v44, v45
	v_max_i32_e32 v50, v46, v50
	v_max_i32_e32 v53, v53, v56
	v_max_i32_e32 v56, v59, v60
	v_max_i32_e32 v55, v55, v47
	v_max_i32_e32 v59, v49, v48
	v_and_b32_e32 v93, 0x7fffff80, v93
	v_and_b32_e32 v25, 0xffffff80, v25
	v_min_i32_e32 v54, v51, v52
	v_min_i32_e32 v46, v57, v50
	v_min_i32_e32 v58, v53, v56
	v_min_i32_e32 v47, v55, v59
	v_max_i32_e32 v52, v51, v52
	v_max_i32_e32 v57, v57, v50
	v_max_i32_e32 v53, v53, v56
	v_max_i32_e32 v55, v55, v59
	v_ashrrev_i32_e32 v56, 31, v16
	v_ashrrev_i32_e32 v59, 31, v23
	v_ashrrev_i32_e32 v60, 31, v20
	v_ashrrev_i32_e32 v63, 31, v31
	v_bitop3_b32 v25, v93, v92, v25 bitop3:0xde
	v_ashrrev_i32_e32 v93, 31, v27
	v_min_i32_e32 v50, v52, v57
	v_max_i32_e32 v52, v52, v57
	v_and_b32_e32 v56, 0x7fffff80, v56
	v_and_b32_e32 v16, 0xffffff80, v16
	v_ashrrev_i32_e32 v57, 31, v19
	v_and_b32_e32 v19, 0xffffff80, v19
	v_and_b32_e32 v59, 0x7fffff80, v59
	v_and_b32_e32 v23, 0xffffff80, v23
	v_and_b32_e32 v60, 0x7fffff80, v60
	v_and_b32_e32 v20, 0xffffff80, v20
	v_and_b32_e32 v63, 0x7fffff80, v63
	v_and_b32_e32 v31, 0xffffff80, v31
	v_and_b32_e32 v93, 0x7fffff80, v93
	v_and_b32_e32 v27, 0xffffff80, v27
	v_bitop3_b32 v16, v56, v100, v16 bitop3:0xde
	v_ashrrev_i32_e32 v56, 31, v17
	v_and_b32_e32 v17, 0xffffff80, v17
	v_bitop3_b32 v19, v57, v19, s50 bitop3:0x6c
	v_ashrrev_i32_e32 v57, 31, v18
	v_and_b32_e32 v18, 0xffffff80, v18
	v_bitop3_b32 v23, v59, v102, v23 bitop3:0xde
	v_ashrrev_i32_e32 v59, 31, v22
	v_bitop3_b32 v20, v60, v99, v20 bitop3:0xde
	v_ashrrev_i32_e32 v60, 31, v21
	v_bitop3_b32 v31, v63, v97, v31 bitop3:0xde
	v_ashrrev_i32_e32 v63, 31, v30
	v_bitop3_b32 v27, v93, v91, v27 bitop3:0xde
	v_ashrrev_i32_e32 v91, 31, v26
	v_bitop3_b32 v17, v56, v17, s50 bitop3:0x6c
	v_bitop3_b32 v18, v57, v18, s50 bitop3:0x6c
	v_and_b32_e32 v59, 0x7fffff80, v59
	v_and_b32_e32 v22, 0xffffff80, v22
	v_and_b32_e32 v60, 0x7fffff80, v60
	v_and_b32_e32 v21, 0xffffff80, v21
	v_and_b32_e32 v63, 0x7fffff80, v63
	v_and_b32_e32 v30, 0xffffff80, v30
	v_and_b32_e32 v91, 0x7fffff80, v91
	v_and_b32_e32 v26, 0xffffff80, v26
	v_or_b32_e32 v17, v17, v105
	v_or_b32_e32 v19, v19, v104
	v_or_b32_e32 v18, v18, v103
	v_bitop3_b32 v22, v59, v101, v22 bitop3:0xde
	v_bitop3_b32 v21, v60, v98, v21 bitop3:0xde
	v_bitop3_b32 v30, v63, v96, v30 bitop3:0xde
	v_bitop3_b32 v26, v91, v85, v26 bitop3:0xde
	v_max_i32_e32 v56, v16, v17
	v_min_i32_e32 v57, v19, v18
	v_min_i32_e32 v16, v16, v17
	v_max_i32_e32 v17, v19, v18
	v_max_i32_e32 v59, v23, v22
	v_min_i32_e32 v60, v20, v21
	v_min_i32_e32 v22, v23, v22
	v_max_i32_e32 v20, v20, v21
	v_max_i32_e32 v63, v31, v30
	v_min_i32_e32 v64, v28, v29
	v_min_i32_e32 v30, v31, v30
	v_max_i32_e32 v28, v28, v29
	v_max_i32_e32 v92, v24, v25
	v_min_i32_e32 v85, v27, v26
	v_min_i32_e32 v24, v24, v25
	v_max_i32_e32 v25, v27, v26
	v_min_i32_e32 v45, v58, v47
	v_max_i32_e32 v47, v58, v47
	v_max_i32_e32 v58, v56, v57
	v_max_i32_e32 v18, v16, v17
	v_min_i32_e32 v61, v59, v60
	v_min_i32_e32 v21, v22, v20
	v_min_i32_e32 v56, v56, v57
	v_min_i32_e32 v16, v16, v17
	v_max_i32_e32 v57, v59, v60
	v_max_i32_e32 v20, v22, v20
	v_max_i32_e32 v65, v63, v64
	v_max_i32_e32 v29, v30, v28
	v_min_i32_e32 v91, v92, v85
	v_min_i32_e32 v26, v24, v25
	v_min_i32_e32 v63, v63, v64
	v_min_i32_e32 v28, v30, v28
	v_max_i32_e32 v64, v92, v85
	v_max_i32_e32 v24, v24, v25
	v_max_i32_e32 v19, v58, v18
	v_min_i32_e32 v23, v61, v21
	v_max_i32_e32 v17, v56, v16
	v_min_i32_e32 v22, v57, v20
	v_min_i32_e32 v18, v58, v18
	v_max_i32_e32 v21, v61, v21
	v_min_i32_e32 v16, v56, v16
	v_max_i32_e32 v20, v57, v20
	v_max_i32_e32 v31, v65, v29
	v_min_i32_e32 v27, v91, v26
	v_max_i32_e32 v30, v63, v28
	v_min_i32_e32 v25, v64, v24
	v_min_i32_e32 v29, v65, v29
	v_max_i32_e32 v26, v91, v26
	v_min_i32_e32 v28, v63, v28
	v_max_i32_e32 v24, v64, v24
	v_min_i32_e32 v33, v62, v35
	v_max_i32_e32 v35, v62, v35
	v_max_i32_e32 v62, v19, v23
; template <bool FROM_LDS>
; __device__ __forceinline__ void p6_task(unsigned char* ws, int lane, int h, int tok, const bf16* qrow_g, const LAS unsigned char* qrow_l, int rsw, LAS unsigned char* scr) {
;     ...
;                 int g[16];
; #pragma unroll
;                 for (int reg = 0; reg < 16; ++reg) { const int n = 32 * kt + (reg & 3) + 8 * (reg >> 2) + 4 * hh; g[reg] = (f2key(s[reg]) & ~127) | n; }
;                 p6_sort16(g);
;                 if (kt == 0) {
; #pragma unroll
;                     for (int i = 0; i < 16; ++i) g0[i] = g[i];
;                 } else if (kt == 1) p6_top16(g0, g);
;                 else if (kt == 2) {
; #pragma unroll
;                     for (int i = 0; i < 16; ++i) g1[i] = g[i];
;                 } else p6_top16(g1, g);
	v_max_i32_e32 v59, v17, v22
	v_max_i32_e32 v58, v18, v21
	v_max_i32_e32 v56, v16, v20
	v_min_i32_e32 v93, v31, v27
	v_min_i32_e32 v85, v30, v25
	v_min_i32_e32 v65, v29, v26
	v_min_i32_e32 v63, v28, v24
	v_max_i32_e32 v60, v62, v59
	v_max_i32_e32 v57, v58, v56
	v_min_i32_e32 v92, v93, v85
	v_min_i32_e32 v64, v65, v63
	v_max_i32_e32 v61, v60, v57
	v_min_i32_e32 v91, v92, v64
	v_min_i32_e32 v57, v60, v57
	v_max_i32_e32 v60, v92, v64
	v_ashrrev_i32_e32 v92, 31, v0
	v_ashrrev_i32_e32 v95, 31, v3
	v_ashrrev_i32_e32 v97, 31, v7
	v_ashrrev_i32_e32 v98, 31, v4
	v_ashrrev_i32_e32 v101, 31, v15
	v_ashrrev_i32_e32 v102, 31, v12
	v_ashrrev_i32_e32 v104, 31, v8
	v_ashrrev_i32_e32 v105, 31, v11
	v_and_b32_e32 v92, 0x7fffff80, v92
	v_and_b32_e32 v0, 0xffffff80, v0
	v_and_b32_e32 v95, 0x7fffff80, v95
	v_and_b32_e32 v3, 0xffffff80, v3
	v_and_b32_e32 v97, 0x7fffff80, v97
	v_and_b32_e32 v7, 0xffffff80, v7
	v_and_b32_e32 v98, 0x7fffff80, v98
	v_and_b32_e32 v4, 0xffffff80, v4
	v_and_b32_e32 v101, 0x7fffff80, v101
	v_and_b32_e32 v15, 0xffffff80, v15
	v_and_b32_e32 v102, 0x7fffff80, v102
	v_and_b32_e32 v12, 0xffffff80, v12
	v_and_b32_e32 v104, 0x7fffff80, v104
	v_and_b32_e32 v8, 0xffffff80, v8
	v_and_b32_e32 v105, 0x7fffff80, v105
	v_and_b32_e32 v11, 0xffffff80, v11
	v_bitop3_b32 v0, v92, v121, v0 bitop3:0xde
	v_ashrrev_i32_e32 v92, 31, v1
	v_bitop3_b32 v3, v95, v119, v3 bitop3:0xde
	v_ashrrev_i32_e32 v95, 31, v2
	v_bitop3_b32 v7, v97, v117, v7 bitop3:0xde
	v_ashrrev_i32_e32 v97, 31, v6
	v_bitop3_b32 v4, v98, v115, v4 bitop3:0xde
	v_ashrrev_i32_e32 v98, 31, v5
	v_bitop3_b32 v15, v101, v113, v15 bitop3:0xde
	v_ashrrev_i32_e32 v101, 31, v14
	v_bitop3_b32 v12, v102, v111, v12 bitop3:0xde
	v_ashrrev_i32_e32 v102, 31, v13
	v_bitop3_b32 v8, v104, v109, v8 bitop3:0xde
	v_ashrrev_i32_e32 v104, 31, v9
	v_bitop3_b32 v11, v105, v107, v11 bitop3:0xde
	v_ashrrev_i32_e32 v105, 31, v10
	v_and_b32_e32 v92, 0x7fffff80, v92
	v_and_b32_e32 v1, 0xffffff80, v1
	v_and_b32_e32 v95, 0x7fffff80, v95
	v_and_b32_e32 v2, 0xffffff80, v2
	v_and_b32_e32 v97, 0x7fffff80, v97
	v_and_b32_e32 v6, 0xffffff80, v6
	v_and_b32_e32 v98, 0x7fffff80, v98
	v_and_b32_e32 v5, 0xffffff80, v5
	v_and_b32_e32 v101, 0x7fffff80, v101
	v_and_b32_e32 v14, 0xffffff80, v14
	v_and_b32_e32 v102, 0x7fffff80, v102
	v_and_b32_e32 v13, 0xffffff80, v13
	v_and_b32_e32 v104, 0x7fffff80, v104
	v_and_b32_e32 v9, 0xffffff80, v9
	v_and_b32_e32 v105, 0x7fffff80, v105
	v_and_b32_e32 v10, 0xffffff80, v10
	v_bitop3_b32 v1, v92, v120, v1 bitop3:0xde
	v_bitop3_b32 v2, v95, v118, v2 bitop3:0xde
	v_bitop3_b32 v6, v97, v116, v6 bitop3:0xde
	v_bitop3_b32 v5, v98, v114, v5 bitop3:0xde
	v_bitop3_b32 v14, v101, v112, v14 bitop3:0xde
	v_bitop3_b32 v13, v102, v110, v13 bitop3:0xde
	v_bitop3_b32 v9, v104, v108, v9 bitop3:0xde
	v_bitop3_b32 v10, v105, v106, v10 bitop3:0xde
	v_max_i32_e32 v92, v0, v1
	v_min_i32_e32 v95, v3, v2
	v_min_i32_e32 v0, v0, v1
	v_max_i32_e32 v1, v3, v2
	v_max_i32_e32 v97, v7, v6
	v_min_i32_e32 v98, v4, v5
	v_min_i32_e32 v6, v7, v6
	v_max_i32_e32 v4, v4, v5
	v_max_i32_e32 v101, v15, v14
	v_min_i32_e32 v102, v12, v13
	v_min_i32_e32 v14, v15, v14
	v_max_i32_e32 v12, v12, v13
	v_max_i32_e32 v104, v8, v9
	v_min_i32_e32 v105, v11, v10
	v_min_i32_e32 v8, v8, v9
	v_max_i32_e32 v9, v11, v10
	v_max_i32_e32 v96, v92, v95
	v_max_i32_e32 v2, v0, v1
	v_min_i32_e32 v99, v97, v98
	v_min_i32_e32 v5, v6, v4
	v_min_i32_e32 v92, v92, v95
	v_min_i32_e32 v0, v0, v1
	v_max_i32_e32 v95, v97, v98
	v_max_i32_e32 v4, v6, v4
	v_max_i32_e32 v103, v101, v102
	v_max_i32_e32 v13, v14, v12
	v_min_i32_e32 v106, v104, v105
	v_min_i32_e32 v10, v8, v9
	v_min_i32_e32 v101, v101, v102
	v_min_i32_e32 v12, v14, v12
	v_max_i32_e32 v102, v104, v105
	v_max_i32_e32 v8, v8, v9
	v_max_i32_e32 v3, v96, v2
	v_min_i32_e32 v7, v99, v5
	v_max_i32_e32 v1, v92, v0
	v_min_i32_e32 v6, v95, v4
	v_min_i32_e32 v2, v96, v2
	v_max_i32_e32 v5, v99, v5
	v_min_i32_e32 v0, v92, v0
	v_max_i32_e32 v4, v95, v4
	v_max_i32_e32 v15, v103, v13
	v_min_i32_e32 v11, v106, v10
	v_max_i32_e32 v14, v101, v12
	v_min_i32_e32 v9, v102, v8
	v_min_i32_e32 v13, v103, v13
	v_max_i32_e32 v10, v106, v10
	v_min_i32_e32 v12, v101, v12
	v_max_i32_e32 v8, v102, v8
	v_max_i32_e32 v100, v3, v7
	v_max_i32_e32 v97, v1, v6
	v_max_i32_e32 v96, v2, v5
	v_max_i32_e32 v92, v0, v4
	v_min_i32_e32 v107, v15, v11
	v_min_i32_e32 v104, v14, v9
	v_min_i32_e32 v103, v13, v10
	v_min_i32_e32 v101, v12, v8
	v_min_i32_e32 v3, v3, v7
	v_min_i32_e32 v1, v1, v6
	v_min_i32_e32 v2, v2, v5
	v_min_i32_e32 v0, v0, v4
	v_max_i32_e32 v7, v15, v11
	v_max_i32_e32 v9, v14, v9
	v_max_i32_e32 v10, v13, v10
	v_max_i32_e32 v8, v12, v8
	v_min_i32_e32 v19, v19, v23
	v_min_i32_e32 v17, v17, v22
	v_min_i32_e32 v18, v18, v21
	v_min_i32_e32 v16, v16, v20
	v_max_i32_e32 v23, v31, v27
	v_max_i32_e32 v25, v30, v25
	v_max_i32_e32 v26, v29, v26
	v_max_i32_e32 v24, v28, v24
	v_max_i32_e32 v98, v100, v97
	v_max_i32_e32 v95, v96, v92
	v_min_i32_e32 v105, v107, v104
	v_min_i32_e32 v102, v103, v101
	v_max_i32_e32 v6, v3, v1
	v_max_i32_e32 v4, v2, v0
	v_min_i32_e32 v11, v7, v9
	v_min_i32_e32 v12, v10, v8
	v_min_i32_e32 v97, v100, v97
	v_min_i32_e32 v92, v96, v92
	v_max_i32_e32 v100, v107, v104
	v_max_i32_e32 v101, v103, v101
	v_min_i32_e32 v1, v3, v1
	v_min_i32_e32 v0, v2, v0
	v_max_i32_e32 v3, v7, v9
	v_max_i32_e32 v7, v10, v8
	v_max_i32_e32 v22, v19, v17
	v_max_i32_e32 v20, v18, v16
	v_min_i32_e32 v27, v23, v25
	v_min_i32_e32 v28, v26, v24
	v_min_i32_e32 v59, v62, v59
	v_min_i32_e32 v56, v58, v56
	v_max_i32_e32 v62, v93, v85
	v_max_i32_e32 v63, v65, v63
	v_min_i32_e32 v17, v19, v17
	v_min_i32_e32 v16, v18, v16
	v_max_i32_e32 v19, v23, v25
	v_max_i32_e32 v23, v26, v24
; __device__ __forceinline__ void p6_top16_partner(int (&a)[16]) {
;     int t[16];
; #pragma unroll
;     for (int i = 0; i < 16; ++i) t[i] = __shfl_xor(a[15 - i], 32);
; #pragma unroll
;     for (int i = 0; i < 16; ++i) a[i] = max(a[i], t[i]);
;     p6_merge16(a);
; }
; template <bool FROM_LDS>
; __device__ __forceinline__ void p6_task(unsigned char* ws, int lane, int h, int tok, const bf16* qrow_g, const LAS unsigned char* qrow_l, int rsw, LAS unsigned char* scr) {
;     ...
;                 p6_sort16(g);
;                 if (kt == 0) {
; #pragma unroll
;                     for (int i = 0; i < 16; ++i) g0[i] = g[i];
;                 } else if (kt == 1) p6_top16(g0, g);
;                 else if (kt == 2) {
; #pragma unroll
;                     for (int i = 0; i < 16; ++i) g1[i] = g[i];
;                 } else p6_top16(g1, g);
;             }
;             p6_top16(g0, g1);
;             p6_top16_partner(g0);
	v_max_i32_e32 v99, v98, v95
	v_min_i32_e32 v106, v105, v102
	v_max_i32_e32 v5, v6, v4
	v_min_i32_e32 v13, v11, v12
	v_max_i32_e32 v96, v97, v92
	v_min_i32_e32 v103, v100, v101
	v_max_i32_e32 v2, v1, v0
	v_min_i32_e32 v8, v3, v7
	v_min_i32_e32 v95, v98, v95
	v_max_i32_e32 v98, v105, v102
	v_min_i32_e32 v4, v6, v4
	v_max_i32_e32 v6, v11, v12
	v_min_i32_e32 v92, v97, v92
	v_max_i32_e32 v97, v100, v101
	v_min_i32_e32 v0, v1, v0
	v_max_i32_e32 v1, v3, v7
	v_max_i32_e32 v21, v22, v20
	v_min_i32_e32 v29, v27, v28
	v_max_i32_e32 v58, v59, v56
	v_min_i32_e32 v65, v62, v63
	v_max_i32_e32 v18, v17, v16
	v_min_i32_e32 v24, v19, v23
	v_min_i32_e32 v20, v22, v20
	v_max_i32_e32 v22, v27, v28
	v_min_i32_e32 v56, v59, v56
	v_max_i32_e32 v59, v62, v63
	v_min_i32_e32 v16, v17, v16
	v_max_i32_e32 v17, v19, v23
	v_min_i32_e32 v108, v99, v106
	v_min_i32_e32 v14, v5, v13
	v_min_i32_e32 v104, v96, v103
	v_min_i32_e32 v9, v2, v8
	v_min_i32_e32 v102, v95, v98
	v_min_i32_e32 v11, v4, v6
	v_min_i32_e32 v100, v92, v97
	v_min_i32_e32 v3, v0, v1
	v_max_i32_e32 v94, v61, v91
	v_max_i32_e32 v30, v21, v29
	v_max_i32_e32 v85, v58, v65
	v_max_i32_e32 v25, v18, v24
	v_max_i32_e32 v64, v57, v60
	v_max_i32_e32 v27, v20, v22
	v_max_i32_e32 v62, v56, v59
	v_max_i32_e32 v19, v16, v17
	v_min_i32_e32 v15, v108, v14
	v_min_i32_e32 v10, v104, v9
	v_min_i32_e32 v12, v102, v11
	v_min_i32_e32 v7, v100, v3
	v_max_i32_e32 v31, v94, v30
	v_max_i32_e32 v26, v85, v25
	v_max_i32_e32 v28, v64, v27
	v_max_i32_e32 v23, v62, v19
	v_min_i32_e32 v107, v15, v10
	v_min_i32_e32 v101, v12, v7
	v_min_i32_e32 v61, v61, v91
	v_min_i32_e32 v21, v21, v29
	v_min_i32_e32 v58, v58, v65
	v_min_i32_e32 v18, v18, v24
	v_min_i32_e32 v57, v57, v60
	v_min_i32_e32 v20, v20, v22
	v_min_i32_e32 v56, v56, v59
	v_min_i32_e32 v16, v16, v17
	v_max_i32_e32 v10, v15, v10
	v_max_i32_e32 v7, v12, v7
	v_max_i32_e32 v93, v31, v26
	v_max_i32_e32 v63, v28, v23
	v_max_i32_e32 v29, v61, v21
	v_max_i32_e32 v24, v58, v18
	v_max_i32_e32 v22, v57, v20
	v_max_i32_e32 v17, v56, v16
	v_max_i32_e32 v60, v99, v106
	v_max_i32_e32 v5, v5, v13
	v_max_i32_e32 v91, v96, v103
	v_max_i32_e32 v2, v2, v8
	v_max_i32_e32 v95, v95, v98
	v_max_i32_e32 v4, v4, v6
	v_max_i32_e32 v92, v92, v97
	v_max_i32_e32 v0, v0, v1
	v_min_i32_e32 v26, v31, v26
	v_min_i32_e32 v23, v28, v23
	v_min_i32_e32 v12, v10, v7
	v_max_i32_e32 v59, v22, v17
	v_min_i32_e32 v13, v60, v5
	v_min_i32_e32 v8, v91, v2
	v_min_i32_e32 v6, v95, v4
	v_min_i32_e32 v1, v92, v0
	v_min_i32_e32 v30, v94, v30
	v_min_i32_e32 v25, v85, v25
	v_min_i32_e32 v27, v64, v27
	v_min_i32_e32 v19, v62, v19
	v_max_i32_e32 v14, v108, v14
	v_max_i32_e32 v9, v104, v9
	v_max_i32_e32 v11, v102, v11
	v_max_i32_e32 v3, v100, v3
	v_min_i32_e32 v21, v61, v21
	v_min_i32_e32 v18, v58, v18
	v_min_i32_e32 v20, v57, v20
	v_min_i32_e32 v16, v56, v16
	v_max_i32_e32 v5, v60, v5
	v_max_i32_e32 v2, v91, v2
	v_max_i32_e32 v4, v95, v4
	v_max_i32_e32 v0, v92, v0
	v_max3_i32 v12, v26, v23, v12
	v_min_i32_e32 v15, v29, v24
	v_min_i32_e32 v17, v22, v17
	v_min_i32_e32 v23, v26, v23
	v_max_i32_e32 v65, v29, v24
	v_min_i32_e32 v96, v13, v8
	v_min_i32_e32 v97, v6, v1
	v_max_i32_e32 v85, v30, v25
	v_max_i32_e32 v62, v27, v19
	v_min_i32_e32 v64, v14, v9
	v_min_i32_e32 v94, v11, v3
	v_max_i32_e32 v58, v21, v18
	v_max_i32_e32 v56, v20, v16
	v_min_i32_e32 v57, v5, v2
	v_min_i32_e32 v60, v4, v0
	v_max_i32_e32 v8, v13, v8
	v_max_i32_e32 v1, v6, v1
	v_min_i32_e32 v22, v30, v25
	v_min_i32_e32 v19, v27, v19
	v_max3_i32 v7, v23, v10, v7
	v_min_i32_e32 v10, v15, v17
	v_min_i32_e32 v105, v107, v101
	v_min_i32_e32 v98, v96, v97
	v_min_i32_e32 v100, v64, v94
	v_min_i32_e32 v61, v57, v60
	v_min_i32_e32 v6, v8, v1
	v_max_i32_e32 v9, v14, v9
	v_max_i32_e32 v3, v11, v3
	v_min_i32_e32 v14, v21, v18
	v_min_i32_e32 v16, v20, v16
	v_max_i32_e32 v2, v5, v2
	v_max_i32_e32 v0, v4, v0
	v_min_i32_e32 v21, v93, v63
	v_min_i32_e32 v24, v65, v59
	v_min_i32_e32 v27, v85, v62
	v_min_i32_e32 v28, v58, v56
	v_max3_i32 v1, v10, v8, v1
	v_min_i32_e32 v10, v22, v19
	v_max3_i32 v105, v93, v63, v105
	v_max3_i32 v98, v65, v59, v98
	v_max3_i32 v100, v85, v62, v100
	v_max3_i32 v61, v58, v56, v61
	v_min_i32_e32 v11, v9, v3
	v_min_i32_e32 v4, v2, v0
	v_max3_i32 v21, v21, v107, v101
	v_max3_i32 v24, v24, v96, v97
	v_max3_i32 v27, v27, v64, v94
	v_max3_i32 v28, v28, v57, v60
	v_max3_i32 v3, v10, v9, v3
	v_min_i32_e32 v9, v14, v16
	v_max3_i32 v6, v15, v17, v6
	v_max3_i32 v11, v22, v19, v11
	v_max3_i32 v4, v14, v16, v4
	v_min_i32_e32 v25, v21, v24
	v_min_i32_e32 v29, v27, v28
	v_max3_i32 v0, v9, v2, v0
	v_max_i32_e32 v15, v105, v98
	v_max_i32_e32 v16, v100, v61
	v_max_i32_e32 v19, v21, v24
	v_max_i32_e32 v21, v27, v28
	v_min_i32_e32 v30, v25, v29
	v_min_i32_e32 v8, v7, v1
	v_min_i32_e32 v2, v3, v0
	v_max_i32_e32 v17, v15, v16
	v_max_i32_e32 v22, v19, v21
	v_min_i32_e32 v15, v15, v16
	v_min_i32_e32 v16, v19, v21
	v_max_i32_e32 v21, v25, v29
	v_max_i32_e32 v24, v71, v126
	s_waitcnt lgkmcnt(7)
	v_max_i32_e32 v25, v79, v132
	v_max_i32_e32 v27, v72, v128
	s_waitcnt lgkmcnt(3)
	v_max_i32_e32 v28, v86, v135
	v_max_i32_e32 v31, v69, v124
	v_max_i32_e32 v56, v77, v133
	v_max_i32_e32 v58, v70, v127
	s_waitcnt lgkmcnt(1)
	v_max_i32_e32 v59, v88, v134
	v_max_i32_e32 v63, v67, v87
	v_max_i32_e32 v64, v75, v130
	v_max_i32_e32 v67, v68, v125
	v_max_i32_e32 v68, v78, v131
	v_max_i32_e32 v66, v66, v89
	v_max_i32_e32 v71, v74, v122
	v_max_i32_e32 v73, v73, v123
	s_waitcnt lgkmcnt(0)
; #define P6_CE(x, y) do { const int hi_ = max(x, y), lo_ = min(x, y); x = hi_; y = lo_; } while (0)
; __device__ __forceinline__ void p6_merge16(int (&a)[16]) {
;     P6_CE(a[0], a[8]); P6_CE(a[1], a[9]); P6_CE(a[2], a[10]); P6_CE(a[3], a[11]); P6_CE(a[4], a[12]); P6_CE(a[5], a[13]); P6_CE(a[6], a[14]); P6_CE(a[7], a[15]); P6_CE(a[0], a[4]); P6_CE(a[1], a[5]); P6_CE(a[2], a[6]); P6_CE(a[3], a[7]); P6_CE(a[8], a[12]); P6_CE(a[9], a[13]); P6_CE(a[10], a[14]); P6_CE(a[11], a[15]); P6_CE(a[0], a[2]); P6_CE(a[1], a[3]); P6_CE(a[4], a[6]); P6_CE(a[5], a[7]); P6_CE(a[8], a[10]); P6_CE(a[9], a[11]); P6_CE(a[12], a[14]); P6_CE(a[13], a[15]); P6_CE(a[0], a[1]); P6_CE(a[2], a[3]); P6_CE(a[4], a[5]); P6_CE(a[6], a[7]); P6_CE(a[8], a[9]); P6_CE(a[10], a[11]); P6_CE(a[12], a[13]); P6_CE(a[14], a[15]);
; }
; __device__ __forceinline__ void p6_top16(int (&a)[16], const int (&b)[16]) {
; #pragma unroll
;     for (int i = 0; i < 16; ++i) a[i] = max(a[i], b[15 - i]);
;     p6_merge16(a);
; }
; __device__ __forceinline__ void p6_top16_partner(int (&a)[16]) {
;     int t[16];
; #pragma unroll
;     for (int i = 0; i < 16; ++i) t[i] = __shfl_xor(a[15 - i], 32);
; #pragma unroll
;     for (int i = 0; i < 16; ++i) a[i] = max(a[i], t[i]);
;     p6_merge16(a);
; }
	v_max_i32_e32 v74, v76, v129
	v_min_i32_e32 v9, v8, v2
	v_max_i32_e32 v1, v7, v1
	v_max_i32_e32 v0, v3, v0
	v_min_i32_e32 v26, v24, v25
	v_min_i32_e32 v29, v27, v28
	v_min_i32_e32 v57, v31, v56
	v_min_i32_e32 v60, v58, v59
	v_min_i32_e32 v65, v63, v64
	v_min_i32_e32 v69, v67, v68
	v_min_i32_e32 v72, v66, v71
	v_min_i32_e32 v75, v73, v74
	v_min_i32_e32 v99, v105, v98
	v_min_i32_e32 v91, v100, v61
	v_min_i32_e32 v13, v12, v6
	v_min_i32_e32 v5, v11, v4
	v_min_i32_e32 v10, v30, v9
	v_max_i32_e32 v6, v12, v6
	v_max_i32_e32 v4, v11, v4
	v_max_i32_e32 v3, v1, v0
	v_min_i32_e32 v0, v1, v0
	v_max_i32_e32 v9, v30, v9
	v_min_i32_e32 v30, v26, v29
	v_min_i32_e32 v61, v57, v60
	v_min_i32_e32 v70, v65, v69
	v_min_i32_e32 v76, v72, v75
	v_min_i32_e32 v156, v174, v148
	v_min_i32_e32 v92, v99, v91
	v_min_i32_e32 v18, v13, v5
	v_max_i32_e32 v11, v6, v4
	v_min_i32_e32 v4, v6, v4
	v_max_i32_e32 v1, v16, v0
	v_min_i32_e32 v0, v16, v0
	v_max_i32_e32 v16, v99, v91
	v_max_i32_e32 v5, v13, v5
	v_max_i32_e32 v2, v8, v2
	v_min_i32_e32 v62, v30, v61
	v_max_i32_e32 v30, v30, v61
	v_max_i32_e32 v61, v70, v76
	v_min_i32_e32 v32, v156, v37
	v_max_i32_e32 v34, v156, v37
	v_min_i32_e32 v44, v54, v46
	v_max_i32_e32 v46, v54, v46
	v_min_i32_e32 v51, v53, v55
	v_max_i32_e32 v53, v53, v55
	v_min_i32_e32 v20, v92, v18
	v_max_i32_e32 v12, v17, v11
	v_max_i32_e32 v7, v22, v3
	v_min_i32_e32 v11, v17, v11
	v_min_i32_e32 v3, v22, v3
	v_max_i32_e32 v6, v15, v4
	v_min_i32_e32 v4, v15, v4
	v_max_i32_e32 v13, v16, v5
	v_max_i32_e32 v8, v21, v2
	v_min_i32_e32 v5, v16, v5
	v_min_i32_e32 v2, v21, v2
	v_max_i32_e32 v18, v92, v18
	v_min_i32_e32 v77, v70, v76
	v_min_i32_e32 v70, v30, v61
	v_max_i32_e32 v30, v30, v61
	v_max_i32_e32 v26, v26, v29
	v_max_i32_e32 v29, v57, v60
	v_max_i32_e32 v60, v65, v69
	v_max_i32_e32 v61, v72, v75
	v_min_i32_e32 v36, v32, v33
	v_min_i32_e32 v37, v34, v35
	v_min_i32_e32 v42, v38, v39
	v_min_i32_e32 v43, v40, v41
	v_min_i32_e32 v48, v44, v45
	v_min_i32_e32 v49, v46, v47
	v_min_i32_e32 v54, v50, v51
	v_min_i32_e32 v55, v52, v53
	v_min_i32_e32 v14, v20, v10
	v_min_i32_e32 v23, v12, v7
	v_min_i32_e32 v17, v11, v3
	v_min_i32_e32 v19, v6, v1
	v_min_i32_e32 v15, v4, v0
	v_min_i32_e32 v22, v13, v8
	v_min_i32_e32 v16, v5, v2
	v_min_i32_e32 v21, v18, v9
	v_min_i32_e32 v57, v26, v29
	v_max_i32_e32 v26, v26, v29
	v_max_i32_e32 v29, v60, v61
	v_min_i32_e32 v65, v60, v61
	v_min_i32_e32 v60, v26, v29
	v_max_i32_e32 v26, v26, v29
	v_max_i32_e32 v24, v24, v25
	v_max_i32_e32 v25, v27, v28
	v_max_i32_e32 v28, v31, v56
	v_max_i32_e32 v29, v58, v59
	v_max_i32_e32 v58, v63, v64
	v_max_i32_e32 v59, v67, v68
	v_max_i32_e32 v63, v66, v71
	v_max_i32_e32 v64, v73, v74
	v_max3_i32 v7, v12, v7, v36
	v_max3_i32 v12, v23, v32, v33
	v_max3_i32 v3, v11, v3, v37
	v_max3_i32 v11, v17, v34, v35
	v_max3_i32 v1, v6, v1, v42
	v_max3_i32 v6, v19, v38, v39
	v_max3_i32 v0, v4, v0, v43
	v_max3_i32 v4, v15, v40, v41
	v_max3_i32 v8, v13, v8, v48
	v_max3_i32 v13, v22, v44, v45
	v_max3_i32 v2, v5, v2, v49
	v_max3_i32 v5, v16, v46, v47
	v_max3_i32 v9, v18, v9, v54
	v_max3_i32 v15, v21, v50, v51
	v_max3_i32 v10, v20, v10, v55
	v_max3_i32 v14, v14, v52, v53
	v_min_i32_e32 v69, v57, v65
	v_max_i32_e32 v57, v57, v65
	v_min_i32_e32 v27, v24, v25
	v_min_i32_e32 v31, v28, v29
	v_min_i32_e32 v61, v58, v59
	v_min_i32_e32 v65, v63, v64
	v_max_i32_e32 v16, v7, v8
	v_min_i32_e32 v7, v7, v8
	v_max_i32_e32 v8, v12, v13
	v_min_i32_e32 v12, v12, v13
	v_max_i32_e32 v13, v3, v2
	v_min_i32_e32 v2, v3, v2
	v_max_i32_e32 v3, v11, v5
	v_min_i32_e32 v5, v11, v5
	v_max_i32_e32 v11, v1, v9
	v_min_i32_e32 v1, v1, v9
	v_max_i32_e32 v9, v6, v15
	v_min_i32_e32 v6, v6, v15
	v_max_i32_e32 v15, v0, v10
	v_min_i32_e32 v0, v0, v10
	v_max_i32_e32 v10, v4, v14
	v_min_i32_e32 v4, v4, v14
	v_min_i32_e32 v56, v27, v31
	v_max_i32_e32 v27, v27, v31
	v_max_i32_e32 v31, v61, v65
	v_max_i32_e32 v14, v16, v11
	v_min_i32_e32 v11, v16, v11
	v_max_i32_e32 v16, v8, v9
	v_min_i32_e32 v8, v8, v9
	v_max_i32_e32 v9, v13, v15
	v_min_i32_e32 v13, v13, v15
	v_max_i32_e32 v15, v3, v10
	v_min_i32_e32 v3, v3, v10
	v_max_i32_e32 v10, v7, v1
	v_min_i32_e32 v1, v7, v1
	v_max_i32_e32 v7, v12, v6
	v_min_i32_e32 v6, v12, v6
	v_max_i32_e32 v12, v2, v0
	v_min_i32_e32 v0, v2, v0
	v_max_i32_e32 v2, v5, v4
	v_min_i32_e32 v4, v5, v4
	v_min_i32_e32 v66, v61, v65
	v_min_i32_e32 v61, v27, v31
	v_max_i32_e32 v27, v27, v31
	v_max_i32_e32 v24, v24, v25
	v_max_i32_e32 v25, v28, v29
	v_max_i32_e32 v29, v58, v59
	v_max_i32_e32 v31, v63, v64
	v_max_i32_e32 v5, v14, v9
	v_min_i32_e32 v9, v14, v9
	v_max_i32_e32 v14, v16, v15
	v_min_i32_e32 v15, v16, v15
	v_max_i32_e32 v16, v11, v13
	v_min_i32_e32 v11, v11, v13
	v_max_i32_e32 v13, v8, v3
	v_min_i32_e32 v3, v8, v3
	v_max_i32_e32 v8, v10, v12
	v_min_i32_e32 v10, v10, v12
	v_max_i32_e32 v12, v7, v2
	v_min_i32_e32 v2, v7, v2
	v_max_i32_e32 v7, v1, v0
	v_min_i32_e32 v0, v1, v0
	v_max_i32_e32 v1, v6, v4
	v_min_i32_e32 v4, v6, v4
	v_min_i32_e32 v28, v24, v25
	v_max_i32_e32 v24, v24, v25
	v_max_i32_e32 v25, v29, v31
	v_max_i32_e32 v6, v5, v14
	v_min_i32_e32 v5, v5, v14
	v_max_i32_e32 v14, v9, v15
	v_min_i32_e32 v9, v9, v15
	v_max_i32_e32 v15, v16, v13
	v_min_i32_e32 v13, v16, v13
	v_max_i32_e32 v16, v11, v3
	v_min_i32_e32 v3, v11, v3
	v_max_i32_e32 v11, v8, v12
	v_min_i32_e32 v8, v8, v12
	v_max_i32_e32 v12, v10, v2
	v_min_i32_e32 v2, v10, v2
	v_max_i32_e32 v10, v7, v1
	v_min_i32_e32 v1, v7, v1
	v_max_i32_e32 v7, v0, v4
	v_min_i32_e32 v0, v0, v4
	v_min_i32_e32 v58, v29, v31
	v_min_i32_e32 v29, v24, v25
	v_max_i32_e32 v24, v24, v25
	ds_bpermute_b32 v4, v83, v0
	ds_bpermute_b32 v17, v83, v7
	ds_bpermute_b32 v18, v83, v1
	ds_bpermute_b32 v19, v83, v10
	ds_bpermute_b32 v20, v83, v2
	ds_bpermute_b32 v21, v83, v12
	ds_bpermute_b32 v22, v83, v8
	ds_bpermute_b32 v23, v83, v11
	ds_bpermute_b32 v25, v83, v3
	ds_bpermute_b32 v31, v83, v16
	ds_bpermute_b32 v32, v83, v13
	ds_bpermute_b32 v33, v83, v15
	ds_bpermute_b32 v34, v83, v9
	ds_bpermute_b32 v35, v83, v14
	ds_bpermute_b32 v36, v83, v5
	ds_bpermute_b32 v37, v83, v6
	s_waitcnt lgkmcnt(14)
; __device__ __forceinline__ void p6_top16_partner(int (&a)[16]) {
;     int t[16];
; #pragma unroll
;     for (int i = 0; i < 16; ++i) t[i] = __shfl_xor(a[15 - i], 32);
; #pragma unroll
;     for (int i = 0; i < 16; ++i) a[i] = max(a[i], t[i]);
;     p6_merge16(a);
; }
; template <bool FROM_LDS>
; __device__ __forceinline__ void p6_task(unsigned char* ws, int lane, int h, int tok, const bf16* qrow_g, const LAS unsigned char* qrow_l, int rsw, LAS unsigned char* scr) {
;     ...
;         float v1[16], v2[16];
; #pragma unroll
;         for (int i = 0; i < 16; ++i) { v1[i] = key2f(k1[0][i] & ~127); v2[i] = key2f(k1[1][i] & ~127); }
	v_max_i32_e32 v4, v6, v4
	v_max_i32_e32 v5, v5, v17
	s_waitcnt lgkmcnt(13)
	v_max_i32_e32 v6, v14, v18
	s_waitcnt lgkmcnt(12)
	v_max_i32_e32 v9, v9, v19
	s_waitcnt lgkmcnt(11)
	v_max_i32_e32 v14, v15, v20
	s_waitcnt lgkmcnt(10)
	v_max_i32_e32 v13, v13, v21
	s_waitcnt lgkmcnt(9)
	v_max_i32_e32 v15, v16, v22
	s_waitcnt lgkmcnt(8)
	v_max_i32_e32 v3, v3, v23
	s_waitcnt lgkmcnt(7)
	v_max_i32_e32 v11, v11, v25
	s_waitcnt lgkmcnt(6)
	v_max_i32_e32 v8, v8, v31
	s_waitcnt lgkmcnt(5)
	v_max_i32_e32 v12, v12, v32
	s_waitcnt lgkmcnt(4)
	v_max_i32_e32 v2, v2, v33
	s_waitcnt lgkmcnt(3)
	v_max_i32_e32 v10, v10, v34
	s_waitcnt lgkmcnt(2)
	v_max_i32_e32 v1, v1, v35
	s_waitcnt lgkmcnt(1)
	v_max_i32_e32 v7, v7, v36
	s_waitcnt lgkmcnt(0)
	v_max_i32_e32 v0, v0, v37
	v_max_i32_e32 v16, v4, v11
	v_min_i32_e32 v4, v4, v11
	v_max_i32_e32 v11, v5, v8
	v_min_i32_e32 v5, v5, v8
	v_max_i32_e32 v8, v6, v12
	v_min_i32_e32 v6, v6, v12
	v_max_i32_e32 v12, v9, v2
	v_min_i32_e32 v2, v9, v2
	v_max_i32_e32 v9, v14, v10
	v_min_i32_e32 v10, v14, v10
	v_max_i32_e32 v14, v13, v1
	v_min_i32_e32 v1, v13, v1
	v_max_i32_e32 v13, v15, v7
	v_min_i32_e32 v7, v15, v7
	v_max_i32_e32 v15, v3, v0
	v_min_i32_e32 v0, v3, v0
	v_max_i32_e32 v3, v16, v9
	v_min_i32_e32 v9, v16, v9
	v_max_i32_e32 v16, v11, v14
	v_min_i32_e32 v11, v11, v14
	v_max_i32_e32 v14, v8, v13
	v_min_i32_e32 v8, v8, v13
	v_max_i32_e32 v13, v12, v15
	v_min_i32_e32 v12, v12, v15
	v_max_i32_e32 v15, v4, v10
	v_min_i32_e32 v4, v4, v10
	v_max_i32_e32 v10, v5, v1
	v_min_i32_e32 v1, v5, v1
	v_max_i32_e32 v5, v6, v7
	v_min_i32_e32 v6, v6, v7
	v_max_i32_e32 v7, v2, v0
	v_min_i32_e32 v0, v2, v0
	v_max_i32_e32 v2, v3, v14
	v_min_i32_e32 v3, v3, v14
	v_max_i32_e32 v14, v16, v13
	v_min_i32_e32 v13, v16, v13
	v_max_i32_e32 v16, v9, v8
	v_min_i32_e32 v8, v9, v8
	v_max_i32_e32 v9, v11, v12
	v_min_i32_e32 v11, v11, v12
	v_max_i32_e32 v12, v15, v5
	v_min_i32_e32 v5, v15, v5
	v_max_i32_e32 v15, v10, v7
	v_min_i32_e32 v7, v10, v7
	v_max_i32_e32 v10, v4, v6
	v_min_i32_e32 v4, v4, v6
	v_max_i32_e32 v6, v1, v0
	v_min_i32_e32 v0, v1, v0
	v_max_i32_e32 v1, v2, v14
	v_min_i32_e32 v2, v2, v14
	v_max_i32_e32 v18, v4, v0
	v_min_i32_e32 v19, v4, v0
	v_and_b32_e32 v0, 0xffffff80, v24
	v_ashrrev_i32_e32 v4, 31, v24
	v_max_i32_e32 v14, v3, v13
	v_max_i32_e32 v17, v10, v6
	v_min_i32_e32 v10, v10, v6
	v_bitop3_b32 v6, v4, v0, s51 bitop3:0x6c
	v_and_b32_e32 v0, 0xffffff80, v2
	v_ashrrev_i32_e32 v4, 31, v2
	v_min_i32_e32 v59, v28, v58
	v_bitop3_b32 v20, v4, v0, s51 bitop3:0x6c
	v_and_b32_e32 v0, 0xffffff80, v14
	v_ashrrev_i32_e32 v4, 31, v14
	v_bitop3_b32 v21, v4, v0, s51 bitop3:0x6c
	v_ashrrev_i32_e32 v4, 31, v59
	v_and_b32_e32 v22, 0x7fffffff, v4
	v_ashrrev_i32_e32 v4, 31, v1
	v_min_i32_e32 v3, v3, v13
	v_max_i32_e32 v13, v16, v9
	v_min_i32_e32 v9, v16, v9
	v_max_i32_e32 v16, v8, v11
	v_min_i32_e32 v8, v8, v11
	v_max_i32_e32 v11, v12, v15
	v_min_i32_e32 v12, v12, v15
	v_max_i32_e32 v15, v5, v7
	v_min_i32_e32 v5, v5, v7
	v_and_b32_e32 v0, 0xffffff80, v1
	v_and_b32_e32 v7, 0xffffff80, v59
	v_and_b32_e32 v4, 0x7fffffff, v4
	v_xor_b32_e32 v4, v4, v0
	v_xor_b32_e32 v22, v22, v7
	v_and_b32_e32 v0, 0xffffff80, v3
	v_ashrrev_i32_e32 v7, 31, v3
	v_bitop3_b32 v23, v7, v0, s51 bitop3:0x6c
	v_and_b32_e32 v0, 0xffffff80, v27
	v_ashrrev_i32_e32 v7, 31, v27
	v_bitop3_b32 v25, v7, v0, s51 bitop3:0x6c
	v_and_b32_e32 v0, 0xffffff80, v13
	v_ashrrev_i32_e32 v7, 31, v13
	v_bitop3_b32 v31, v7, v0, s51 bitop3:0x6c
	v_and_b32_e32 v0, 0xffffff80, v9
	v_ashrrev_i32_e32 v7, 31, v9
	v_min_i32_e32 v67, v56, v66
	v_bitop3_b32 v32, v7, v0, s51 bitop3:0x6c
	v_and_b32_e32 v0, 0xffffff80, v16
	v_ashrrev_i32_e32 v7, 31, v16
	v_bitop3_b32 v33, v7, v0, s51 bitop3:0x6c
	v_and_b32_e32 v0, 0xffffff80, v67
	v_ashrrev_i32_e32 v7, 31, v67
	v_bitop3_b32 v7, v7, v0, s51 bitop3:0x6c
	v_and_b32_e32 v0, 0xffffff80, v8
	v_ashrrev_i32_e32 v34, 31, v8
	v_bitop3_b32 v34, v34, v0, s51 bitop3:0x6c
	v_and_b32_e32 v0, 0xffffff80, v26
	v_ashrrev_i32_e32 v35, 31, v26
	v_bitop3_b32 v35, v35, v0, s51 bitop3:0x6c
	v_and_b32_e32 v0, 0xffffff80, v11
	v_ashrrev_i32_e32 v36, 31, v11
	v_bitop3_b32 v36, v36, v0, s51 bitop3:0x6c
	v_and_b32_e32 v0, 0xffffff80, v60
	v_ashrrev_i32_e32 v37, 31, v60
	v_bitop3_b32 v37, v37, v0, s51 bitop3:0x6c
	v_and_b32_e32 v0, 0xffffff80, v12
	v_ashrrev_i32_e32 v38, 31, v12
	v_bitop3_b32 v38, v38, v0, s51 bitop3:0x6c
	v_and_b32_e32 v0, 0xffffff80, v57
	v_ashrrev_i32_e32 v39, 31, v57
	v_bitop3_b32 v39, v39, v0, s51 bitop3:0x6c
	v_and_b32_e32 v0, 0xffffff80, v15
	v_ashrrev_i32_e32 v40, 31, v15
	v_bitop3_b32 v40, v40, v0, s51 bitop3:0x6c
	v_and_b32_e32 v0, 0xffffff80, v69
	v_ashrrev_i32_e32 v41, 31, v69
	v_bitop3_b32 v41, v41, v0, s51 bitop3:0x6c
	v_and_b32_e32 v0, 0xffffff80, v5
	v_ashrrev_i32_e32 v42, 31, v5
	v_bitop3_b32 v42, v42, v0, s51 bitop3:0x6c
	v_and_b32_e32 v0, 0xffffff80, v30
	v_ashrrev_i32_e32 v43, 31, v30
	v_bitop3_b32 v43, v43, v0, s51 bitop3:0x6c
	v_and_b32_e32 v0, 0xffffff80, v17
	v_ashrrev_i32_e32 v44, 31, v17
	v_bitop3_b32 v44, v44, v0, s51 bitop3:0x6c
	v_and_b32_e32 v0, 0xffffff80, v70
	v_ashrrev_i32_e32 v45, 31, v70
	v_min_i32_e32 v78, v62, v77
	v_max_i32_e32 v62, v62, v77
	v_bitop3_b32 v45, v45, v0, s51 bitop3:0x6c
	v_and_b32_e32 v0, 0xffffff80, v10
	v_ashrrev_i32_e32 v46, 31, v10
	v_bitop3_b32 v46, v46, v0, s51 bitop3:0x6c
	v_and_b32_e32 v0, 0xffffff80, v62
	v_ashrrev_i32_e32 v47, 31, v62
	v_bitop3_b32 v47, v47, v0, s51 bitop3:0x6c
	v_and_b32_e32 v0, 0xffffff80, v18
	v_ashrrev_i32_e32 v48, 31, v18
	v_bitop3_b32 v48, v48, v0, s51 bitop3:0x6c
	v_and_b32_e32 v0, 0xffffff80, v78
	v_ashrrev_i32_e32 v49, 31, v78
	v_bitop3_b32 v49, v49, v0, s51 bitop3:0x6c
	v_and_b32_e32 v0, 0xffffff80, v19
; #define LAS __attribute__((address_space(3)))
; #define P6_CAND(k, Ia, Ja, Ib, Jb) do { const float sa_ = v1[Ia] + v2[Ja], sb_ = v1[Ib] + v2[Jb]; \
;             const int key_ = (f2key(hh ? sb_ : sa_) & ~255) | (hh ? ((Ib) << 4 | (Jb)) : ((Ia) << 4 | (Ja))); if ((k) < 16) ca[(k) & 15] = key_; else cb[(k) & 15] = key_; } while (0)
; template <bool FROM_LDS>
; __device__ __forceinline__ void p6_task(unsigned char* ws, int lane, int h, int tok, const bf16* qrow_g, const LAS unsigned char* qrow_l, int rsw, LAS unsigned char* scr) {
;     ...
;         for (int i = 0; i < 16; ++i) { v1[i] = key2f(k1[0][i] & ~127); v2[i] = key2f(k1[1][i] & ~127); }
;         { v4u w;
; #pragma unroll
;           for (int q = 0; q < 4; ++q) { unsigned x = 0;
; #pragma unroll
;               for (int c = 0; c < 4; ++c) x |= (unsigned)((hh ? k1[1][4 * q + c] : k1[0][4 * q + c]) & 127) << (8 * c);
;               w[q] = x; }
;           *(LAS v4u*)(scr + 16 * hh) = w; }
;         int ca[16], cb[16];
;     ...
;         P6_CAND(0, 0, 0, 0, 1);
;         P6_CAND(1, 0, 2, 0, 3);
;         P6_CAND(2, 0, 4, 0, 5);
;         P6_CAND(3, 0, 6, 0, 7);
;         P6_CAND(4, 0, 8, 0, 9);
;         P6_CAND(5, 0, 10, 0, 11);
;         P6_CAND(6, 0, 12, 0, 13);
;         P6_CAND(7, 0, 14, 0, 15);
;         P6_CAND(8, 1, 0, 1, 1);
;         P6_CAND(9, 1, 2, 1, 3);
;         P6_CAND(10, 1, 4, 1, 5);
;         P6_CAND(11, 1, 6, 1, 7);
;         P6_CAND(12, 2, 0, 2, 1);
;         P6_CAND(13, 2, 2, 2, 3);
;         P6_CAND(14, 2, 4, 3, 0);
;         P6_CAND(15, 3, 1, 3, 2);
;         P6_CAND(16, 3, 3, 4, 0);
;         P6_CAND(17, 4, 1, 4, 2);
;         P6_CAND(18, 5, 0, 5, 1);
;         P6_CAND(19, 6, 0, 6, 1);
;         P6_CAND(20, 7, 0, 7, 1);
;         P6_CAND(21, 8, 0, 9, 0);
;         P6_CAND(22, 10, 0, 11, 0);
;         P6_CAND(23, 12, 0, 13, 0);
;         P6_CAND(24, 14, 0, 15, 0);
	v_ashrrev_i32_e32 v50, 31, v19
	v_cmp_gt_u32_e32 vcc, 32, v169
	v_bitop3_b32 v50, v50, v0, s51 bitop3:0x6c
	v_max_i32_e32 v28, v28, v58
	v_cndmask_b32_e32 v0, v1, v24, vcc
	v_cndmask_b32_e32 v1, v2, v29, vcc
	v_and_b32_e32 v0, 0x7f, v0
	v_lshlrev_b32_e32 v1, 8, v1
	v_and_or_b32 v0, v1, s52, v0
	v_cndmask_b32_e32 v1, v14, v28, vcc
	v_cndmask_b32_e32 v2, v3, v59, vcc
	v_lshlrev_b32_e32 v1, 16, v1
	v_lshlrev_b32_e32 v2, 24, v2
	v_and_b32_e32 v1, 0x7f0000, v1
	v_and_b32_e32 v2, 0x7f000000, v2
	v_or3_b32 v0, v0, v1, v2
	v_cndmask_b32_e32 v1, v13, v27, vcc
	v_cndmask_b32_e32 v2, v9, v61, vcc
	v_max_i32_e32 v56, v56, v66
	v_and_b32_e32 v1, 0x7f, v1
	v_lshlrev_b32_e32 v2, 8, v2
	v_and_or_b32 v1, v2, s52, v1
	v_cndmask_b32_e32 v2, v16, v56, vcc
	v_cndmask_b32_e32 v3, v8, v67, vcc
	v_lshlrev_b32_e32 v2, 16, v2
	v_lshlrev_b32_e32 v3, 24, v3
	v_and_b32_e32 v2, 0x7f0000, v2
	v_and_b32_e32 v3, 0x7f000000, v3
	v_or3_b32 v1, v1, v2, v3
	v_cndmask_b32_e32 v2, v11, v26, vcc
	v_cndmask_b32_e32 v3, v12, v60, vcc
	v_and_b32_e32 v2, 0x7f, v2
	v_lshlrev_b32_e32 v3, 8, v3
	v_and_or_b32 v2, v3, s52, v2
	v_cndmask_b32_e32 v3, v15, v57, vcc
	v_cndmask_b32_e32 v5, v5, v69, vcc
	v_lshlrev_b32_e32 v3, 16, v3
	v_lshlrev_b32_e32 v5, 24, v5
	v_and_b32_e32 v3, 0x7f0000, v3
	v_and_b32_e32 v5, 0x7f000000, v5
	v_or3_b32 v2, v2, v3, v5
	v_cndmask_b32_e32 v3, v17, v30, vcc
	v_cndmask_b32_e32 v5, v10, v70, vcc
	v_and_b32_e32 v3, 0x7f, v3
	v_lshlrev_b32_e32 v5, 8, v5
	v_and_or_b32 v3, v5, s52, v3
	v_cndmask_b32_e32 v5, v18, v62, vcc
	v_cndmask_b32_e32 v8, v19, v78, vcc
	v_lshlrev_b32_e32 v5, 16, v5
	v_lshlrev_b32_e32 v8, 24, v8
	v_and_b32_e32 v5, 0x7f0000, v5
	v_and_b32_e32 v8, 0x7f000000, v8
	v_cmp_lt_u32_e64 s[4:5], 31, v169
	v_or3_b32 v3, v3, v5, v8
	v_ashrrev_i32_e32 v15, 31, v28
	v_cndmask_b32_e64 v8, v4, v20, s[4:5]
	v_add_f32_e32 v5, v8, v6
	v_ashrrev_i32_e32 v9, 31, v5
	v_and_b32_e32 v9, 0x7fffff00, v9
	v_and_b32_e32 v5, 0xffffff00, v5
	v_cndmask_b32_e64 v10, 0, 1, s[4:5]
	v_bitop3_b32 v16, v9, v10, v5 bitop3:0xde
	v_cndmask_b32_e64 v5, v21, v23, s[4:5]
	v_add_f32_e32 v9, v5, v6
	v_ashrrev_i32_e32 v10, 31, v9
	v_and_b32_e32 v10, 0x7fffff00, v10
	v_and_b32_e32 v9, 0xffffff00, v9
	v_cndmask_b32_e64 v11, 2, 3, s[4:5]
	v_bitop3_b32 v17, v10, v11, v9 bitop3:0xde
	v_cndmask_b32_e64 v11, v31, v32, s[4:5]
	v_cndmask_b32_e64 v10, v33, v34, s[4:5]
	v_add_f32_e32 v12, v10, v6
	v_add_f32_e32 v13, v11, v6
	v_cndmask_b32_e64 v9, 4, 5, s[4:5]
	v_ashrrev_i32_e32 v14, 31, v13
	v_and_b32_e32 v14, 0x7fffff00, v14
	v_and_b32_e32 v13, 0xffffff00, v13
	v_bitop3_b32 v18, v14, v9, v13 bitop3:0xde
	v_ashrrev_i32_e32 v9, 31, v12
	v_and_b32_e32 v9, 0x7fffff00, v9
	v_and_b32_e32 v12, 0xffffff00, v12
	v_cndmask_b32_e64 v13, 6, 7, s[4:5]
	v_bitop3_b32 v19, v9, v13, v12 bitop3:0xde
	v_cndmask_b32_e64 v9, v36, v38, s[4:5]
	v_add_f32_e32 v9, v6, v9
	v_ashrrev_i32_e32 v12, 31, v9
	v_and_b32_e32 v12, 0x7fffff00, v12
	v_and_b32_e32 v9, 0xffffff00, v9
	v_cndmask_b32_e64 v13, 8, 9, s[4:5]
	v_bitop3_b32 v24, v12, v13, v9 bitop3:0xde
	v_cndmask_b32_e64 v9, v40, v42, s[4:5]
	v_add_f32_e32 v9, v6, v9
	v_ashrrev_i32_e32 v12, 31, v9
	v_and_b32_e32 v12, 0x7fffff00, v12
	v_and_b32_e32 v9, 0xffffff00, v9
	v_cndmask_b32_e64 v13, 10, 11, s[4:5]
	v_bitop3_b32 v26, v12, v13, v9 bitop3:0xde
	v_cndmask_b32_e64 v9, v44, v46, s[4:5]
	v_add_f32_e32 v9, v6, v9
	v_ashrrev_i32_e32 v12, 31, v9
	v_and_b32_e32 v12, 0x7fffff00, v12
	v_and_b32_e32 v9, 0xffffff00, v9
	v_cndmask_b32_e64 v13, 12, 13, s[4:5]
	v_ashrrev_i32_e32 v14, 31, v29
	v_bitop3_b32 v27, v12, v13, v9 bitop3:0xde
	v_and_b32_e32 v9, 0xffffff80, v29
	v_and_b32_e32 v14, 0x7fffffff, v14
	v_and_b32_e32 v12, 0xffffff80, v28
	v_and_b32_e32 v28, 0x7fffffff, v15
	v_xor_b32_e32 v15, v14, v9
	v_cndmask_b32_e64 v13, v48, v50, s[4:5]
	v_xor_b32_e32 v14, v28, v12
	v_mov_b32_e32 v9, v6
	v_mov_b32_e32 v12, v15
	v_add_f32_e32 v12, v8, v12
	v_add_f32_e32 v13, v9, v13
	v_cndmask_b32_e64 v30, 14, 15, s[4:5]
	v_ashrrev_i32_e32 v6, 31, v13
	v_and_b32_e32 v6, 0x7fffff00, v6
	v_and_b32_e32 v9, 0xffffff00, v13
	v_bitop3_b32 v13, v6, v30, v9 bitop3:0xde
	v_ashrrev_i32_e32 v6, 31, v12
	v_cndmask_b32_e64 v32, 16, 17, s[4:5]
	v_and_b32_e32 v6, 0x7fffff00, v6
	v_and_b32_e32 v9, 0xffffff00, v12
	v_bitop3_b32 v12, v6, v32, v9 bitop3:0xde
	v_add_f32_e32 v6, v5, v15
	v_ashrrev_i32_e32 v9, 31, v6
	v_cndmask_b32_e64 v33, 18, 19, s[4:5]
	v_and_b32_e32 v9, 0x7fffff00, v9
	v_and_b32_e32 v6, 0xffffff00, v6
	v_bitop3_b32 v28, v9, v33, v6 bitop3:0xde
	v_add_f32_e32 v6, v11, v15
	v_ashrrev_i32_e32 v9, 31, v6
	v_cndmask_b32_e64 v34, 20, 21, s[4:5]
	v_and_b32_e32 v9, 0x7fffff00, v9
	v_and_b32_e32 v6, 0xffffff00, v6
	v_bitop3_b32 v29, v9, v34, v6 bitop3:0xde
	v_mov_b32_e32 v9, v10
	v_add_f32_e32 v10, v8, v14
	v_add_f32_e32 v11, v9, v15
	v_cndmask_b32_e64 v36, 22, 23, s[4:5]
	v_ashrrev_i32_e32 v6, 31, v11
	v_and_b32_e32 v6, 0x7fffff00, v6
	v_and_b32_e32 v9, 0xffffff00, v11
	v_bitop3_b32 v9, v6, v36, v9 bitop3:0xde
	v_ashrrev_i32_e32 v6, 31, v10
	v_and_b32_e32 v6, 0x7fffff00, v6
	v_and_b32_e32 v10, 0xffffff00, v10
	v_cndmask_b32_e64 v11, 32, 33, s[4:5]
	v_add_f32_e32 v5, v5, v14
	v_bitop3_b32 v15, v6, v11, v10 bitop3:0xde
	v_ashrrev_i32_e32 v6, 31, v5
	v_and_b32_e32 v6, 0x7fffff00, v6
	v_and_b32_e32 v5, 0xffffff00, v5
	v_cndmask_b32_e64 v10, 34, 35, s[4:5]
	v_bitop3_b32 v30, v6, v10, v5 bitop3:0xde
	v_add_f32_e32 v5, v14, v31
	v_add_f32_e32 v6, v4, v22
	v_cndmask_b32_e64 v5, v5, v6, s[4:5]
	v_ashrrev_i32_e32 v6, 31, v5
	v_and_b32_e32 v6, 0x7fffff00, v6
	v_and_b32_e32 v5, 0xffffff00, v5
	v_cndmask_b32_e64 v10, 36, 48, s[4:5]
	v_bitop3_b32 v14, v6, v10, v5 bitop3:0xde
	v_cndmask_b32_e64 v5, v20, v21, s[4:5]
; __device__ __forceinline__ void p6_sort16(int (&a)[16]) {
;     P6_CE(a[0], a[1]); P6_CE(a[3], a[2]); P6_CE(a[4], a[5]); P6_CE(a[7], a[6]); P6_CE(a[8], a[9]); P6_CE(a[11], a[10]); P6_CE(a[12], a[13]); P6_CE(a[15], a[14]); P6_CE(a[0], a[2]); P6_CE(a[1], a[3]); P6_CE(a[6], a[4]); P6_CE(a[7], a[5]); P6_CE(a[8], a[10]); P6_CE(a[9], a[11]); P6_CE(a[14], a[12]); P6_CE(a[15], a[13]); P6_CE(a[0], a[1]); P6_CE(a[2], a[3]); P6_CE(a[5], a[4]); P6_CE(a[7], a[6]); P6_CE(a[8], a[9]); P6_CE(a[10], a[11]); P6_CE(a[13], a[12]); P6_CE(a[15], a[14]); P6_CE(a[0], a[4]); P6_CE(a[1], a[5]); P6_CE(a[2], a[6]); P6_CE(a[3], a[7]); P6_CE(a[12], a[8]); P6_CE(a[13], a[9]); P6_CE(a[14], a[10]); P6_CE(a[15], a[11]); P6_CE(a[0], a[2]); P6_CE(a[1], a[3]); P6_CE(a[4], a[6]); P6_CE(a[5], a[7]); P6_CE(a[10], a[8]); P6_CE(a[11], a[9]); P6_CE(a[14], a[12]); P6_CE(a[15], a[13]); P6_CE(a[0], a[1]); P6_CE(a[2], a[3]); P6_CE(a[4], a[5]); P6_CE(a[6], a[7]); P6_CE(a[9], a[8]); P6_CE(a[11], a[10]); P6_CE(a[13], a[12]); P6_CE(a[15], a[14]); P6_CE(a[0], a[8]); P6_CE(a[1], a[9]); P6_CE(a[2], a[10]); P6_CE(a[3], a[11]); P6_CE(a[4], a[12]); P6_CE(a[5], a[13]); P6_CE(a[6], a[14]); P6_CE(a[7], a[15]); P6_CE(a[0], a[4]); P6_CE(a[1], a[5]); P6_CE(a[2], a[6]); P6_CE(a[3], a[7]); P6_CE(a[8], a[12]); P6_CE(a[9], a[13]); P6_CE(a[10], a[14]); P6_CE(a[11], a[15]); P6_CE(a[0], a[2]); P6_CE(a[1], a[3]); P6_CE(a[4], a[6]); P6_CE(a[5], a[7]); P6_CE(a[8], a[10]); P6_CE(a[9], a[11]); P6_CE(a[12], a[14]); P6_CE(a[13], a[15]); P6_CE(a[0], a[1]); P6_CE(a[2], a[3]); P6_CE(a[4], a[5]); P6_CE(a[6], a[7]); P6_CE(a[8], a[9]); P6_CE(a[10], a[11]); P6_CE(a[12], a[13]); P6_CE(a[14], a[15]);
; template <bool FROM_LDS>
; __device__ __forceinline__ void p6_task(unsigned char* ws, int lane, int h, int tok, const bf16* qrow_g, const LAS unsigned char* qrow_l, int rsw, LAS unsigned char* scr) {
;     ...
;         P6_CAND(14, 2, 4, 3, 0);
;         P6_CAND(15, 3, 1, 3, 2);
;         P6_CAND(16, 3, 3, 4, 0);
;         P6_CAND(17, 4, 1, 4, 2);
;         P6_CAND(18, 5, 0, 5, 1);
;         P6_CAND(19, 6, 0, 6, 1);
;         P6_CAND(20, 7, 0, 7, 1);
;         P6_CAND(21, 8, 0, 9, 0);
;         P6_CAND(22, 10, 0, 11, 0);
;         P6_CAND(23, 12, 0, 13, 0);
;         P6_CAND(24, 14, 0, 15, 0);
;     ...
; #pragma unroll
;         for (int i = 9; i < 16; ++i) cb[i] = INT_MINV;
;         p6_sort16(ca); p6_sort16(cb); p6_top16(ca, cb); p6_top16_partner(ca);
	v_add_f32_e32 v6, v5, v22
	v_ashrrev_i32_e32 v10, 31, v6
	v_and_b32_e32 v10, 0x7fffff00, v10
	v_and_b32_e32 v6, 0xffffff00, v6
	v_cndmask_b32_e64 v11, 49, 50, s[4:5]
	v_bitop3_b32 v20, v10, v11, v6 bitop3:0xde
	v_add_f32_e32 v6, v22, v23
	v_add_f32_e32 v10, v4, v25
	v_cndmask_b32_e64 v6, v6, v10, s[4:5]
	v_ashrrev_i32_e32 v10, 31, v6
	v_and_b32_e32 v10, 0x7fffff00, v10
	v_and_b32_e32 v6, 0xffffff00, v6
	v_cndmask_b32_e64 v11, 51, 64, s[4:5]
	v_add_f32_e32 v5, v5, v25
	v_bitop3_b32 v21, v10, v11, v6 bitop3:0xde
	v_ashrrev_i32_e32 v6, 31, v5
	v_and_b32_e32 v6, 0x7fffff00, v6
	v_and_b32_e32 v5, 0xffffff00, v5
	v_cndmask_b32_e64 v10, v153, v230, s[4:5]
	v_ashrrev_i32_e32 v11, 31, v61
	v_ashrrev_i32_e32 v23, 31, v56
	v_bitop3_b32 v22, v6, v10, v5 bitop3:0xde
	v_and_b32_e32 v6, 0xffffff80, v61
	v_and_b32_e32 v10, 0xffffff80, v56
	v_and_b32_e32 v11, 0x7fffffff, v11
	v_and_b32_e32 v23, 0x7fffffff, v23
	v_xor_b32_e32 v11, v11, v6
	v_xor_b32_e32 v10, v23, v10
	v_add_f32_e32 v10, v8, v10
	v_add_f32_e32 v11, v8, v11
	v_ashrrev_i32_e32 v6, 31, v11
	v_cndmask_b32_e64 v5, v252, v253, s[4:5]
	v_and_b32_e32 v6, 0x7fffff00, v6
	v_and_b32_e32 v11, 0xffffff00, v11
	v_bitop3_b32 v11, v6, v5, v11 bitop3:0xde
	v_ashrrev_i32_e32 v5, 31, v10
	v_and_b32_e32 v5, 0x7fffff00, v5
	v_and_b32_e32 v6, 0xffffff00, v10
	v_cndmask_b32_e64 v10, v150, v158, s[4:5]
	v_bitop3_b32 v10, v5, v10, v6 bitop3:0xde
	v_cndmask_b32_e64 v6, v35, v37, s[4:5]
	v_mov_b32_e32 v5, v8
	v_add_f32_e32 v6, v4, v6
	v_add_f32_e32 v7, v5, v7
	v_cndmask_b32_e64 v23, v159, v160, s[4:5]
	v_ashrrev_i32_e32 v5, 31, v7
	v_and_b32_e32 v5, 0x7fffff00, v5
	v_and_b32_e32 v7, 0xffffff00, v7
	v_bitop3_b32 v5, v5, v23, v7 bitop3:0xde
	v_ashrrev_i32_e32 v7, 31, v6
	v_and_b32_e32 v7, 0x7fffff00, v7
	v_and_b32_e32 v6, 0xffffff00, v6
	v_cndmask_b32_e64 v8, v161, v162, s[4:5]
	v_bitop3_b32 v6, v7, v8, v6 bitop3:0xde
	v_cndmask_b32_e64 v7, v39, v41, s[4:5]
	v_add_f32_e32 v7, v4, v7
	v_ashrrev_i32_e32 v8, 31, v7
	v_and_b32_e32 v8, 0x7fffff00, v8
	v_and_b32_e32 v7, 0xffffff00, v7
	v_cndmask_b32_e64 v23, v163, v164, s[4:5]
	v_bitop3_b32 v7, v8, v23, v7 bitop3:0xde
	v_cndmask_b32_e64 v8, v43, v45, s[4:5]
	v_add_f32_e32 v8, v4, v8
	v_ashrrev_i32_e32 v23, 31, v8
	v_and_b32_e32 v23, 0x7fffff00, v23
	v_and_b32_e32 v8, 0xffffff00, v8
	v_cndmask_b32_e64 v25, v165, v166, s[4:5]
	v_bitop3_b32 v8, v23, v25, v8 bitop3:0xde
	v_cndmask_b32_e64 v23, v47, v49, s[4:5]
	v_add_f32_e32 v4, v4, v23
	v_ashrrev_i32_e32 v23, 31, v4
	v_and_b32_e32 v23, 0x7fffff00, v23
	v_and_b32_e32 v4, 0xffffff00, v4
	v_cndmask_b32_e64 v25, v167, v168, s[4:5]
	v_bitop3_b32 v4, v23, v25, v4 bitop3:0xde
	v_max_i32_e32 v23, v16, v17
	v_min_i32_e32 v16, v16, v17
	v_max_i32_e32 v17, v19, v18
	v_min_i32_e32 v18, v19, v18
	v_max_i32_e32 v19, v24, v26
	v_min_i32_e32 v24, v24, v26
	v_max_i32_e32 v25, v13, v27
	v_min_i32_e32 v13, v13, v27
	v_max_i32_e32 v26, v12, v28
	v_min_i32_e32 v12, v12, v28
	v_max_i32_e32 v27, v9, v29
	v_min_i32_e32 v9, v9, v29
	v_max_i32_e32 v28, v15, v30
	v_min_i32_e32 v15, v15, v30
	v_max_i32_e32 v29, v20, v14
	v_min_i32_e32 v14, v20, v14
	v_max_i32_e32 v33, v21, v22
	v_min_i32_e32 v21, v21, v22
	v_max_i32_e32 v22, v10, v11
	v_min_i32_e32 v10, v10, v11
	v_max_i32_e32 v11, v5, v6
	v_min_i32_e32 v5, v5, v6
	v_max_i32_e32 v6, v8, v7
	v_min_i32_e32 v7, v8, v7
	v_max_i32_e32 v20, v23, v18
	v_min_i32_e32 v18, v23, v18
	v_max_i32_e32 v23, v16, v17
	v_min_i32_e32 v16, v16, v17
	v_max_i32_e32 v17, v13, v19
	v_min_i32_e32 v13, v13, v19
	v_max_i32_e32 v19, v25, v24
	v_min_i32_e32 v24, v25, v24
	v_max_i32_e32 v25, v26, v9
	v_min_i32_e32 v9, v26, v9
	v_max_i32_e32 v26, v12, v27
	v_min_i32_e32 v12, v12, v27
	v_max_i32_e32 v27, v14, v28
	v_min_i32_e32 v14, v14, v28
	v_max_i32_e32 v28, v29, v15
	v_min_i32_e32 v15, v29, v15
	v_max_i32_e32 v8, v33, v10
	v_min_i32_e32 v10, v33, v10
	v_max_i32_e32 v33, v21, v22
	v_min_i32_e32 v21, v21, v22
	v_max_i32_e32 v22, v7, v11
	v_min_i32_e32 v7, v7, v11
	v_max_i32_e32 v11, v6, v5
	v_min_i32_e32 v5, v6, v5
	v_max_i32_e32 v29, v20, v23
	v_min_i32_e32 v20, v20, v23
	v_max_i32_e32 v23, v18, v16
	v_min_i32_e32 v16, v18, v16
	v_max_i32_e32 v18, v24, v13
	v_min_i32_e32 v13, v24, v13
	v_max_i32_e32 v24, v19, v17
	v_min_i32_e32 v17, v19, v17
	v_max_i32_e32 v19, v25, v26
	v_min_i32_e32 v25, v25, v26
	v_max_i32_e32 v26, v9, v12
	v_min_i32_e32 v9, v9, v12
	v_max_i32_e32 v12, v15, v14
	v_min_i32_e32 v14, v15, v14
	v_max_i32_e32 v15, v28, v27
	v_min_i32_e32 v27, v28, v27
	v_max_i32_e32 v6, v8, v33
	v_min_i32_e32 v8, v8, v33
	v_max_i32_e32 v33, v10, v21
	v_min_i32_e32 v10, v10, v21
	v_max_i32_e32 v21, v5, v7
	v_min_i32_e32 v5, v5, v7
	v_max_i32_e32 v7, v11, v22
	v_min_i32_e32 v11, v11, v22
	v_max_i32_e32 v28, v29, v13
	v_min_i32_e32 v13, v29, v13
	v_max_i32_e32 v29, v20, v18
	v_min_i32_e32 v18, v20, v18
	v_max_i32_e32 v20, v23, v17
	v_min_i32_e32 v17, v23, v17
	v_max_i32_e32 v23, v16, v24
	v_min_i32_e32 v16, v16, v24
	v_max_i32_e32 v24, v14, v19
	v_min_i32_e32 v14, v14, v19
	v_max_i32_e32 v19, v12, v25
	v_min_i32_e32 v12, v12, v25
	v_max_i32_e32 v25, v27, v26
	v_min_i32_e32 v26, v27, v26
	v_max_i32_e32 v27, v15, v9
	v_min_i32_e32 v9, v15, v9
	v_max_i32_e32 v22, v6, v5
	v_min_i32_e32 v5, v6, v5
	v_max_i32_e32 v6, v8, v21
	v_min_i32_e32 v8, v8, v21
	v_max_i32_e32 v21, v33, v11
	v_min_i32_e32 v11, v33, v11
	v_max_i32_e32 v33, v10, v7
	v_min_i32_e32 v7, v10, v7
	v_max_i32_e32 v15, v28, v20
	v_min_i32_e32 v20, v28, v20
	v_max_i32_e32 v28, v29, v23
	v_min_i32_e32 v23, v29, v23
	v_max_i32_e32 v29, v13, v17
	v_min_i32_e32 v13, v13, v17
	v_max_i32_e32 v17, v18, v16
	v_min_i32_e32 v16, v18, v16
	v_max_i32_e32 v18, v26, v14
	v_min_i32_e32 v14, v26, v14
; __device__ __forceinline__ void p6_sort16(int (&a)[16]) {
;     P6_CE(a[0], a[1]); P6_CE(a[3], a[2]); P6_CE(a[4], a[5]); P6_CE(a[7], a[6]); P6_CE(a[8], a[9]); P6_CE(a[11], a[10]); P6_CE(a[12], a[13]); P6_CE(a[15], a[14]); P6_CE(a[0], a[2]); P6_CE(a[1], a[3]); P6_CE(a[6], a[4]); P6_CE(a[7], a[5]); P6_CE(a[8], a[10]); P6_CE(a[9], a[11]); P6_CE(a[14], a[12]); P6_CE(a[15], a[13]); P6_CE(a[0], a[1]); P6_CE(a[2], a[3]); P6_CE(a[5], a[4]); P6_CE(a[7], a[6]); P6_CE(a[8], a[9]); P6_CE(a[10], a[11]); P6_CE(a[13], a[12]); P6_CE(a[15], a[14]); P6_CE(a[0], a[4]); P6_CE(a[1], a[5]); P6_CE(a[2], a[6]); P6_CE(a[3], a[7]); P6_CE(a[12], a[8]); P6_CE(a[13], a[9]); P6_CE(a[14], a[10]); P6_CE(a[15], a[11]); P6_CE(a[0], a[2]); P6_CE(a[1], a[3]); P6_CE(a[4], a[6]); P6_CE(a[5], a[7]); P6_CE(a[10], a[8]); P6_CE(a[11], a[9]); P6_CE(a[14], a[12]); P6_CE(a[15], a[13]); P6_CE(a[0], a[1]); P6_CE(a[2], a[3]); P6_CE(a[4], a[5]); P6_CE(a[6], a[7]); P6_CE(a[9], a[8]); P6_CE(a[11], a[10]); P6_CE(a[13], a[12]); P6_CE(a[15], a[14]); P6_CE(a[0], a[8]); P6_CE(a[1], a[9]); P6_CE(a[2], a[10]); P6_CE(a[3], a[11]); P6_CE(a[4], a[12]); P6_CE(a[5], a[13]); P6_CE(a[6], a[14]); P6_CE(a[7], a[15]); P6_CE(a[0], a[4]); P6_CE(a[1], a[5]); P6_CE(a[2], a[6]); P6_CE(a[3], a[7]); P6_CE(a[8], a[12]); P6_CE(a[9], a[13]); P6_CE(a[10], a[14]); P6_CE(a[11], a[15]); P6_CE(a[0], a[2]); P6_CE(a[1], a[3]); P6_CE(a[4], a[6]); P6_CE(a[5], a[7]); P6_CE(a[8], a[10]); P6_CE(a[9], a[11]); P6_CE(a[12], a[14]); P6_CE(a[13], a[15]); P6_CE(a[0], a[1]); P6_CE(a[2], a[3]); P6_CE(a[4], a[5]); P6_CE(a[6], a[7]); P6_CE(a[8], a[9]); P6_CE(a[10], a[11]); P6_CE(a[12], a[13]); P6_CE(a[14], a[15]);
; }
; __device__ __forceinline__ void p6_merge16(int (&a)[16]) {
;     P6_CE(a[0], a[8]); P6_CE(a[1], a[9]); P6_CE(a[2], a[10]); P6_CE(a[3], a[11]); P6_CE(a[4], a[12]); P6_CE(a[5], a[13]); P6_CE(a[6], a[14]); P6_CE(a[7], a[15]); P6_CE(a[0], a[4]); P6_CE(a[1], a[5]); P6_CE(a[2], a[6]); P6_CE(a[3], a[7]); P6_CE(a[8], a[12]); P6_CE(a[9], a[13]); P6_CE(a[10], a[14]); P6_CE(a[11], a[15]); P6_CE(a[0], a[2]); P6_CE(a[1], a[3]); P6_CE(a[4], a[6]); P6_CE(a[5], a[7]); P6_CE(a[8], a[10]); P6_CE(a[9], a[11]); P6_CE(a[12], a[14]); P6_CE(a[13], a[15]); P6_CE(a[0], a[1]); P6_CE(a[2], a[3]); P6_CE(a[4], a[5]); P6_CE(a[6], a[7]); P6_CE(a[8], a[9]); P6_CE(a[10], a[11]); P6_CE(a[12], a[13]); P6_CE(a[14], a[15]);
; }
	v_max_i32_e32 v26, v9, v12
	v_min_i32_e32 v9, v9, v12
	v_max_i32_e32 v12, v25, v24
	v_min_i32_e32 v24, v25, v24
	v_max_i32_e32 v25, v27, v19
	v_min_i32_e32 v19, v27, v19
	v_max_i32_e32 v10, v22, v21
	v_min_i32_e32 v21, v22, v21
	v_max_i32_e32 v22, v6, v33
	v_min_i32_e32 v6, v6, v33
	v_max_i32_e32 v33, v5, v11
	v_min_i32_e32 v5, v5, v11
	v_max_i32_e32 v11, v8, v7
	v_min_i32_e32 v7, v8, v7
	v_max_i32_e32 v27, v15, v28
	v_min_i32_e32 v15, v15, v28
	v_max_i32_e32 v28, v20, v23
	v_min_i32_e32 v20, v20, v23
	v_max_i32_e32 v23, v29, v17
	v_min_i32_e32 v17, v29, v17
	v_max_i32_e32 v29, v13, v16
	v_min_i32_e32 v13, v13, v16
	v_max_i32_e32 v16, v9, v14
	v_min_i32_e32 v9, v9, v14
	v_max_i32_e32 v14, v26, v18
	v_min_i32_e32 v18, v26, v18
	v_max_i32_e32 v26, v19, v24
	v_min_i32_e32 v19, v19, v24
	v_max_i32_e32 v24, v25, v12
	v_min_i32_e32 v12, v25, v12
	v_max_i32_e32 v8, v10, v22
	v_min_i32_e32 v10, v10, v22
	v_max_i32_e32 v22, v21, v6
	v_min_i32_e32 v6, v21, v6
	v_max_i32_e32 v21, v33, v11
	v_min_i32_e32 v11, v33, v11
	v_max_i32_e32 v33, v5, v7
	v_min_i32_e32 v5, v5, v7
	v_max_i32_e32 v25, v27, v9
	v_min_i32_e32 v9, v27, v9
	v_max_i32_e32 v27, v15, v16
	v_min_i32_e32 v15, v15, v16
	v_max_i32_e32 v16, v28, v18
	v_min_i32_e32 v18, v28, v18
	v_max_i32_e32 v28, v20, v14
	v_min_i32_e32 v14, v20, v14
	v_max_i32_e32 v20, v23, v19
	v_min_i32_e32 v19, v23, v19
	v_max_i32_e32 v23, v17, v26
	v_min_i32_e32 v17, v17, v26
	v_max_i32_e32 v26, v29, v12
	v_min_i32_e32 v12, v29, v12
	v_max_i32_e32 v29, v13, v24
	v_min_i32_e32 v13, v13, v24
	v_max_i32_e32 v7, v5, v4
	v_max_i32_e32 v24, v25, v20
	v_min_i32_e32 v20, v25, v20
	v_max_i32_e32 v25, v27, v23
	v_min_i32_e32 v23, v27, v23
	v_max_i32_e32 v27, v16, v26
	v_min_i32_e32 v16, v16, v26
	v_max_i32_e32 v26, v28, v29
	v_min_i32_e32 v28, v28, v29
	v_max_i32_e32 v29, v9, v19
	v_min_i32_e32 v9, v9, v19
	v_max_i32_e32 v19, v15, v17
	v_min_i32_e32 v15, v15, v17
	v_max_i32_e32 v17, v18, v12
	v_min_i32_e32 v12, v18, v12
	v_max_i32_e32 v18, v14, v13
	v_min_i32_e32 v13, v14, v13
	v_min_i32_e32 v4, v5, v4
	v_max_i32_e32 v5, v8, v21
	v_min_i32_e32 v8, v8, v21
	v_max_i32_e32 v21, v10, v11
	v_min_i32_e32 v10, v10, v11
	v_max_i32_e32 v11, v22, v33
	v_min_i32_e32 v22, v22, v33
	v_max_i32_e32 v33, v6, v7
	v_min_i32_e32 v6, v6, v7
	v_max_i32_e32 v14, v24, v27
	v_min_i32_e32 v24, v24, v27
	v_max_i32_e32 v27, v25, v26
	v_min_i32_e32 v25, v25, v26
	v_max_i32_e32 v26, v20, v16
	v_min_i32_e32 v16, v20, v16
	v_max_i32_e32 v20, v23, v28
	v_min_i32_e32 v23, v23, v28
	v_max_i32_e32 v28, v29, v17
	v_min_i32_e32 v17, v29, v17
	v_max_i32_e32 v29, v19, v18
	v_min_i32_e32 v18, v19, v18
	v_max_i32_e32 v19, v9, v12
	v_min_i32_e32 v9, v9, v12
	v_max_i32_e32 v12, v15, v13
	v_min_i32_e32 v13, v15, v13
	v_max_i32_e32 v7, v5, v11
	v_min_i32_e32 v5, v5, v11
	v_max_i32_e32 v11, v21, v33
	v_min_i32_e32 v21, v21, v33
	v_max_i32_e32 v33, v8, v22
	v_min_i32_e32 v8, v8, v22
	v_max_i32_e32 v22, v10, v6
	v_min_i32_e32 v6, v10, v6
	v_max_i32_e32 v15, v14, v27
	v_min_i32_e32 v14, v14, v27
	v_max_i32_e32 v27, v24, v25
	v_min_i32_e32 v24, v24, v25
	v_max_i32_e32 v25, v26, v20
	v_min_i32_e32 v20, v26, v20
	v_max_i32_e32 v26, v16, v23
	v_min_i32_e32 v16, v16, v23
	v_min_i32_e32 v23, v28, v29
	v_min_i32_e32 v30, v17, v18
	v_min_i32_e32 v31, v19, v12
	v_min_i32_e32 v32, v9, v13
	v_min_i32_e32 v10, v7, v11
	v_min_i32_e32 v34, v5, v21
	v_min_i32_e32 v35, v33, v22
	v_min_i32_e32 v36, v8, v6
	v_max_i32_e32 v4, v16, v4
	v_max3_i32 v16, v28, v29, v36
	v_max3_i32 v6, v23, v8, v6
	v_max3_i32 v8, v17, v18, v35
	v_max3_i32 v17, v30, v33, v22
	v_max3_i32 v12, v19, v12, v34
	v_max3_i32 v5, v31, v5, v21
	v_max3_i32 v9, v9, v13, v10
	v_max3_i32 v7, v32, v7, v11
	v_max_i32_e32 v10, v15, v16
	v_min_i32_e32 v11, v15, v16
	v_max_i32_e32 v13, v14, v6
	v_min_i32_e32 v6, v14, v6
	v_max_i32_e32 v14, v27, v8
	v_min_i32_e32 v8, v27, v8
	v_max_i32_e32 v15, v24, v17
	v_min_i32_e32 v16, v24, v17
	v_max_i32_e32 v17, v25, v12
	v_min_i32_e32 v12, v25, v12
	v_max_i32_e32 v18, v20, v5
	v_min_i32_e32 v5, v20, v5
	v_max_i32_e32 v19, v26, v9
	v_min_i32_e32 v9, v26, v9
	v_max_i32_e32 v20, v4, v7
	v_min_i32_e32 v4, v4, v7
	v_max_i32_e32 v7, v10, v17
	v_min_i32_e32 v10, v10, v17
	v_max_i32_e32 v17, v13, v18
	v_min_i32_e32 v13, v13, v18
	v_max_i32_e32 v18, v14, v19
	v_min_i32_e32 v14, v14, v19
	v_max_i32_e32 v19, v15, v20
	v_min_i32_e32 v15, v15, v20
	v_max_i32_e32 v20, v11, v12
	v_min_i32_e32 v11, v11, v12
	v_max_i32_e32 v12, v6, v5
	v_min_i32_e32 v5, v6, v5
	v_max_i32_e32 v6, v8, v9
	v_min_i32_e32 v8, v8, v9
	v_max_i32_e32 v9, v16, v4
	v_min_i32_e32 v4, v16, v4
	v_max_i32_e32 v16, v7, v18
	v_min_i32_e32 v7, v7, v18
	v_max_i32_e32 v18, v17, v19
	v_min_i32_e32 v17, v17, v19
	v_max_i32_e32 v19, v10, v14
	v_min_i32_e32 v10, v10, v14
	v_max_i32_e32 v14, v13, v15
	v_min_i32_e32 v13, v13, v15
	v_max_i32_e32 v15, v20, v6
	v_min_i32_e32 v6, v20, v6
	v_max_i32_e32 v20, v12, v9
	v_min_i32_e32 v9, v12, v9
	v_max_i32_e32 v12, v11, v8
	v_min_i32_e32 v8, v11, v8
	v_max_i32_e32 v11, v5, v4
	v_min_i32_e32 v4, v5, v4
	v_max_i32_e32 v5, v16, v18
	v_min_i32_e32 v16, v16, v18
	v_max_i32_e32 v18, v7, v17
	v_min_i32_e32 v7, v7, v17
	v_max_i32_e32 v17, v19, v14
	v_min_i32_e32 v14, v19, v14
	v_max_i32_e32 v19, v10, v13
	v_min_i32_e32 v10, v10, v13
	v_max_i32_e32 v13, v15, v20
	v_min_i32_e32 v15, v15, v20
	v_max_i32_e32 v20, v6, v9
	v_min_i32_e32 v6, v6, v9
	v_max_i32_e32 v9, v12, v11
	v_min_i32_e32 v11, v12, v11
	v_max_i32_e32 v12, v8, v4
	v_min_i32_e32 v4, v8, v4
	ds_bpermute_b32 v8, v83, v4
	ds_bpermute_b32 v21, v83, v12
	ds_bpermute_b32 v22, v83, v11
	ds_bpermute_b32 v23, v83, v9
	ds_bpermute_b32 v24, v83, v6
	ds_bpermute_b32 v25, v83, v20
	ds_bpermute_b32 v26, v83, v15
	ds_bpermute_b32 v27, v83, v13
	ds_bpermute_b32 v28, v83, v10
	ds_bpermute_b32 v29, v83, v19
	ds_bpermute_b32 v30, v83, v14
	ds_bpermute_b32 v31, v83, v17
	ds_bpermute_b32 v32, v83, v7
	ds_bpermute_b32 v33, v83, v18
	ds_bpermute_b32 v34, v83, v16
	ds_bpermute_b32 v35, v83, v5
	s_waitcnt lgkmcnt(14)
; __device__ __forceinline__ void p6_top16_partner(int (&a)[16]) {
;     int t[16];
; #pragma unroll
;     for (int i = 0; i < 16; ++i) t[i] = __shfl_xor(a[15 - i], 32);
; #pragma unroll
;     for (int i = 0; i < 16; ++i) a[i] = max(a[i], t[i]);
;     p6_merge16(a);
; template <bool FROM_LDS>
; __device__ __forceinline__ void p6_task(unsigned char* ws, int lane, int h, int tok, const bf16* qrow_g, const LAS unsigned char* qrow_l, int rsw, LAS unsigned char* scr) {
;     ...
;         p6_sort16(ca); p6_sort16(cb); p6_top16(ca, cb); p6_top16_partner(ca);
;         asm volatile("s_waitcnt lgkmcnt(0)" ::: "memory");
;         float top[16], gs = 0.f;
;         const float smax = key2f(ca[0] & ~255);
; #pragma unroll
;         for (int i = 0; i < 16; ++i) ca[i] = ((ca[i] & 255) << 24) | (int)((unsigned)ca[i] >> 8);
;         p6_sort16(ca);
	v_max_i32_e32 v5, v5, v8
	v_max_i32_e32 v8, v16, v21
	s_waitcnt lgkmcnt(13)
	v_max_i32_e32 v16, v18, v22
	s_waitcnt lgkmcnt(12)
	v_max_i32_e32 v7, v7, v23
	s_waitcnt lgkmcnt(11)
	v_max_i32_e32 v17, v17, v24
	s_waitcnt lgkmcnt(10)
	v_max_i32_e32 v14, v14, v25
	s_waitcnt lgkmcnt(9)
	v_max_i32_e32 v18, v19, v26
	s_waitcnt lgkmcnt(8)
	v_max_i32_e32 v10, v10, v27
	s_waitcnt lgkmcnt(7)
	v_max_i32_e32 v13, v13, v28
	s_waitcnt lgkmcnt(6)
	v_max_i32_e32 v15, v15, v29
	s_waitcnt lgkmcnt(5)
	v_max_i32_e32 v19, v20, v30
	s_waitcnt lgkmcnt(4)
	v_max_i32_e32 v6, v6, v31
	s_waitcnt lgkmcnt(3)
	v_max_i32_e32 v9, v9, v32
	s_waitcnt lgkmcnt(2)
	v_max_i32_e32 v11, v11, v33
	s_waitcnt lgkmcnt(1)
	v_max_i32_e32 v12, v12, v34
	s_waitcnt lgkmcnt(0)
	v_max_i32_e32 v4, v4, v35
	v_max_i32_e32 v20, v5, v13
	v_min_i32_e32 v5, v5, v13
	v_max_i32_e32 v13, v8, v15
	v_min_i32_e32 v8, v8, v15
	v_max_i32_e32 v15, v16, v19
	v_min_i32_e32 v16, v16, v19
	v_max_i32_e32 v19, v7, v6
	v_min_i32_e32 v6, v7, v6
	v_max_i32_e32 v7, v17, v9
	v_min_i32_e32 v9, v17, v9
	v_max_i32_e32 v17, v14, v11
	v_min_i32_e32 v11, v14, v11
	v_max_i32_e32 v14, v18, v12
	v_min_i32_e32 v12, v18, v12
	v_max_i32_e32 v18, v10, v4
	v_min_i32_e32 v4, v10, v4
	v_max_i32_e32 v10, v20, v7
	v_min_i32_e32 v7, v20, v7
	v_max_i32_e32 v20, v13, v17
	v_min_i32_e32 v13, v13, v17
	v_max_i32_e32 v17, v15, v14
	v_min_i32_e32 v14, v15, v14
	v_max_i32_e32 v15, v19, v18
	v_min_i32_e32 v18, v19, v18
	v_max_i32_e32 v19, v5, v9
	v_min_i32_e32 v5, v5, v9
	v_max_i32_e32 v9, v8, v11
	v_min_i32_e32 v8, v8, v11
	v_max_i32_e32 v11, v16, v12
	v_min_i32_e32 v12, v16, v12
	v_max_i32_e32 v16, v6, v4
	v_min_i32_e32 v4, v6, v4
	v_max_i32_e32 v6, v10, v17
	v_min_i32_e32 v10, v10, v17
	v_max_i32_e32 v17, v20, v15
	v_min_i32_e32 v15, v20, v15
	v_max_i32_e32 v20, v7, v14
	v_min_i32_e32 v7, v7, v14
	v_max_i32_e32 v14, v13, v18
	v_min_i32_e32 v13, v13, v18
	v_max_i32_e32 v18, v19, v11
	v_min_i32_e32 v11, v19, v11
	v_max_i32_e32 v19, v9, v16
	v_min_i32_e32 v9, v9, v16
	v_max_i32_e32 v16, v5, v12
	v_min_i32_e32 v5, v5, v12
	v_max_i32_e32 v12, v8, v4
	v_min_i32_e32 v4, v8, v4
	v_max_i32_e32 v8, v6, v17
	v_min_i32_e32 v6, v6, v17
	v_max_i32_e32 v17, v10, v15
	v_min_i32_e32 v10, v10, v15
	v_max_i32_e32 v15, v20, v14
	v_min_i32_e32 v14, v20, v14
	v_max_i32_e32 v20, v7, v13
	v_min_i32_e32 v7, v7, v13
	v_max_i32_e32 v13, v18, v19
	v_min_i32_e32 v18, v18, v19
	v_max_i32_e32 v19, v11, v9
	v_min_i32_e32 v9, v11, v9
	v_max_i32_e32 v11, v16, v12
	v_min_i32_e32 v12, v16, v12
	v_max_i32_e32 v16, v5, v4
	v_min_i32_e32 v4, v5, v4
	v_alignbit_b32 v5, v8, v8, 8
	v_alignbit_b32 v6, v6, v6, 8
	v_alignbit_b32 v17, v17, v17, 8
	v_alignbit_b32 v10, v10, v10, 8
	v_alignbit_b32 v15, v15, v15, 8
	v_alignbit_b32 v14, v14, v14, 8
	v_alignbit_b32 v20, v20, v20, 8
	v_alignbit_b32 v7, v7, v7, 8
	v_alignbit_b32 v13, v13, v13, 8
	v_alignbit_b32 v18, v18, v18, 8
	v_alignbit_b32 v19, v19, v19, 8
	v_alignbit_b32 v9, v9, v9, 8
	v_alignbit_b32 v11, v11, v11, 8
	v_alignbit_b32 v12, v12, v12, 8
	v_alignbit_b32 v16, v16, v16, 8
	v_alignbit_b32 v4, v4, v4, 8
	v_max_i32_e32 v21, v5, v6
	v_min_i32_e32 v5, v5, v6
	v_max_i32_e32 v6, v10, v17
	v_min_i32_e32 v10, v10, v17
	v_max_i32_e32 v17, v15, v14
	v_min_i32_e32 v14, v15, v14
	v_max_i32_e32 v15, v7, v20
	v_min_i32_e32 v7, v7, v20
	v_max_i32_e32 v20, v13, v18
	v_min_i32_e32 v13, v13, v18
	v_max_i32_e32 v18, v9, v19
	v_min_i32_e32 v9, v9, v19
	v_max_i32_e32 v19, v11, v12
	v_min_i32_e32 v11, v11, v12
	v_max_i32_e32 v12, v4, v16
	v_min_i32_e32 v4, v4, v16
	v_max_i32_e32 v16, v21, v10
	v_min_i32_e32 v10, v21, v10
	v_max_i32_e32 v21, v5, v6
	v_min_i32_e32 v5, v5, v6
	v_max_i32_e32 v6, v7, v17
	v_min_i32_e32 v7, v7, v17
	v_max_i32_e32 v17, v15, v14
	v_min_i32_e32 v14, v15, v14
	v_max_i32_e32 v15, v20, v9
	v_min_i32_e32 v9, v20, v9
	v_max_i32_e32 v20, v13, v18
	v_min_i32_e32 v13, v13, v18
	v_max_i32_e32 v18, v4, v19
	v_min_i32_e32 v4, v4, v19
	v_max_i32_e32 v19, v12, v11
	v_min_i32_e32 v11, v12, v11
	v_max_i32_e32 v12, v16, v21
	v_min_i32_e32 v16, v16, v21
	v_max_i32_e32 v21, v10, v5
	v_min_i32_e32 v5, v10, v5
	v_max_i32_e32 v10, v14, v7
	v_min_i32_e32 v7, v14, v7
	v_max_i32_e32 v14, v17, v6
	v_min_i32_e32 v6, v17, v6
	v_max_i32_e32 v17, v15, v20
	v_min_i32_e32 v15, v15, v20
	v_max_i32_e32 v20, v9, v13
	v_min_i32_e32 v9, v9, v13
	v_max_i32_e32 v13, v11, v4
	v_min_i32_e32 v4, v11, v4
	v_max_i32_e32 v11, v19, v18
	v_min_i32_e32 v18, v19, v18
	v_max_i32_e32 v19, v12, v7
	v_min_i32_e32 v7, v12, v7
	v_max_i32_e32 v12, v16, v10
	v_min_i32_e32 v10, v16, v10
	v_max_i32_e32 v16, v21, v6
	v_min_i32_e32 v6, v21, v6
	v_max_i32_e32 v21, v5, v14
	v_min_i32_e32 v5, v5, v14
	v_max_i32_e32 v14, v4, v17
	v_min_i32_e32 v4, v4, v17
	v_max_i32_e32 v17, v13, v15
	v_min_i32_e32 v13, v13, v15
	v_max_i32_e32 v15, v18, v20
	v_min_i32_e32 v18, v18, v20
	v_max_i32_e32 v20, v11, v9
	v_min_i32_e32 v9, v11, v9
	v_max_i32_e32 v11, v19, v16
	v_min_i32_e32 v16, v19, v16
	v_max_i32_e32 v19, v12, v21
	v_min_i32_e32 v12, v12, v21
	v_max_i32_e32 v21, v7, v6
	v_min_i32_e32 v6, v7, v6
	v_max_i32_e32 v7, v10, v5
	v_min_i32_e32 v5, v10, v5
	v_max_i32_e32 v10, v18, v4
	v_min_i32_e32 v4, v18, v4
	v_max_i32_e32 v18, v9, v13
	v_min_i32_e32 v9, v9, v13
	v_max_i32_e32 v13, v15, v14
	v_min_i32_e32 v14, v15, v14
	v_max_i32_e32 v15, v20, v17
	v_min_i32_e32 v17, v20, v17
	v_max_i32_e32 v20, v11, v19
	v_min_i32_e32 v11, v11, v19
	v_max_i32_e32 v19, v16, v12
	v_min_i32_e32 v12, v16, v12
	v_max_i32_e32 v16, v21, v7
	v_min_i32_e32 v7, v21, v7
	v_max_i32_e32 v21, v6, v5
	v_min_i32_e32 v5, v6, v5
	v_max_i32_e32 v6, v9, v4
	v_min_i32_e32 v4, v9, v4
	v_max_i32_e32 v9, v18, v10
	v_min_i32_e32 v10, v18, v10
; __device__ __forceinline__ void p6_sort16(int (&a)[16]) {
;     P6_CE(a[0], a[1]); P6_CE(a[3], a[2]); P6_CE(a[4], a[5]); P6_CE(a[7], a[6]); P6_CE(a[8], a[9]); P6_CE(a[11], a[10]); P6_CE(a[12], a[13]); P6_CE(a[15], a[14]); P6_CE(a[0], a[2]); P6_CE(a[1], a[3]); P6_CE(a[6], a[4]); P6_CE(a[7], a[5]); P6_CE(a[8], a[10]); P6_CE(a[9], a[11]); P6_CE(a[14], a[12]); P6_CE(a[15], a[13]); P6_CE(a[0], a[1]); P6_CE(a[2], a[3]); P6_CE(a[5], a[4]); P6_CE(a[7], a[6]); P6_CE(a[8], a[9]); P6_CE(a[10], a[11]); P6_CE(a[13], a[12]); P6_CE(a[15], a[14]); P6_CE(a[0], a[4]); P6_CE(a[1], a[5]); P6_CE(a[2], a[6]); P6_CE(a[3], a[7]); P6_CE(a[12], a[8]); P6_CE(a[13], a[9]); P6_CE(a[14], a[10]); P6_CE(a[15], a[11]); P6_CE(a[0], a[2]); P6_CE(a[1], a[3]); P6_CE(a[4], a[6]); P6_CE(a[5], a[7]); P6_CE(a[10], a[8]); P6_CE(a[11], a[9]); P6_CE(a[14], a[12]); P6_CE(a[15], a[13]); P6_CE(a[0], a[1]); P6_CE(a[2], a[3]); P6_CE(a[4], a[5]); P6_CE(a[6], a[7]); P6_CE(a[9], a[8]); P6_CE(a[11], a[10]); P6_CE(a[13], a[12]); P6_CE(a[15], a[14]); P6_CE(a[0], a[8]); P6_CE(a[1], a[9]); P6_CE(a[2], a[10]); P6_CE(a[3], a[11]); P6_CE(a[4], a[12]); P6_CE(a[5], a[13]); P6_CE(a[6], a[14]); P6_CE(a[7], a[15]); P6_CE(a[0], a[4]); P6_CE(a[1], a[5]); P6_CE(a[2], a[6]); P6_CE(a[3], a[7]); P6_CE(a[8], a[12]); P6_CE(a[9], a[13]); P6_CE(a[10], a[14]); P6_CE(a[11], a[15]); P6_CE(a[0], a[2]); P6_CE(a[1], a[3]); P6_CE(a[4], a[6]); P6_CE(a[5], a[7]); P6_CE(a[8], a[10]); P6_CE(a[9], a[11]); P6_CE(a[12], a[14]); P6_CE(a[13], a[15]); P6_CE(a[0], a[1]); P6_CE(a[2], a[3]); P6_CE(a[4], a[5]); P6_CE(a[6], a[7]); P6_CE(a[8], a[9]); P6_CE(a[10], a[11]); P6_CE(a[12], a[13]); P6_CE(a[14], a[15]);
; }
; template <bool FROM_LDS>
; __device__ __forceinline__ void p6_task(unsigned char* ws, int lane, int h, int tok, const bf16* qrow_g, const LAS unsigned char* qrow_l, int rsw, LAS unsigned char* scr) {
;     ...
;         const float smax = key2f(ca[0] & ~255);
; #pragma unroll
;         for (int i = 0; i < 16; ++i) ca[i] = ((ca[i] & 255) << 24) | (int)((unsigned)ca[i] >> 8);
;         p6_sort16(ca);
; #pragma unroll
;         for (int i = 0; i < 16; ++i) ca[i] = (ca[i] << 8) | ((ca[i] >> 24) & 255);
; #pragma unroll
;         for (int i = 0; i < 16; ++i) { top[i] = key2f(ca[i] & ~255); }
; #pragma unroll
;         for (int i = 0; i < 16; ++i) { top[i] = __expf(top[i] - smax); gs += top[i]; }
	v_max_i32_e32 v18, v17, v14
	v_min_i32_e32 v14, v17, v14
	v_max_i32_e32 v17, v15, v13
	v_min_i32_e32 v13, v15, v13
	v_max_i32_e32 v15, v20, v4
	v_min_i32_e32 v4, v20, v4
	v_max_i32_e32 v20, v11, v6
	v_min_i32_e32 v6, v11, v6
	v_max_i32_e32 v11, v19, v10
	v_min_i32_e32 v10, v19, v10
	v_max_i32_e32 v19, v12, v9
	v_min_i32_e32 v9, v12, v9
	v_max_i32_e32 v12, v16, v14
	v_min_i32_e32 v14, v16, v14
	v_max_i32_e32 v16, v7, v18
	v_min_i32_e32 v7, v7, v18
	v_max_i32_e32 v18, v21, v13
	v_min_i32_e32 v13, v21, v13
	v_max_i32_e32 v21, v5, v17
	v_min_i32_e32 v5, v5, v17
	v_max_i32_e32 v17, v15, v12
	v_min_i32_e32 v12, v15, v12
	v_max_i32_e32 v15, v20, v16
	v_min_i32_e32 v16, v20, v16
	v_max_i32_e32 v20, v11, v18
	v_min_i32_e32 v11, v11, v18
	v_max_i32_e32 v18, v19, v21
	v_min_i32_e32 v19, v19, v21
	v_max_i32_e32 v21, v4, v14
	v_min_i32_e32 v4, v4, v14
	v_max_i32_e32 v14, v6, v7
	v_min_i32_e32 v6, v6, v7
	v_max_i32_e32 v7, v10, v13
	v_min_i32_e32 v10, v10, v13
	v_max_i32_e32 v13, v9, v5
	v_min_i32_e32 v5, v9, v5
	v_max_i32_e32 v9, v17, v20
	v_min_i32_e32 v17, v17, v20
	v_max_i32_e32 v20, v15, v18
	v_min_i32_e32 v15, v15, v18
	v_max_i32_e32 v18, v12, v11
	v_min_i32_e32 v11, v12, v11
	v_max_i32_e32 v12, v16, v19
	v_min_i32_e32 v16, v16, v19
	v_max_i32_e32 v19, v21, v7
	v_min_i32_e32 v7, v21, v7
	v_max_i32_e32 v21, v14, v13
	v_min_i32_e32 v13, v14, v13
	v_max_i32_e32 v14, v4, v10
	v_min_i32_e32 v4, v4, v10
	v_max_i32_e32 v10, v6, v5
	v_min_i32_e32 v5, v6, v5
	v_max_i32_e32 v6, v9, v20
	v_min_i32_e32 v9, v9, v20
	v_max_i32_e32 v20, v17, v15
	v_min_i32_e32 v15, v17, v15
	v_max_i32_e32 v17, v18, v12
	v_min_i32_e32 v12, v18, v12
	v_max_i32_e32 v18, v11, v16
	v_min_i32_e32 v11, v11, v16
	v_max_i32_e32 v16, v19, v21
	v_min_i32_e32 v19, v19, v21
	v_max_i32_e32 v21, v7, v13
	v_min_i32_e32 v7, v7, v13
	v_max_i32_e32 v13, v14, v10
	v_min_i32_e32 v10, v14, v10
	v_max_i32_e32 v14, v4, v5
	v_min_i32_e32 v4, v4, v5
	v_alignbit_b32 v5, v6, v6, 24
	v_alignbit_b32 v6, v9, v9, 24
	v_and_b32_e32 v9, 0xffffff00, v5
	v_ashrrev_i32_e32 v22, 31, v5
	v_alignbit_b32 v20, v20, v20, 24
	v_bitop3_b32 v9, v22, v9, s51 bitop3:0x6c
	v_and_b32_e32 v22, 0xffffff00, v6
	v_ashrrev_i32_e32 v23, 31, v6
	v_alignbit_b32 v15, v15, v15, 24
	v_bitop3_b32 v22, v23, v22, s51 bitop3:0x6c
	v_and_b32_e32 v23, 0xffffff00, v20
	v_ashrrev_i32_e32 v24, 31, v20
	v_alignbit_b32 v17, v17, v17, 24
	v_bitop3_b32 v23, v24, v23, s51 bitop3:0x6c
	v_and_b32_e32 v24, 0xffffff00, v15
	v_ashrrev_i32_e32 v25, 31, v15
	v_alignbit_b32 v12, v12, v12, 24
	v_bitop3_b32 v24, v25, v24, s51 bitop3:0x6c
	v_and_b32_e32 v25, 0xffffff00, v17
	v_ashrrev_i32_e32 v26, 31, v17
	v_alignbit_b32 v18, v18, v18, 24
	v_bitop3_b32 v25, v26, v25, s51 bitop3:0x6c
	v_and_b32_e32 v26, 0xffffff00, v12
	v_ashrrev_i32_e32 v27, 31, v12
	v_alignbit_b32 v11, v11, v11, 24
	v_bitop3_b32 v26, v27, v26, s51 bitop3:0x6c
	v_and_b32_e32 v27, 0xffffff00, v18
	v_ashrrev_i32_e32 v28, 31, v18
	v_alignbit_b32 v16, v16, v16, 24
	v_bitop3_b32 v27, v28, v27, s51 bitop3:0x6c
	v_and_b32_e32 v28, 0xffffff00, v11
	v_ashrrev_i32_e32 v29, 31, v11
	v_alignbit_b32 v19, v19, v19, 24
	v_bitop3_b32 v28, v29, v28, s51 bitop3:0x6c
	v_and_b32_e32 v29, 0xffffff00, v16
	v_ashrrev_i32_e32 v30, 31, v16
	v_alignbit_b32 v21, v21, v21, 24
	v_bitop3_b32 v29, v30, v29, s51 bitop3:0x6c
	v_and_b32_e32 v30, 0xffffff00, v19
	v_ashrrev_i32_e32 v31, 31, v19
	v_alignbit_b32 v13, v13, v13, 24
	v_bitop3_b32 v30, v31, v30, s51 bitop3:0x6c
	v_and_b32_e32 v31, 0xffffff00, v21
	v_ashrrev_i32_e32 v32, 31, v21
	v_alignbit_b32 v10, v10, v10, 24
	v_bitop3_b32 v31, v32, v31, s51 bitop3:0x6c
	v_and_b32_e32 v32, 0xffffff00, v13
	v_ashrrev_i32_e32 v33, 31, v13
	v_alignbit_b32 v14, v14, v14, 24
	v_bitop3_b32 v32, v33, v32, s51 bitop3:0x6c
	v_and_b32_e32 v33, 0xffffff00, v10
	v_ashrrev_i32_e32 v34, 31, v10
	v_alignbit_b32 v4, v4, v4, 24
	v_bitop3_b32 v33, v34, v33, s51 bitop3:0x6c
	v_and_b32_e32 v34, 0xffffff00, v14
	v_ashrrev_i32_e32 v35, 31, v14
	v_bitop3_b32 v34, v35, v34, s51 bitop3:0x6c
	v_and_b32_e32 v35, 0xffffff00, v4
	v_ashrrev_i32_e32 v36, 31, v4
	v_bitop3_b32 v35, v36, v35, s51 bitop3:0x6c
	v_and_b32_e32 v36, 0xffffff00, v8
	v_ashrrev_i32_e32 v8, 31, v8
	v_and_b32_e32 v8, 0x7fffffff, v8
	v_alignbit_b32 v7, v7, v7, 24
	v_xor_b32_e32 v8, v8, v36
	v_ashrrev_i32_e32 v38, 31, v7
	v_sub_f32_e32 v9, v9, v8
	v_and_b32_e32 v37, 0xffffff00, v7
	v_and_b32_e32 v38, 0x7fffffff, v38
	v_mul_f32_e32 v9, 0x3fb8aa3b, v9
	v_xor_b32_e32 v36, v38, v37
	v_exp_f32_e32 v37, v9
	v_sub_f32_e32 v9, v22, v8
	v_mul_f32_e32 v9, 0x3fb8aa3b, v9
	v_exp_f32_e32 v22, v9
	v_sub_f32_e32 v9, v23, v8
	v_mul_f32_e32 v9, 0x3fb8aa3b, v9
	v_exp_f32_e32 v23, v9
	v_sub_f32_e32 v9, v24, v8
	v_mul_f32_e32 v9, 0x3fb8aa3b, v9
	v_sub_f32_e32 v25, v25, v8
	v_exp_f32_e32 v24, v9
	v_mul_f32_e32 v25, 0x3fb8aa3b, v25
	v_sub_f32_e32 v26, v26, v8
	v_add_f32_e32 v9, 0, v37
	v_exp_f32_e32 v25, v25
	v_mul_f32_e32 v26, 0x3fb8aa3b, v26
	v_sub_f32_e32 v27, v27, v8
	v_add_f32_e32 v9, v22, v9
	v_exp_f32_e32 v26, v26
	v_mul_f32_e32 v27, 0x3fb8aa3b, v27
	v_sub_f32_e32 v28, v28, v8
	v_add_f32_e32 v9, v23, v9
	v_exp_f32_e32 v27, v27
	v_mul_f32_e32 v28, 0x3fb8aa3b, v28
	v_sub_f32_e32 v29, v29, v8
	v_add_f32_e32 v9, v24, v9
	v_exp_f32_e32 v28, v28
; template <bool FROM_LDS>
; __device__ __forceinline__ void p6_task(unsigned char* ws, int lane, int h, int tok, const bf16* qrow_g, const LAS unsigned char* qrow_l, int rsw, LAS unsigned char* scr) {
;     ...
;         for (int i = 0; i < 16; ++i) { top[i] = __expf(top[i] - smax); gs += top[i]; }
;         const float ginv = 1.0f / gs;
;         unsigned short* re = (unsigned short*)(RE16b + (size_t)tok * 256) + 2 * h + hh;
;         float gq[8];
; #pragma unroll
;         for (int r = 0; r < 8; ++r) { const int key = hh ? ca[r + 8] : ca[r]; const int ci = (key >> 4) & 15, cj = key & 15;
;             const int e = (int)scr[ci] * 128 + (int)scr[16 + cj];
;             re[r * 16] = (unsigned short)e; gq[r] = (hh ? top[r + 8] : top[r]) * ginv; }
;         float* rg = RG + ((size_t)tok * 8 + h) * 16 + 8 * hh;
;         *(f32x4*)rg = (f32x4){gq[0], gq[1], gq[2], gq[3]}; *(f32x4*)(rg + 4) = (f32x4){gq[4], gq[5], gq[6], gq[7]};
;         asm volatile("s_waitcnt lgkmcnt(0)" ::: "memory");
	v_mul_f32_e32 v29, 0x3fb8aa3b, v29
	v_sub_f32_e32 v30, v30, v8
	v_add_f32_e32 v9, v25, v9
	v_exp_f32_e32 v29, v29
	v_mul_f32_e32 v30, 0x3fb8aa3b, v30
	v_sub_f32_e32 v31, v31, v8
	v_add_f32_e32 v9, v26, v9
	v_exp_f32_e32 v30, v30
	v_mul_f32_e32 v31, 0x3fb8aa3b, v31
	v_sub_f32_e32 v36, v36, v8
	v_add_f32_e32 v9, v27, v9
	v_exp_f32_e32 v31, v31
	v_mul_f32_e32 v36, 0x3fb8aa3b, v36
	v_sub_f32_e32 v32, v32, v8
	v_add_f32_e32 v9, v28, v9
	v_exp_f32_e32 v36, v36
	v_mul_f32_e32 v32, 0x3fb8aa3b, v32
	v_sub_f32_e32 v33, v33, v8
	v_add_f32_e32 v9, v29, v9
	v_exp_f32_e32 v32, v32
	v_mul_f32_e32 v33, 0x3fb8aa3b, v33
	v_sub_f32_e32 v34, v34, v8
	v_add_f32_e32 v9, v30, v9
	v_exp_f32_e32 v33, v33
	v_mul_f32_e32 v34, 0x3fb8aa3b, v34
	v_sub_f32_e32 v8, v35, v8
	v_add_f32_e32 v9, v31, v9
	v_exp_f32_e32 v34, v34
	v_mul_f32_e32 v8, 0x3fb8aa3b, v8
	v_add_f32_e32 v9, v36, v9
	v_exp_f32_e32 v35, v8
	v_add_f32_e32 v8, v32, v9
	v_add_f32_e32 v8, v33, v8
	v_add_f32_e32 v8, v34, v8
	v_add_f32_e32 v8, v35, v8
	v_div_scale_f32 v9, s[2:3], v8, v8, 1.0
	v_rcp_f32_e32 v38, v9
	v_lshl_add_u32 v39, v84, 4, v90
	ds_write_b128 v39, v[0:3]
	v_ashrrev_i32_e32 v83, 31, v82
	v_fma_f32 v0, -v9, v38, 1.0
	v_fmac_f32_e32 v38, v0, v38
	v_div_scale_f32 v0, vcc, 1.0, v8, 1.0
	v_mul_f32_e32 v1, v0, v38
	v_fma_f32 v2, -v9, v1, v0
	v_fmac_f32_e32 v1, v2, v38
	v_fma_f32 v0, -v9, v1, v0
	v_div_fmas_f32 v0, v0, v38, v1
	v_div_fixup_f32 v38, v0, v8, 1.0
	v_lshlrev_b64 v[0:1], 8, v[82:83]
	v_lshl_add_u64 v[0:1], s[42:43], 0, v[0:1]
	v_lshl_add_u64 v[0:1], s[0:1], 1, v[0:1]
	v_ashrrev_i32_e32 v85, 31, v84
	v_lshl_add_u64 v[8:9], v[84:85], 1, v[0:1]
	v_cndmask_b32_e64 v0, v5, v16, s[4:5]
	v_cndmask_b32_e64 v2, v6, v19, s[4:5]
	v_cndmask_b32_e64 v5, v20, v21, s[4:5]
	v_cndmask_b32_e64 v7, v15, v7, s[4:5]
	v_bfe_u32 v1, v0, 4, 4
	v_and_b32_e32 v0, 15, v0
	v_bfe_u32 v3, v2, 4, 4
	v_and_b32_e32 v2, 15, v2
	v_bfe_u32 v6, v5, 4, 4
	v_and_b32_e32 v5, 15, v5
	v_bfe_u32 v15, v7, 4, 4
	v_and_b32_e32 v7, 15, v7
	s_waitcnt lgkmcnt(0)
	v_add_u32_e32 v1, v90, v1
	v_add_u32_e32 v0, v90, v0
	v_add_u32_e32 v3, v90, v3
	v_add_u32_e32 v2, v90, v2
	v_add_u32_e32 v6, v90, v6
	v_add_u32_e32 v5, v90, v5
	v_add_u32_e32 v15, v90, v15
	v_add_u32_e32 v7, v90, v7
	ds_read_u8 v1, v1
	ds_read_u8 v0, v0 offset:16
	ds_read_u8 v3, v3
	ds_read_u8 v2, v2 offset:16
	ds_read_u8 v6, v6
	ds_read_u8 v5, v5 offset:16
	ds_read_u8 v15, v15
	ds_read_u8 v7, v7 offset:16
	s_waitcnt lgkmcnt(7)
	v_lshlrev_b16_e32 v1, 7, v1
	s_waitcnt lgkmcnt(6)
	v_add_u16_e32 v0, v1, v0
	s_waitcnt lgkmcnt(5)
	v_lshlrev_b16_e32 v1, 7, v3
	s_waitcnt lgkmcnt(4)
	v_add_u16_e32 v1, v1, v2
	s_waitcnt lgkmcnt(3)
	v_lshlrev_b16_e32 v2, 7, v6
	s_waitcnt lgkmcnt(1)
	v_lshlrev_b16_e32 v3, 7, v15
	v_add_u16_e32 v2, v2, v5
	s_waitcnt lgkmcnt(0)
	v_add_u16_e32 v3, v3, v7
	v_cndmask_b32_e64 v5, v17, v13, s[4:5]
	v_cndmask_b32_e64 v7, v12, v10, s[4:5]
	v_cndmask_b32_e64 v12, v18, v14, s[4:5]
	v_cndmask_b32_e64 v4, v11, v4, s[4:5]
	v_bfe_u32 v6, v5, 4, 4
	v_and_b32_e32 v5, 15, v5
	v_bfe_u32 v10, v7, 4, 4
	v_and_b32_e32 v7, 15, v7
	v_bfe_u32 v13, v12, 4, 4
	v_and_b32_e32 v12, 15, v12
	v_bfe_u32 v11, v4, 4, 4
	global_store_short v[8:9], v0, off
	global_store_short v[8:9], v1, off offset:32
	global_store_short v[8:9], v2, off offset:64
	global_store_short v[8:9], v3, off offset:96
	v_add_u32_e32 v6, v90, v6
	v_add_u32_e32 v5, v90, v5
	v_add_u32_e32 v10, v90, v10
	v_add_u32_e32 v7, v90, v7
	v_add_u32_e32 v13, v90, v13
	v_add_u32_e32 v12, v90, v12
	v_and_b32_e32 v4, 15, v4
	v_add_u32_e32 v11, v90, v11
	v_add_u32_e32 v4, v90, v4
	ds_read_u8 v6, v6
	ds_read_u8 v5, v5 offset:16
	ds_read_u8 v10, v10
	ds_read_u8 v7, v7 offset:16
	ds_read_u8 v13, v13
	ds_read_u8 v12, v12 offset:16
	ds_read_u8 v11, v11
	ds_read_u8 v14, v4 offset:16
	s_waitcnt lgkmcnt(7)
	v_lshlrev_b16_e32 v4, 7, v6
	s_waitcnt lgkmcnt(6)
	v_add_u16_e32 v4, v4, v5
	s_waitcnt lgkmcnt(5)
	v_lshlrev_b16_e32 v5, 7, v10
	s_waitcnt lgkmcnt(4)
	v_add_u16_e32 v5, v5, v7
	s_waitcnt lgkmcnt(3)
	v_lshlrev_b16_e32 v6, 7, v13
	s_waitcnt lgkmcnt(1)
	v_lshlrev_b16_e32 v7, 7, v11
	v_add_u16_e32 v6, v6, v12
	s_waitcnt lgkmcnt(0)
	v_add_u16_e32 v7, v7, v14
	global_store_short v[8:9], v4, off offset:128
	global_store_short v[8:9], v5, off offset:160
	global_store_short v[8:9], v6, off offset:192
	global_store_short v[8:9], v7, off offset:224
	v_lshlrev_b64 v[8:9], 9, v[82:83]
	v_lshl_add_u64 v[8:9], s[44:45], 0, v[8:9]
	s_ashr_i64 s[0:1], s[16:17], 26
	v_cndmask_b32_e64 v0, v37, v29, s[4:5]
	v_cndmask_b32_e64 v1, v22, v30, s[4:5]
	v_cndmask_b32_e64 v2, v23, v31, s[4:5]
	v_cndmask_b32_e64 v3, v24, v36, s[4:5]
	v_lshl_add_u64 v[8:9], v[8:9], 0, s[0:1]
	v_mul_f32_e32 v0, v0, v38
	v_mul_f32_e32 v1, v1, v38
	v_mul_f32_e32 v2, v2, v38
	v_mul_f32_e32 v3, v3, v38
	v_cndmask_b32_e64 v4, v25, v32, s[4:5]
	v_cndmask_b32_e64 v5, v26, v33, s[4:5]
	v_cndmask_b32_e64 v6, v27, v34, s[4:5]
	v_cndmask_b32_e64 v7, v28, v35, s[4:5]
	v_lshl_add_u64 v[8:9], v[80:81], 2, v[8:9]
	v_mul_f32_e32 v4, v4, v38
	v_mul_f32_e32 v5, v5, v38
	v_mul_f32_e32 v6, v6, v38
	v_mul_f32_e32 v7, v7, v38
	global_store_dwordx4 v[8:9], v[0:3], off
	global_store_dwordx4 v[8:9], v[4:7], off offset:16
	s_waitcnt lgkmcnt(0)
	s_waitcnt lgkmcnt(0)
	s_barrier
	s_add_i32 s53, s53, 1
	s_mov_b64 s[0:1], 0

;     __device__ __forceinline__ void fused(typename pg8::AccT<I8_>::type (&acc)[2][2][4][2], const pg8::Unit& u, int wr, int wc, int fr, int fq, LAS unsigned char* lds, int wid, int lane) const {
;     ...
;         if (lane < 32) { const int r = 32 * wid + lane;
;             const f32x4* p = (const f32x4*)(ss + (size_t)(u.pm * 256 + r) * 32); f32x4 v[8];
; #pragma unroll
;             for (int i = 0; i < 8; ++i) v[i] = p[i];
;             float s = 0.f;
; #pragma unroll
;             for (int i = 0; i < 8; ++i) s += (v[i][0] + v[i][1]) + (v[i][2] + v[i][3]);
;             float sc = 1.0f / sqrtf(s * (1.0f / 2048.0f) + 1e-6f);
;             if (I8_) sc *= sx[u.pm * 256 + r];
;             rsl[r] = sc; }
.LBB0_598:
	v_cmp_lt_i32_e32 vcc, 31, v169
	s_barrier
	s_and_saveexec_b64 s[0:1], vcc
	s_xor_b64 s[0:1], exec, s[0:1]
	s_lshl_b32 s4, s21, 8
	s_or_saveexec_b64 s[2:3], s[0:1]
	v_mov_b32_e32 v172, s4
	s_xor_b64 exec, exec, s[2:3]
	s_cbranch_execz .LBB0_587
	v_add_u32_e32 v148, s77, v169
	s_lshl_b32 s4, s21, 8
	v_add_u32_e32 v154, s4, v148
	v_ashrrev_i32_e32 v155, 31, v154
	v_lshlrev_b64 v[128:129], 7, v[154:155]
	v_lshl_add_u64 v[156:157], s[12:13], 0, v[128:129]
	global_load_dwordx4 v[128:131], v[156:157], off
	global_load_dwordx4 v[132:135], v[156:157], off offset:16
	global_load_dwordx4 v[136:139], v[156:157], off offset:32
	global_load_dwordx4 v[140:143], v[156:157], off offset:48
	global_load_dwordx4 v[172:175], v[156:157], off offset:64
	global_load_dwordx4 v[176:179], v[156:157], off offset:80
	global_load_dwordx4 v[180:183], v[156:157], off offset:96
	global_load_dwordx4 v[184:187], v[156:157], off offset:112
	v_lshl_add_u64 v[154:155], v[154:155], 2, s[14:15]
	global_load_dword v188, v[154:155], off
	s_waitcnt vmcnt(0)
	v_mov_b32_e32 v154, v128
	v_mov_b32_e32 v155, v132
	v_mov_b32_e32 v132, v129
	v_mov_b32_e32 v128, v130
	v_mov_b32_e32 v129, v134
	v_mov_b32_e32 v134, v131
	v_mov_b32_e32 v130, v137
	v_mov_b32_e32 v131, v138
	v_mov_b32_e32 v137, v139
	v_add_f32_e32 v132, v154, v132
	v_add_f32_e32 v133, v155, v133
	v_add_f32_e32 v128, v128, v134
	v_add_f32_e32 v129, v129, v135
	v_add_f32_e32 v130, v130, v136
	v_add_f32_e32 v131, v131, v137
	v_add_f32_e32 v128, v132, v128
	v_add_f32_e32 v129, v133, v129
	v_pk_add_f32 v[130:131], v[130:131], v[130:131] op_sel:[0,1] op_sel_hi:[1,0]
	v_add_f32_e32 v128, 0, v128
	v_add_f32_e32 v138, v140, v141
	v_add_f32_e32 v140, v142, v143
	v_mov_b32_e32 v143, v172
	v_mov_b32_e32 v139, v174
	v_mov_b32_e32 v141, v175
	v_mov_b32_e32 v131, v173
	v_add_f32_e32 v142, v128, v129
	v_mov_b32_e32 v156, v177
	v_mov_b32_e32 v157, v178
	v_mov_b32_e32 v177, v179
	v_add_f32_e32 v134, v138, v140
	v_add_f32_e32 v135, v139, v141
	v_add_f32_e32 v128, v142, v130
	v_add_f32_e32 v129, v143, v131
	v_add_f32_e32 v136, v156, v176
	v_add_f32_e32 v137, v157, v177
	v_add_f32_e32 v128, v128, v134
	v_add_f32_e32 v129, v129, v135
	v_add_f32_e32 v132, v136, v137
	v_add_f32_e32 v133, v137, v136
	v_pk_add_f32 v[128:129], v[128:129], v[128:129] op_sel:[0,1] op_sel_hi:[1,0]
	v_add_f32_e32 v174, v180, v181
	v_add_f32_e32 v178, v182, v183
	v_mov_b32_e32 v175, v186
	v_mov_b32_e32 v179, v187
	v_mov_b32_e32 v133, v185
	v_mov_b32_e32 v129, v184
	v_add_f32_e32 v138, v174, v178
	v_add_f32_e32 v139, v175, v179
	v_add_f32_e32 v128, v128, v132
	v_add_f32_e32 v129, v129, v133
	v_lshl_add_u32 v130, v148, 2, 0
	v_add_f32_e32 v128, v128, v138
	v_add_f32_e32 v129, v129, v139
	v_add_u32_e32 v130, 0x22800, v130
	v_add_f32_e32 v128, v128, v129
	v_mov_b32_e32 v129, 0x358637bd
	v_fmamk_f32 v128, v128, 0x3a000000, v129
	v_mul_f32_e32 v129, 0x4f800000, v128
	v_cmp_gt_f32_e32 vcc, s49, v128
	v_mov_b32_e32 v172, s4
	s_nop 0
	v_cndmask_b32_e32 v128, v128, v129, vcc
	v_sqrt_f32_e32 v129, v128
	s_nop 0
	v_add_u32_e32 v131, -1, v129
	v_add_u32_e32 v132, 1, v129
	v_fma_f32 v133, -v131, v129, v128
	v_fma_f32 v134, -v132, v129, v128
	v_cmp_ge_f32_e64 s[0:1], 0, v133
	s_nop 1
	v_cndmask_b32_e64 v129, v129, v131, s[0:1]
	v_cmp_lt_f32_e64 s[0:1], 0, v134
	s_nop 1
	v_cndmask_b32_e64 v129, v129, v132, s[0:1]
	v_mul_f32_e32 v131, 0x37800000, v129
	v_cndmask_b32_e32 v129, v129, v131, vcc
	v_cmp_class_f32_e32 vcc, v128, v151
	s_nop 1
	v_cndmask_b32_e32 v128, v129, v128, vcc
	v_div_scale_f32 v129, s[0:1], v128, v128, 1.0
	v_rcp_f32_e32 v131, v129
	v_div_scale_f32 v132, vcc, 1.0, v128, 1.0
	v_fma_f32 v133, -v129, v131, 1.0
	v_fmac_f32_e32 v131, v133, v131
	v_mul_f32_e32 v133, v132, v131
	v_fma_f32 v134, -v129, v133, v132
	v_fmac_f32_e32 v133, v134, v131
	v_fma_f32 v129, -v129, v133, v132
	v_div_fmas_f32 v129, v129, v131, v133
	v_div_fixup_f32 v128, v129, v128, 1.0
	v_mul_f32_e32 v128, v188, v128
	ds_write_b32 v130, v128
	s_branch .LBB0_587
